# cross-lane row sums via v_permlane16/32_swap instead of ds_bpermute round trips (P1 epilogue, q/k head norms)
# speedup vs baseline: 1.0011x; 1.0011x over previous
; __device__ __forceinline__ unsigned cvt_pk(float lo, float hi) { unsigned r; asm("v_cvt_pk_bf16_f32 %0, %1, %2" : "=v"(r) : "v"(lo), "v"(hi)); return r; }
; __device__ __forceinline__ void fadd_atomic(float* p, float v) { __hip_atomic_fetch_add(p, v, __ATOMIC_RELAXED, __HIP_MEMORY_SCOPE_AGENT); }
;     __device__ __forceinline__ void operator()(const f32x4 (&acc)[2][2][4][2], const Unit& u, int wr, int wc, int fr, int fq) const {
;     ...
;             for (int m = 0; m < 4; ++m) { const int row = row0 + ai * HALF + m * 16; const float s = pre[ai * 4 + m];
; #pragma unroll
;                 for (int bj = 0; bj < 2; ++bj) { const int hc = u.pn * 2 + bj; const int col = u.pn * BM + bj * HALF + wc * 32 + 8 * fq;
;                     const f32x4 v0 = acc[ai][bj][m][0] * s, v1 = acc[ai][bj][m][1] * s;
;                     u32x4 w; w.x = cvt_pk(v0[0], v0[1]); w.y = cvt_pk(v0[2], v0[3]); w.z = cvt_pk(v1[0], v1[1]); w.w = cvt_pk(v1[2], v1[3]);
;                     *(u32x4*)(P + (size_t)row * INP + col) = w;
;                     if (hc < 5) { float q = (v0[0] * v0[0] + v0[1] * v0[1]) + (v0[2] * v0[2] + v0[3] * v0[3]) + (v1[0] * v1[0] + v1[1] * v1[1]) + (v1[2] * v1[2] + v1[3] * v1[3]);
;                         q += __shfl_xor(q, 16); q += __shfl_xor(q, 32);
;                         if (fq == 0) fadd_atomic((hc < 3 ? ss_cq : ss_ckv) + row, q); } } }
.LBB0_153:
	v_lshl_or_b32 v158, s14, 8, v166
	s_waitcnt vmcnt(0)
	v_pk_mul_f32 v[160:161], v[124:125], v[144:145] op_sel_hi:[1,0]
	v_pk_mul_f32 v[124:125], v[120:121], v[144:145] op_sel_hi:[1,0]
	v_mov_b64_e32 v[120:121], s[30:31]
	v_ashrrev_i32_e32 v159, 31, v158
	v_mad_i64_i32 v[120:121], s[0:1], v156, s73, v[120:121]
	s_cmp_lt_i32 s14, 3
	v_ashrrev_i32_e32 v157, 31, v156
	v_pk_mul_f32 v[126:127], v[126:127], v[144:145] op_sel_hi:[1,0]
	v_pk_mul_f32 v[122:123], v[122:123], v[144:145] op_sel_hi:[1,0]
	v_lshl_add_u64 v[120:121], v[158:159], 1, v[120:121]
	s_cselect_b64 s[8:9], -1, 0
	s_cmp_gt_i32 s14, 2
	v_cvt_pk_bf16_f32 v170, v160, v161
	v_cvt_pk_bf16_f32 v171, v126, v127
	v_cvt_pk_bf16_f32 v172, v124, v125
	v_cvt_pk_bf16_f32 v173, v122, v123
	global_store_dwordx4 v[120:121], v[170:173], off
	s_cbranch_scc1 .LBB0_157
	v_mul_f32_e32 v145, v161, v161
	v_mul_f32_e32 v127, v127, v127
	v_fmac_f32_e32 v145, v160, v160
	v_fmac_f32_e32 v127, v126, v126
	v_mul_f32_e32 v125, v125, v125
	v_add_f32_e32 v126, v145, v127
	v_fmac_f32_e32 v125, v124, v124
	v_mul_f32_e32 v123, v123, v123
	v_add_f32_e32 v124, v125, v126
	v_fmac_f32_e32 v123, v122, v122
	v_add_f32_e32 v122, v123, v124
	v_and_b32_e32 v124, 64, v168
	v_xor_b32_e32 v123, 16, v168
	v_add_u32_e32 v124, 64, v124
	v_cmp_lt_i32_e32 vcc, v123, v124
	s_nop 1
	v_cndmask_b32_e32 v123, v168, v123, vcc
	v_lshlrev_b32_e32 v123, 2, v123
	v_mov_b32_e32 v123, v122
	s_nop 1
	v_permlane16_swap_b32_e32 v122, v123
	s_waitcnt lgkmcnt(0)
	v_add_f32_e32 v122, v122, v123
	v_xor_b32_e32 v123, 32, v168
	v_cmp_lt_i32_e32 vcc, v123, v124
	s_nop 1
	v_cndmask_b32_e32 v123, v168, v123, vcc
	v_lshlrev_b32_e32 v123, 2, v123
	v_mov_b32_e32 v123, v122
	s_nop 1
	v_permlane32_swap_b32_e32 v122, v123
	s_and_saveexec_b64 s[0:1], s[2:3]
	s_cbranch_execz .LBB0_156
	s_cmp_eq_u32 s14, 2
	s_cselect_b32 s65, s19, s23
	s_cselect_b32 s74, s97, s22
	v_mov_b32_e32 v124, s74
	v_mov_b32_e32 v125, s65
	v_lshl_add_u64 v[124:125], v[156:157], 2, v[124:125]
	s_waitcnt lgkmcnt(0)
	v_add_f32_e32 v122, v122, v123
	global_atomic_add_f32 v[124:125], v122, off

; __device__ __forceinline__ unsigned cvt_pk(float lo, float hi) { unsigned r; asm("v_cvt_pk_bf16_f32 %0, %1, %2" : "=v"(r) : "v"(lo), "v"(hi)); return r; }
; __device__ __forceinline__ void fadd_atomic(float* p, float v) { __hip_atomic_fetch_add(p, v, __ATOMIC_RELAXED, __HIP_MEMORY_SCOPE_AGENT); }
;     __device__ __forceinline__ void operator()(const f32x4 (&acc)[2][2][4][2], const Unit& u, int wr, int wc, int fr, int fq) const {
;     ...
;             for (int m = 0; m < 4; ++m) { const int row = row0 + ai * HALF + m * 16; const float s = pre[ai * 4 + m];
; #pragma unroll
;                 for (int bj = 0; bj < 2; ++bj) { const int hc = u.pn * 2 + bj; const int col = u.pn * BM + bj * HALF + wc * 32 + 8 * fq;
;                     const f32x4 v0 = acc[ai][bj][m][0] * s, v1 = acc[ai][bj][m][1] * s;
;                     u32x4 w; w.x = cvt_pk(v0[0], v0[1]); w.y = cvt_pk(v0[2], v0[3]); w.z = cvt_pk(v1[0], v1[1]); w.w = cvt_pk(v1[2], v1[3]);
;                     *(u32x4*)(P + (size_t)row * INP + col) = w;
;                     if (hc < 5) { float q = (v0[0] * v0[0] + v0[1] * v0[1]) + (v0[2] * v0[2] + v0[3] * v0[3]) + (v1[0] * v1[0] + v1[1] * v1[1]) + (v1[2] * v1[2] + v1[3] * v1[3]);
;                         q += __shfl_xor(q, 16); q += __shfl_xor(q, 32);
;                         if (fq == 0) fadd_atomic((hc < 3 ? ss_cq : ss_ckv) + row, q); } } }
.LBB0_157:
	s_lshl_b32 s0, s14, 1
	s_or_b32 s65, s0, 1
	v_mov_b32_e32 v145, v144
	v_mov_b32_e32 v122, v144
	s_waitcnt lgkmcnt(0)
	v_mov_b32_e32 v123, v144
	s_cmp_lt_i32 s65, 5
	v_pk_mul_f32 v[118:119], v[118:119], v[122:123]
	v_pk_mul_f32 v[116:117], v[116:117], v[144:145]
	v_pk_mul_f32 v[114:115], v[114:115], v[122:123]
	v_pk_mul_f32 v[112:113], v[112:113], v[144:145]
	s_cselect_b64 s[90:91], -1, 0
	s_cmp_gt_i32 s65, 4
	v_cvt_pk_bf16_f32 v122, v116, v117
	v_cvt_pk_bf16_f32 v123, v118, v119
	v_cvt_pk_bf16_f32 v124, v112, v113
	v_cvt_pk_bf16_f32 v125, v114, v115
	global_store_dwordx4 v[120:121], v[122:125], off offset:256
	s_cbranch_scc1 .LBB0_161
	v_mul_f32_e32 v117, v117, v117
	v_fmac_f32_e32 v117, v116, v116
	v_mul_f32_e32 v116, v119, v119
	v_fmac_f32_e32 v116, v118, v118
	v_mul_f32_e32 v113, v113, v113
	v_add_f32_e32 v116, v117, v116
	v_fmac_f32_e32 v113, v112, v112
	v_add_f32_e32 v112, v113, v116
	v_mul_f32_e32 v113, v115, v115
	v_fmac_f32_e32 v113, v114, v114
	v_and_b32_e32 v114, 64, v168
	v_add_f32_e32 v112, v113, v112
	v_xor_b32_e32 v113, 16, v168
	v_add_u32_e32 v114, 64, v114
	v_cmp_lt_i32_e32 vcc, v113, v114
	s_nop 1
	v_cndmask_b32_e32 v113, v168, v113, vcc
	v_lshlrev_b32_e32 v113, 2, v113
	v_mov_b32_e32 v113, v112
	s_nop 1
	v_permlane16_swap_b32_e32 v112, v113
	s_waitcnt lgkmcnt(0)
	v_add_f32_e32 v112, v112, v113
	v_xor_b32_e32 v113, 32, v168
	v_cmp_lt_i32_e32 vcc, v113, v114
	s_nop 1
	v_cndmask_b32_e32 v113, v168, v113, vcc
	v_lshlrev_b32_e32 v113, 2, v113
	v_mov_b32_e32 v113, v112
	s_nop 1
	v_permlane32_swap_b32_e32 v112, v113
	s_and_saveexec_b64 s[0:1], s[2:3]
	s_cbranch_execz .LBB0_160
	s_cmp_lt_i32 s65, 3
	s_cselect_b32 s74, s23, s19
	s_cselect_b32 s75, s22, s97
	v_mov_b32_e32 v114, s75
	v_mov_b32_e32 v115, s74
	v_lshl_add_u64 v[114:115], v[156:157], 2, v[114:115]
	s_waitcnt lgkmcnt(0)
	v_add_f32_e32 v112, v112, v113
	global_atomic_add_f32 v[114:115], v112, off

; __device__ __forceinline__ unsigned cvt_pk(float lo, float hi) { unsigned r; asm("v_cvt_pk_bf16_f32 %0, %1, %2" : "=v"(r) : "v"(lo), "v"(hi)); return r; }
; __device__ __forceinline__ void fadd_atomic(float* p, float v) { __hip_atomic_fetch_add(p, v, __ATOMIC_RELAXED, __HIP_MEMORY_SCOPE_AGENT); }
;     __device__ __forceinline__ void operator()(const f32x4 (&acc)[2][2][4][2], const Unit& u, int wr, int wc, int fr, int fq) const {
;     ...
;             for (int m = 0; m < 4; ++m) { const int row = row0 + ai * HALF + m * 16; const float s = pre[ai * 4 + m];
; #pragma unroll
;                 for (int bj = 0; bj < 2; ++bj) { const int hc = u.pn * 2 + bj; const int col = u.pn * BM + bj * HALF + wc * 32 + 8 * fq;
;                     const f32x4 v0 = acc[ai][bj][m][0] * s, v1 = acc[ai][bj][m][1] * s;
;                     u32x4 w; w.x = cvt_pk(v0[0], v0[1]); w.y = cvt_pk(v0[2], v0[3]); w.z = cvt_pk(v1[0], v1[1]); w.w = cvt_pk(v1[2], v1[3]);
;                     *(u32x4*)(P + (size_t)row * INP + col) = w;
;                     if (hc < 5) { float q = (v0[0] * v0[0] + v0[1] * v0[1]) + (v0[2] * v0[2] + v0[3] * v0[3]) + (v1[0] * v1[0] + v1[1] * v1[1]) + (v1[2] * v1[2] + v1[3] * v1[3]);
;                         q += __shfl_xor(q, 16); q += __shfl_xor(q, 32);
;                         if (fq == 0) fadd_atomic((hc < 3 ? ss_cq : ss_ckv) + row, q); } } }
.LBB0_161:
	v_add_u32_e32 v118, 16, v156
	s_waitcnt lgkmcnt(0)
	v_pk_mul_f32 v[112:113], v[108:109], v[146:147] op_sel_hi:[1,0]
	v_pk_mul_f32 v[108:109], v[104:105], v[146:147] op_sel_hi:[1,0]
	v_mov_b64_e32 v[104:105], s[30:31]
	v_mad_i64_i32 v[104:105], s[0:1], v118, s73, v[104:105]
	v_cndmask_b32_e64 v118, 0, 1, s[8:9]
	v_pk_mul_f32 v[110:111], v[110:111], v[146:147] op_sel_hi:[1,0]
	v_pk_mul_f32 v[106:107], v[106:107], v[146:147] op_sel_hi:[1,0]
	v_lshl_add_u64 v[104:105], v[158:159], 1, v[104:105]
	v_cmp_ne_u32_e64 s[0:1], 1, v118
	s_andn2_b64 vcc, exec, s[8:9]
	v_cvt_pk_bf16_f32 v114, v112, v113
	v_cvt_pk_bf16_f32 v115, v110, v111
	v_cvt_pk_bf16_f32 v116, v108, v109
	v_cvt_pk_bf16_f32 v117, v106, v107
	global_store_dwordx4 v[104:105], v[114:117], off
	s_cbranch_vccnz .LBB0_165
	v_mul_f32_e32 v113, v113, v113
	v_mul_f32_e32 v111, v111, v111
	v_fmac_f32_e32 v113, v112, v112
	v_fmac_f32_e32 v111, v110, v110
	v_mul_f32_e32 v109, v109, v109
	v_add_f32_e32 v110, v113, v111
	v_fmac_f32_e32 v109, v108, v108
	v_mul_f32_e32 v107, v107, v107
	v_add_f32_e32 v108, v109, v110
	v_fmac_f32_e32 v107, v106, v106
	v_add_f32_e32 v106, v107, v108
	v_and_b32_e32 v108, 64, v168
	v_xor_b32_e32 v107, 16, v168
	v_add_u32_e32 v108, 64, v108
	v_cmp_lt_i32_e32 vcc, v107, v108
	s_nop 1
	v_cndmask_b32_e32 v107, v168, v107, vcc
	v_lshlrev_b32_e32 v107, 2, v107
	v_mov_b32_e32 v107, v106
	s_nop 1
	v_permlane16_swap_b32_e32 v106, v107
	s_waitcnt lgkmcnt(0)
	v_add_f32_e32 v106, v106, v107
	v_xor_b32_e32 v107, 32, v168
	v_cmp_lt_i32_e32 vcc, v107, v108
	s_nop 1
	v_cndmask_b32_e32 v107, v168, v107, vcc
	v_lshlrev_b32_e32 v107, 2, v107
	v_mov_b32_e32 v107, v106
	s_nop 1
	v_permlane32_swap_b32_e32 v106, v107
	s_and_saveexec_b64 s[8:9], s[2:3]
	s_cbranch_execz .LBB0_164
	s_cmp_eq_u32 s14, 2
	s_cselect_b32 s74, s19, s23
	s_cselect_b32 s75, s97, s22
	v_mov_b32_e32 v108, s75
	v_mov_b32_e32 v109, s74
	v_lshl_add_u64 v[108:109], v[156:157], 2, v[108:109]
	s_waitcnt lgkmcnt(0)
	v_add_f32_e32 v106, v106, v107
	global_atomic_add_f32 v[108:109], v106, off offset:64

; __device__ __forceinline__ unsigned cvt_pk(float lo, float hi) { unsigned r; asm("v_cvt_pk_bf16_f32 %0, %1, %2" : "=v"(r) : "v"(lo), "v"(hi)); return r; }
; __device__ __forceinline__ void fadd_atomic(float* p, float v) { __hip_atomic_fetch_add(p, v, __ATOMIC_RELAXED, __HIP_MEMORY_SCOPE_AGENT); }
;     __device__ __forceinline__ void operator()(const f32x4 (&acc)[2][2][4][2], const Unit& u, int wr, int wc, int fr, int fq) const {
;     ...
;             for (int m = 0; m < 4; ++m) { const int row = row0 + ai * HALF + m * 16; const float s = pre[ai * 4 + m];
; #pragma unroll
;                 for (int bj = 0; bj < 2; ++bj) { const int hc = u.pn * 2 + bj; const int col = u.pn * BM + bj * HALF + wc * 32 + 8 * fq;
;                     const f32x4 v0 = acc[ai][bj][m][0] * s, v1 = acc[ai][bj][m][1] * s;
;                     u32x4 w; w.x = cvt_pk(v0[0], v0[1]); w.y = cvt_pk(v0[2], v0[3]); w.z = cvt_pk(v1[0], v1[1]); w.w = cvt_pk(v1[2], v1[3]);
;                     *(u32x4*)(P + (size_t)row * INP + col) = w;
;                     if (hc < 5) { float q = (v0[0] * v0[0] + v0[1] * v0[1]) + (v0[2] * v0[2] + v0[3] * v0[3]) + (v1[0] * v1[0] + v1[1] * v1[1]) + (v1[2] * v1[2] + v1[3] * v1[3]);
;                         q += __shfl_xor(q, 16); q += __shfl_xor(q, 32);
;                         if (fq == 0) fadd_atomic((hc < 3 ? ss_cq : ss_ckv) + row, q); } } }
.LBB0_165:
	v_mov_b32_e32 v147, v146
	v_mov_b32_e32 v106, v146
	s_waitcnt lgkmcnt(0)
	v_mov_b32_e32 v107, v146
	v_cndmask_b32_e64 v110, 0, 1, s[90:91]
	v_pk_mul_f32 v[102:103], v[102:103], v[106:107]
	v_pk_mul_f32 v[100:101], v[100:101], v[146:147]
	v_pk_mul_f32 v[98:99], v[98:99], v[106:107]
	v_pk_mul_f32 v[96:97], v[96:97], v[146:147]
	v_cmp_ne_u32_e64 s[8:9], 1, v110
	s_andn2_b64 vcc, exec, s[90:91]
	v_cvt_pk_bf16_f32 v106, v100, v101
	v_cvt_pk_bf16_f32 v107, v102, v103
	v_cvt_pk_bf16_f32 v108, v96, v97
	v_cvt_pk_bf16_f32 v109, v98, v99
	global_store_dwordx4 v[104:105], v[106:109], off offset:256
	s_cbranch_vccnz .LBB0_169
	v_mul_f32_e32 v101, v101, v101
	v_fmac_f32_e32 v101, v100, v100
	v_mul_f32_e32 v100, v103, v103
	v_fmac_f32_e32 v100, v102, v102
	v_mul_f32_e32 v97, v97, v97
	v_add_f32_e32 v100, v101, v100
	v_fmac_f32_e32 v97, v96, v96
	v_add_f32_e32 v96, v97, v100
	v_mul_f32_e32 v97, v99, v99
	v_fmac_f32_e32 v97, v98, v98
	v_and_b32_e32 v98, 64, v168
	v_add_f32_e32 v96, v97, v96
	v_xor_b32_e32 v97, 16, v168
	v_add_u32_e32 v98, 64, v98
	v_cmp_lt_i32_e32 vcc, v97, v98
	s_nop 1
	v_cndmask_b32_e32 v97, v168, v97, vcc
	v_lshlrev_b32_e32 v97, 2, v97
	v_mov_b32_e32 v97, v96
	s_nop 1
	v_permlane16_swap_b32_e32 v96, v97
	s_waitcnt lgkmcnt(0)
	v_add_f32_e32 v96, v96, v97
	v_xor_b32_e32 v97, 32, v168
	v_cmp_lt_i32_e32 vcc, v97, v98
	s_nop 1
	v_cndmask_b32_e32 v97, v168, v97, vcc
	v_lshlrev_b32_e32 v97, 2, v97
	v_mov_b32_e32 v97, v96
	s_nop 1
	v_permlane32_swap_b32_e32 v96, v97
	s_and_saveexec_b64 s[90:91], s[2:3]
	s_cbranch_execz .LBB0_168
	s_cmp_lt_i32 s65, 3
	s_cselect_b32 s74, s23, s19
	s_cselect_b32 s75, s22, s97
	v_mov_b32_e32 v98, s75
	v_mov_b32_e32 v99, s74
	v_lshl_add_u64 v[98:99], v[156:157], 2, v[98:99]
	s_waitcnt lgkmcnt(0)
	v_add_f32_e32 v96, v96, v97
	global_atomic_add_f32 v[98:99], v96, off offset:64

; __device__ __forceinline__ unsigned cvt_pk(float lo, float hi) { unsigned r; asm("v_cvt_pk_bf16_f32 %0, %1, %2" : "=v"(r) : "v"(lo), "v"(hi)); return r; }
; __device__ __forceinline__ void fadd_atomic(float* p, float v) { __hip_atomic_fetch_add(p, v, __ATOMIC_RELAXED, __HIP_MEMORY_SCOPE_AGENT); }
;     __device__ __forceinline__ void operator()(const f32x4 (&acc)[2][2][4][2], const Unit& u, int wr, int wc, int fr, int fq) const {
;     ...
;             for (int m = 0; m < 4; ++m) { const int row = row0 + ai * HALF + m * 16; const float s = pre[ai * 4 + m];
; #pragma unroll
;                 for (int bj = 0; bj < 2; ++bj) { const int hc = u.pn * 2 + bj; const int col = u.pn * BM + bj * HALF + wc * 32 + 8 * fq;
;                     const f32x4 v0 = acc[ai][bj][m][0] * s, v1 = acc[ai][bj][m][1] * s;
;                     u32x4 w; w.x = cvt_pk(v0[0], v0[1]); w.y = cvt_pk(v0[2], v0[3]); w.z = cvt_pk(v1[0], v1[1]); w.w = cvt_pk(v1[2], v1[3]);
;                     *(u32x4*)(P + (size_t)row * INP + col) = w;
;                     if (hc < 5) { float q = (v0[0] * v0[0] + v0[1] * v0[1]) + (v0[2] * v0[2] + v0[3] * v0[3]) + (v1[0] * v1[0] + v1[1] * v1[1]) + (v1[2] * v1[2] + v1[3] * v1[3]);
;                         q += __shfl_xor(q, 16); q += __shfl_xor(q, 32);
;                         if (fq == 0) fadd_atomic((hc < 3 ? ss_cq : ss_ckv) + row, q); } } }
.LBB0_169:
	v_add_u32_e32 v102, 32, v156
	s_waitcnt lgkmcnt(0)
	v_pk_mul_f32 v[96:97], v[92:93], v[148:149] op_sel_hi:[1,0]
	v_pk_mul_f32 v[92:93], v[88:89], v[148:149] op_sel_hi:[1,0]
	v_mov_b64_e32 v[88:89], s[30:31]
	v_mad_i64_i32 v[88:89], s[74:75], v102, s73, v[88:89]
	v_pk_mul_f32 v[94:95], v[94:95], v[148:149] op_sel_hi:[1,0]
	v_pk_mul_f32 v[90:91], v[90:91], v[148:149] op_sel_hi:[1,0]
	v_lshl_add_u64 v[88:89], v[158:159], 1, v[88:89]
	s_and_b64 vcc, exec, s[0:1]
	v_cvt_pk_bf16_f32 v98, v96, v97
	v_cvt_pk_bf16_f32 v99, v94, v95
	v_cvt_pk_bf16_f32 v100, v92, v93
	v_cvt_pk_bf16_f32 v101, v90, v91
	global_store_dwordx4 v[88:89], v[98:101], off
	s_cbranch_vccnz .LBB0_173
	v_mul_f32_e32 v97, v97, v97
	v_mul_f32_e32 v95, v95, v95
	v_fmac_f32_e32 v97, v96, v96
	v_fmac_f32_e32 v95, v94, v94
	v_mul_f32_e32 v93, v93, v93
	v_add_f32_e32 v94, v97, v95
	v_fmac_f32_e32 v93, v92, v92
	v_mul_f32_e32 v91, v91, v91
	v_add_f32_e32 v92, v93, v94
	v_fmac_f32_e32 v91, v90, v90
	v_add_f32_e32 v90, v91, v92
	v_and_b32_e32 v92, 64, v168
	v_xor_b32_e32 v91, 16, v168
	v_add_u32_e32 v92, 64, v92
	v_cmp_lt_i32_e32 vcc, v91, v92
	s_nop 1
	v_cndmask_b32_e32 v91, v168, v91, vcc
	v_lshlrev_b32_e32 v91, 2, v91
	v_mov_b32_e32 v91, v90
	s_nop 1
	v_permlane16_swap_b32_e32 v90, v91
	s_waitcnt lgkmcnt(0)
	v_add_f32_e32 v90, v90, v91
	v_xor_b32_e32 v91, 32, v168
	v_cmp_lt_i32_e32 vcc, v91, v92
	s_nop 1
	v_cndmask_b32_e32 v91, v168, v91, vcc
	v_lshlrev_b32_e32 v91, 2, v91
	v_mov_b32_e32 v91, v90
	s_nop 1
	v_permlane32_swap_b32_e32 v90, v91
	s_and_saveexec_b64 s[90:91], s[2:3]
	s_cbranch_execz .LBB0_172
	s_cmp_eq_u32 s14, 2
	s_cselect_b32 s74, s19, s23
	s_cselect_b32 s75, s97, s22
	v_mov_b32_e32 v92, s75
	v_mov_b32_e32 v93, s74
	v_lshl_add_u64 v[92:93], v[156:157], 2, v[92:93]
	s_waitcnt lgkmcnt(0)
	v_add_f32_e32 v90, v90, v91
	global_atomic_add_f32 v[92:93], v90, off offset:128

; __device__ __forceinline__ unsigned cvt_pk(float lo, float hi) { unsigned r; asm("v_cvt_pk_bf16_f32 %0, %1, %2" : "=v"(r) : "v"(lo), "v"(hi)); return r; }
; __device__ __forceinline__ void fadd_atomic(float* p, float v) { __hip_atomic_fetch_add(p, v, __ATOMIC_RELAXED, __HIP_MEMORY_SCOPE_AGENT); }
;     __device__ __forceinline__ void operator()(const f32x4 (&acc)[2][2][4][2], const Unit& u, int wr, int wc, int fr, int fq) const {
;     ...
;             for (int m = 0; m < 4; ++m) { const int row = row0 + ai * HALF + m * 16; const float s = pre[ai * 4 + m];
; #pragma unroll
;                 for (int bj = 0; bj < 2; ++bj) { const int hc = u.pn * 2 + bj; const int col = u.pn * BM + bj * HALF + wc * 32 + 8 * fq;
;                     const f32x4 v0 = acc[ai][bj][m][0] * s, v1 = acc[ai][bj][m][1] * s;
;                     u32x4 w; w.x = cvt_pk(v0[0], v0[1]); w.y = cvt_pk(v0[2], v0[3]); w.z = cvt_pk(v1[0], v1[1]); w.w = cvt_pk(v1[2], v1[3]);
;                     *(u32x4*)(P + (size_t)row * INP + col) = w;
;                     if (hc < 5) { float q = (v0[0] * v0[0] + v0[1] * v0[1]) + (v0[2] * v0[2] + v0[3] * v0[3]) + (v1[0] * v1[0] + v1[1] * v1[1]) + (v1[2] * v1[2] + v1[3] * v1[3]);
;                         q += __shfl_xor(q, 16); q += __shfl_xor(q, 32);
;                         if (fq == 0) fadd_atomic((hc < 3 ? ss_cq : ss_ckv) + row, q); } } }
.LBB0_173:
	v_mov_b32_e32 v149, v148
	v_mov_b32_e32 v90, v148
	s_waitcnt lgkmcnt(0)
	v_mov_b32_e32 v91, v148
	v_pk_mul_f32 v[86:87], v[86:87], v[90:91]
	v_pk_mul_f32 v[84:85], v[84:85], v[148:149]
	v_pk_mul_f32 v[82:83], v[82:83], v[90:91]
	v_pk_mul_f32 v[80:81], v[80:81], v[148:149]
	s_and_b64 vcc, exec, s[8:9]
	v_cvt_pk_bf16_f32 v90, v84, v85
	v_cvt_pk_bf16_f32 v91, v86, v87
	v_cvt_pk_bf16_f32 v92, v80, v81
	v_cvt_pk_bf16_f32 v93, v82, v83
	global_store_dwordx4 v[88:89], v[90:93], off offset:256
	s_cbranch_vccnz .LBB0_177
	v_mul_f32_e32 v85, v85, v85
	v_fmac_f32_e32 v85, v84, v84
	v_mul_f32_e32 v84, v87, v87
	v_fmac_f32_e32 v84, v86, v86
	v_mul_f32_e32 v81, v81, v81
	v_add_f32_e32 v84, v85, v84
	v_fmac_f32_e32 v81, v80, v80
	v_add_f32_e32 v80, v81, v84
	v_mul_f32_e32 v81, v83, v83
	v_fmac_f32_e32 v81, v82, v82
	v_and_b32_e32 v82, 64, v168
	v_add_f32_e32 v80, v81, v80
	v_xor_b32_e32 v81, 16, v168
	v_add_u32_e32 v82, 64, v82
	v_cmp_lt_i32_e32 vcc, v81, v82
	s_nop 1
	v_cndmask_b32_e32 v81, v168, v81, vcc
	v_lshlrev_b32_e32 v81, 2, v81
	v_mov_b32_e32 v81, v80
	s_nop 1
	v_permlane16_swap_b32_e32 v80, v81
	s_waitcnt lgkmcnt(0)
	v_add_f32_e32 v80, v80, v81
	v_xor_b32_e32 v81, 32, v168
	v_cmp_lt_i32_e32 vcc, v81, v82
	s_nop 1
	v_cndmask_b32_e32 v81, v168, v81, vcc
	v_lshlrev_b32_e32 v81, 2, v81
	v_mov_b32_e32 v81, v80
	s_nop 1
	v_permlane32_swap_b32_e32 v80, v81
	s_and_saveexec_b64 s[90:91], s[2:3]
	s_cbranch_execz .LBB0_176
	s_cmp_lt_i32 s65, 3
	s_cselect_b32 s74, s23, s19
	s_cselect_b32 s75, s22, s97
	v_mov_b32_e32 v82, s75
	v_mov_b32_e32 v83, s74
	v_lshl_add_u64 v[82:83], v[156:157], 2, v[82:83]
	s_waitcnt lgkmcnt(0)
	v_add_f32_e32 v80, v80, v81
	global_atomic_add_f32 v[82:83], v80, off offset:128

; __device__ __forceinline__ unsigned cvt_pk(float lo, float hi) { unsigned r; asm("v_cvt_pk_bf16_f32 %0, %1, %2" : "=v"(r) : "v"(lo), "v"(hi)); return r; }
; __device__ __forceinline__ void fadd_atomic(float* p, float v) { __hip_atomic_fetch_add(p, v, __ATOMIC_RELAXED, __HIP_MEMORY_SCOPE_AGENT); }
;     __device__ __forceinline__ void operator()(const f32x4 (&acc)[2][2][4][2], const Unit& u, int wr, int wc, int fr, int fq) const {
;     ...
;             for (int m = 0; m < 4; ++m) { const int row = row0 + ai * HALF + m * 16; const float s = pre[ai * 4 + m];
; #pragma unroll
;                 for (int bj = 0; bj < 2; ++bj) { const int hc = u.pn * 2 + bj; const int col = u.pn * BM + bj * HALF + wc * 32 + 8 * fq;
;                     const f32x4 v0 = acc[ai][bj][m][0] * s, v1 = acc[ai][bj][m][1] * s;
;                     u32x4 w; w.x = cvt_pk(v0[0], v0[1]); w.y = cvt_pk(v0[2], v0[3]); w.z = cvt_pk(v1[0], v1[1]); w.w = cvt_pk(v1[2], v1[3]);
;                     *(u32x4*)(P + (size_t)row * INP + col) = w;
;                     if (hc < 5) { float q = (v0[0] * v0[0] + v0[1] * v0[1]) + (v0[2] * v0[2] + v0[3] * v0[3]) + (v1[0] * v1[0] + v1[1] * v1[1]) + (v1[2] * v1[2] + v1[3] * v1[3]);
;                         q += __shfl_xor(q, 16); q += __shfl_xor(q, 32);
;                         if (fq == 0) fadd_atomic((hc < 3 ? ss_cq : ss_ckv) + row, q); } } }
.LBB0_177:
	v_add_u32_e32 v86, 48, v156
	s_waitcnt lgkmcnt(0)
	v_pk_mul_f32 v[80:81], v[76:77], v[150:151] op_sel_hi:[1,0]
	v_pk_mul_f32 v[76:77], v[72:73], v[150:151] op_sel_hi:[1,0]
	v_mov_b64_e32 v[72:73], s[30:31]
	v_mad_i64_i32 v[72:73], s[74:75], v86, s73, v[72:73]
	v_pk_mul_f32 v[78:79], v[78:79], v[150:151] op_sel_hi:[1,0]
	v_pk_mul_f32 v[74:75], v[74:75], v[150:151] op_sel_hi:[1,0]
	v_lshl_add_u64 v[72:73], v[158:159], 1, v[72:73]
	s_and_b64 vcc, exec, s[0:1]
	v_cvt_pk_bf16_f32 v82, v80, v81
	v_cvt_pk_bf16_f32 v83, v78, v79
	v_cvt_pk_bf16_f32 v84, v76, v77
	v_cvt_pk_bf16_f32 v85, v74, v75
	global_store_dwordx4 v[72:73], v[82:85], off
	s_cbranch_vccnz .LBB0_181
	v_mul_f32_e32 v81, v81, v81
	v_mul_f32_e32 v79, v79, v79
	v_fmac_f32_e32 v81, v80, v80
	v_fmac_f32_e32 v79, v78, v78
	v_mul_f32_e32 v77, v77, v77
	v_add_f32_e32 v78, v81, v79
	v_fmac_f32_e32 v77, v76, v76
	v_mul_f32_e32 v75, v75, v75
	v_add_f32_e32 v76, v77, v78
	v_fmac_f32_e32 v75, v74, v74
	v_add_f32_e32 v74, v75, v76
	v_and_b32_e32 v76, 64, v168
	v_xor_b32_e32 v75, 16, v168
	v_add_u32_e32 v76, 64, v76
	v_cmp_lt_i32_e32 vcc, v75, v76
	s_nop 1
	v_cndmask_b32_e32 v75, v168, v75, vcc
	v_lshlrev_b32_e32 v75, 2, v75
	v_mov_b32_e32 v75, v74
	s_nop 1
	v_permlane16_swap_b32_e32 v74, v75
	s_waitcnt lgkmcnt(0)
	v_add_f32_e32 v74, v74, v75
	v_xor_b32_e32 v75, 32, v168
	v_cmp_lt_i32_e32 vcc, v75, v76
	s_nop 1
	v_cndmask_b32_e32 v75, v168, v75, vcc
	v_lshlrev_b32_e32 v75, 2, v75
	v_mov_b32_e32 v75, v74
	s_nop 1
	v_permlane32_swap_b32_e32 v74, v75
	s_and_saveexec_b64 s[90:91], s[2:3]
	s_cbranch_execz .LBB0_180
	s_cmp_eq_u32 s14, 2
	s_cselect_b32 s74, s19, s23
	s_cselect_b32 s75, s97, s22
	v_mov_b32_e32 v76, s75
	v_mov_b32_e32 v77, s74
	v_lshl_add_u64 v[76:77], v[156:157], 2, v[76:77]
	s_waitcnt lgkmcnt(0)
	v_add_f32_e32 v74, v74, v75
	global_atomic_add_f32 v[76:77], v74, off offset:192

; __device__ __forceinline__ unsigned cvt_pk(float lo, float hi) { unsigned r; asm("v_cvt_pk_bf16_f32 %0, %1, %2" : "=v"(r) : "v"(lo), "v"(hi)); return r; }
; __device__ __forceinline__ void fadd_atomic(float* p, float v) { __hip_atomic_fetch_add(p, v, __ATOMIC_RELAXED, __HIP_MEMORY_SCOPE_AGENT); }
;     __device__ __forceinline__ void operator()(const f32x4 (&acc)[2][2][4][2], const Unit& u, int wr, int wc, int fr, int fq) const {
;     ...
;             for (int m = 0; m < 4; ++m) { const int row = row0 + ai * HALF + m * 16; const float s = pre[ai * 4 + m];
; #pragma unroll
;                 for (int bj = 0; bj < 2; ++bj) { const int hc = u.pn * 2 + bj; const int col = u.pn * BM + bj * HALF + wc * 32 + 8 * fq;
;                     const f32x4 v0 = acc[ai][bj][m][0] * s, v1 = acc[ai][bj][m][1] * s;
;                     u32x4 w; w.x = cvt_pk(v0[0], v0[1]); w.y = cvt_pk(v0[2], v0[3]); w.z = cvt_pk(v1[0], v1[1]); w.w = cvt_pk(v1[2], v1[3]);
;                     *(u32x4*)(P + (size_t)row * INP + col) = w;
;                     if (hc < 5) { float q = (v0[0] * v0[0] + v0[1] * v0[1]) + (v0[2] * v0[2] + v0[3] * v0[3]) + (v1[0] * v1[0] + v1[1] * v1[1]) + (v1[2] * v1[2] + v1[3] * v1[3]);
;                         q += __shfl_xor(q, 16); q += __shfl_xor(q, 32);
;                         if (fq == 0) fadd_atomic((hc < 3 ? ss_cq : ss_ckv) + row, q); } } }
.LBB0_181:
	v_mov_b32_e32 v151, v150
	v_mov_b32_e32 v74, v150
	s_waitcnt lgkmcnt(0)
	v_mov_b32_e32 v75, v150
	v_pk_mul_f32 v[70:71], v[70:71], v[74:75]
	v_pk_mul_f32 v[68:69], v[68:69], v[150:151]
	v_pk_mul_f32 v[66:67], v[66:67], v[74:75]
	v_pk_mul_f32 v[64:65], v[64:65], v[150:151]
	s_and_b64 vcc, exec, s[8:9]
	v_cvt_pk_bf16_f32 v74, v68, v69
	v_cvt_pk_bf16_f32 v75, v70, v71
	v_cvt_pk_bf16_f32 v76, v64, v65
	v_cvt_pk_bf16_f32 v77, v66, v67
	global_store_dwordx4 v[72:73], v[74:77], off offset:256
	s_cbranch_vccnz .LBB0_185
	v_mul_f32_e32 v69, v69, v69
	v_fmac_f32_e32 v69, v68, v68
	v_mul_f32_e32 v68, v71, v71
	v_fmac_f32_e32 v68, v70, v70
	v_mul_f32_e32 v65, v65, v65
	v_add_f32_e32 v68, v69, v68
	v_fmac_f32_e32 v65, v64, v64
	v_add_f32_e32 v64, v65, v68
	v_mul_f32_e32 v65, v67, v67
	v_fmac_f32_e32 v65, v66, v66
	v_and_b32_e32 v66, 64, v168
	v_add_f32_e32 v64, v65, v64
	v_xor_b32_e32 v65, 16, v168
	v_add_u32_e32 v66, 64, v66
	v_cmp_lt_i32_e32 vcc, v65, v66
	s_nop 1
	v_cndmask_b32_e32 v65, v168, v65, vcc
	v_lshlrev_b32_e32 v65, 2, v65
	v_mov_b32_e32 v65, v64
	s_nop 1
	v_permlane16_swap_b32_e32 v64, v65
	s_waitcnt lgkmcnt(0)
	v_add_f32_e32 v64, v64, v65
	v_xor_b32_e32 v65, 32, v168
	v_cmp_lt_i32_e32 vcc, v65, v66
	s_nop 1
	v_cndmask_b32_e32 v65, v168, v65, vcc
	v_lshlrev_b32_e32 v65, 2, v65
	v_mov_b32_e32 v65, v64
	s_nop 1
	v_permlane32_swap_b32_e32 v64, v65
	s_and_saveexec_b64 s[90:91], s[2:3]
	s_cbranch_execz .LBB0_184
	s_cmp_lt_i32 s65, 3
	s_cselect_b32 s74, s23, s19
	s_cselect_b32 s75, s22, s97
	v_mov_b32_e32 v66, s75
	v_mov_b32_e32 v67, s74
	v_lshl_add_u64 v[66:67], v[156:157], 2, v[66:67]
	s_waitcnt lgkmcnt(0)
	v_add_f32_e32 v64, v64, v65
	global_atomic_add_f32 v[66:67], v64, off offset:192

; __device__ __forceinline__ unsigned cvt_pk(float lo, float hi) { unsigned r; asm("v_cvt_pk_bf16_f32 %0, %1, %2" : "=v"(r) : "v"(lo), "v"(hi)); return r; }
; __device__ __forceinline__ void fadd_atomic(float* p, float v) { __hip_atomic_fetch_add(p, v, __ATOMIC_RELAXED, __HIP_MEMORY_SCOPE_AGENT); }
;     __device__ __forceinline__ void operator()(const f32x4 (&acc)[2][2][4][2], const Unit& u, int wr, int wc, int fr, int fq) const {
;     ...
;             for (int m = 0; m < 4; ++m) { const int row = row0 + ai * HALF + m * 16; const float s = pre[ai * 4 + m];
; #pragma unroll
;                 for (int bj = 0; bj < 2; ++bj) { const int hc = u.pn * 2 + bj; const int col = u.pn * BM + bj * HALF + wc * 32 + 8 * fq;
;                     const f32x4 v0 = acc[ai][bj][m][0] * s, v1 = acc[ai][bj][m][1] * s;
;                     u32x4 w; w.x = cvt_pk(v0[0], v0[1]); w.y = cvt_pk(v0[2], v0[3]); w.z = cvt_pk(v1[0], v1[1]); w.w = cvt_pk(v1[2], v1[3]);
;                     *(u32x4*)(P + (size_t)row * INP + col) = w;
;                     if (hc < 5) { float q = (v0[0] * v0[0] + v0[1] * v0[1]) + (v0[2] * v0[2] + v0[3] * v0[3]) + (v1[0] * v1[0] + v1[1] * v1[1]) + (v1[2] * v1[2] + v1[3] * v1[3]);
;                         q += __shfl_xor(q, 16); q += __shfl_xor(q, 32);
;                         if (fq == 0) fadd_atomic((hc < 3 ? ss_cq : ss_ckv) + row, q); } } }
.LBB0_185:
	v_add_u32_e32 v70, 0x80, v156
	s_waitcnt lgkmcnt(0)
	v_pk_mul_f32 v[64:65], v[60:61], v[152:153] op_sel_hi:[1,0]
	v_pk_mul_f32 v[60:61], v[56:57], v[152:153] op_sel_hi:[1,0]
	v_mov_b64_e32 v[56:57], s[30:31]
	v_mad_i64_i32 v[56:57], s[74:75], v70, s73, v[56:57]
	v_pk_mul_f32 v[62:63], v[62:63], v[152:153] op_sel_hi:[1,0]
	v_pk_mul_f32 v[58:59], v[58:59], v[152:153] op_sel_hi:[1,0]
	v_lshl_add_u64 v[56:57], v[158:159], 1, v[56:57]
	s_and_b64 vcc, exec, s[0:1]
	v_cvt_pk_bf16_f32 v66, v64, v65
	v_cvt_pk_bf16_f32 v67, v62, v63
	v_cvt_pk_bf16_f32 v68, v60, v61
	v_cvt_pk_bf16_f32 v69, v58, v59
	global_store_dwordx4 v[56:57], v[66:69], off
	s_cbranch_vccnz .LBB0_189
	v_mul_f32_e32 v65, v65, v65
	v_mul_f32_e32 v63, v63, v63
	v_fmac_f32_e32 v65, v64, v64
	v_fmac_f32_e32 v63, v62, v62
	v_mul_f32_e32 v61, v61, v61
	v_add_f32_e32 v62, v65, v63
	v_fmac_f32_e32 v61, v60, v60
	v_mul_f32_e32 v59, v59, v59
	v_add_f32_e32 v60, v61, v62
	v_fmac_f32_e32 v59, v58, v58
	v_add_f32_e32 v58, v59, v60
	v_and_b32_e32 v60, 64, v168
	v_xor_b32_e32 v59, 16, v168
	v_add_u32_e32 v60, 64, v60
	v_cmp_lt_i32_e32 vcc, v59, v60
	s_nop 1
	v_cndmask_b32_e32 v59, v168, v59, vcc
	v_lshlrev_b32_e32 v59, 2, v59
	v_mov_b32_e32 v59, v58
	s_nop 1
	v_permlane16_swap_b32_e32 v58, v59
	s_waitcnt lgkmcnt(0)
	v_add_f32_e32 v58, v58, v59
	v_xor_b32_e32 v59, 32, v168
	v_cmp_lt_i32_e32 vcc, v59, v60
	s_nop 1
	v_cndmask_b32_e32 v59, v168, v59, vcc
	v_lshlrev_b32_e32 v59, 2, v59
	v_mov_b32_e32 v59, v58
	s_nop 1
	v_permlane32_swap_b32_e32 v58, v59
	s_and_saveexec_b64 s[90:91], s[2:3]
	s_cbranch_execz .LBB0_188
	s_cmp_eq_u32 s14, 2
	s_cselect_b32 s74, s19, s23
	s_cselect_b32 s75, s97, s22
	v_mov_b32_e32 v60, s75
	v_mov_b32_e32 v61, s74
	v_lshl_add_u64 v[60:61], v[156:157], 2, v[60:61]
	s_waitcnt lgkmcnt(0)
	v_add_f32_e32 v58, v58, v59
	global_atomic_add_f32 v[60:61], v58, off offset:512

; __device__ __forceinline__ unsigned cvt_pk(float lo, float hi) { unsigned r; asm("v_cvt_pk_bf16_f32 %0, %1, %2" : "=v"(r) : "v"(lo), "v"(hi)); return r; }
; __device__ __forceinline__ void fadd_atomic(float* p, float v) { __hip_atomic_fetch_add(p, v, __ATOMIC_RELAXED, __HIP_MEMORY_SCOPE_AGENT); }
;     __device__ __forceinline__ void operator()(const f32x4 (&acc)[2][2][4][2], const Unit& u, int wr, int wc, int fr, int fq) const {
;     ...
;             for (int m = 0; m < 4; ++m) { const int row = row0 + ai * HALF + m * 16; const float s = pre[ai * 4 + m];
; #pragma unroll
;                 for (int bj = 0; bj < 2; ++bj) { const int hc = u.pn * 2 + bj; const int col = u.pn * BM + bj * HALF + wc * 32 + 8 * fq;
;                     const f32x4 v0 = acc[ai][bj][m][0] * s, v1 = acc[ai][bj][m][1] * s;
;                     u32x4 w; w.x = cvt_pk(v0[0], v0[1]); w.y = cvt_pk(v0[2], v0[3]); w.z = cvt_pk(v1[0], v1[1]); w.w = cvt_pk(v1[2], v1[3]);
;                     *(u32x4*)(P + (size_t)row * INP + col) = w;
;                     if (hc < 5) { float q = (v0[0] * v0[0] + v0[1] * v0[1]) + (v0[2] * v0[2] + v0[3] * v0[3]) + (v1[0] * v1[0] + v1[1] * v1[1]) + (v1[2] * v1[2] + v1[3] * v1[3]);
;                         q += __shfl_xor(q, 16); q += __shfl_xor(q, 32);
;                         if (fq == 0) fadd_atomic((hc < 3 ? ss_cq : ss_ckv) + row, q); } } }
.LBB0_189:
	v_mov_b32_e32 v58, v152
	s_waitcnt lgkmcnt(0)
	v_mov_b32_e32 v59, v152
	v_mov_b32_e32 v60, v152
	v_mov_b32_e32 v61, v152
	v_pk_mul_f32 v[54:55], v[54:55], v[60:61]
	v_pk_mul_f32 v[52:53], v[52:53], v[58:59]
	v_pk_mul_f32 v[50:51], v[50:51], v[60:61]
	v_pk_mul_f32 v[48:49], v[48:49], v[58:59]
	s_and_b64 vcc, exec, s[8:9]
	v_cvt_pk_bf16_f32 v58, v52, v53
	v_cvt_pk_bf16_f32 v59, v54, v55
	v_cvt_pk_bf16_f32 v60, v48, v49
	v_cvt_pk_bf16_f32 v61, v50, v51
	global_store_dwordx4 v[56:57], v[58:61], off offset:256
	s_cbranch_vccnz .LBB0_193
	v_mul_f32_e32 v53, v53, v53
	v_fmac_f32_e32 v53, v52, v52
	v_mul_f32_e32 v52, v55, v55
	v_fmac_f32_e32 v52, v54, v54
	v_mul_f32_e32 v49, v49, v49
	v_add_f32_e32 v52, v53, v52
	v_fmac_f32_e32 v49, v48, v48
	v_add_f32_e32 v48, v49, v52
	v_mul_f32_e32 v49, v51, v51
	v_fmac_f32_e32 v49, v50, v50
	v_and_b32_e32 v50, 64, v168
	v_add_f32_e32 v48, v49, v48
	v_xor_b32_e32 v49, 16, v168
	v_add_u32_e32 v50, 64, v50
	v_cmp_lt_i32_e32 vcc, v49, v50
	s_nop 1
	v_cndmask_b32_e32 v49, v168, v49, vcc
	v_lshlrev_b32_e32 v49, 2, v49
	v_mov_b32_e32 v49, v48
	s_nop 1
	v_permlane16_swap_b32_e32 v48, v49
	s_waitcnt lgkmcnt(0)
	v_add_f32_e32 v48, v48, v49
	v_xor_b32_e32 v49, 32, v168
	v_cmp_lt_i32_e32 vcc, v49, v50
	s_nop 1
	v_cndmask_b32_e32 v49, v168, v49, vcc
	v_lshlrev_b32_e32 v49, 2, v49
	v_mov_b32_e32 v49, v48
	s_nop 1
	v_permlane32_swap_b32_e32 v48, v49
	s_and_saveexec_b64 s[90:91], s[2:3]
	s_cbranch_execz .LBB0_192
	s_cmp_lt_i32 s65, 3
	s_cselect_b32 s74, s23, s19
	s_cselect_b32 s75, s22, s97
	v_mov_b32_e32 v50, s75
	v_mov_b32_e32 v51, s74
	v_lshl_add_u64 v[50:51], v[156:157], 2, v[50:51]
	s_waitcnt lgkmcnt(0)
	v_add_f32_e32 v48, v48, v49
	global_atomic_add_f32 v[50:51], v48, off offset:512

; __device__ __forceinline__ unsigned cvt_pk(float lo, float hi) { unsigned r; asm("v_cvt_pk_bf16_f32 %0, %1, %2" : "=v"(r) : "v"(lo), "v"(hi)); return r; }
; __device__ __forceinline__ void fadd_atomic(float* p, float v) { __hip_atomic_fetch_add(p, v, __ATOMIC_RELAXED, __HIP_MEMORY_SCOPE_AGENT); }
;     __device__ __forceinline__ void operator()(const f32x4 (&acc)[2][2][4][2], const Unit& u, int wr, int wc, int fr, int fq) const {
;     ...
;             for (int m = 0; m < 4; ++m) { const int row = row0 + ai * HALF + m * 16; const float s = pre[ai * 4 + m];
; #pragma unroll
;                 for (int bj = 0; bj < 2; ++bj) { const int hc = u.pn * 2 + bj; const int col = u.pn * BM + bj * HALF + wc * 32 + 8 * fq;
;                     const f32x4 v0 = acc[ai][bj][m][0] * s, v1 = acc[ai][bj][m][1] * s;
;                     u32x4 w; w.x = cvt_pk(v0[0], v0[1]); w.y = cvt_pk(v0[2], v0[3]); w.z = cvt_pk(v1[0], v1[1]); w.w = cvt_pk(v1[2], v1[3]);
;                     *(u32x4*)(P + (size_t)row * INP + col) = w;
;                     if (hc < 5) { float q = (v0[0] * v0[0] + v0[1] * v0[1]) + (v0[2] * v0[2] + v0[3] * v0[3]) + (v1[0] * v1[0] + v1[1] * v1[1]) + (v1[2] * v1[2] + v1[3] * v1[3]);
;                         q += __shfl_xor(q, 16); q += __shfl_xor(q, 32);
;                         if (fq == 0) fadd_atomic((hc < 3 ? ss_cq : ss_ckv) + row, q); } } }
.LBB0_193:
	v_add_u32_e32 v54, 0x90, v156
	s_waitcnt lgkmcnt(0)
	v_pk_mul_f32 v[48:49], v[44:45], v[152:153] op_sel:[0,1]
	v_pk_mul_f32 v[44:45], v[40:41], v[152:153] op_sel:[0,1]
	v_mov_b64_e32 v[40:41], s[30:31]
	v_mad_i64_i32 v[40:41], s[74:75], v54, s73, v[40:41]
	v_pk_mul_f32 v[46:47], v[46:47], v[152:153] op_sel:[0,1]
	v_pk_mul_f32 v[42:43], v[42:43], v[152:153] op_sel:[0,1]
	v_lshl_add_u64 v[40:41], v[158:159], 1, v[40:41]
	s_and_b64 vcc, exec, s[0:1]
	v_cvt_pk_bf16_f32 v50, v48, v49
	v_cvt_pk_bf16_f32 v51, v46, v47
	v_cvt_pk_bf16_f32 v52, v44, v45
	v_cvt_pk_bf16_f32 v53, v42, v43
	global_store_dwordx4 v[40:41], v[50:53], off
	s_cbranch_vccnz .LBB0_197
	v_mul_f32_e32 v49, v49, v49
	v_mul_f32_e32 v47, v47, v47
	v_fmac_f32_e32 v49, v48, v48
	v_fmac_f32_e32 v47, v46, v46
	v_mul_f32_e32 v45, v45, v45
	v_add_f32_e32 v46, v49, v47
	v_fmac_f32_e32 v45, v44, v44
	v_mul_f32_e32 v43, v43, v43
	v_add_f32_e32 v44, v45, v46
	v_fmac_f32_e32 v43, v42, v42
	v_add_f32_e32 v42, v43, v44
	v_and_b32_e32 v44, 64, v168
	v_xor_b32_e32 v43, 16, v168
	v_add_u32_e32 v44, 64, v44
	v_cmp_lt_i32_e32 vcc, v43, v44
	s_nop 1
	v_cndmask_b32_e32 v43, v168, v43, vcc
	v_lshlrev_b32_e32 v43, 2, v43
	v_mov_b32_e32 v43, v42
	s_nop 1
	v_permlane16_swap_b32_e32 v42, v43
	s_waitcnt lgkmcnt(0)
	v_add_f32_e32 v42, v42, v43
	v_xor_b32_e32 v43, 32, v168
	v_cmp_lt_i32_e32 vcc, v43, v44
	s_nop 1
	v_cndmask_b32_e32 v43, v168, v43, vcc
	v_lshlrev_b32_e32 v43, 2, v43
	v_mov_b32_e32 v43, v42
	s_nop 1
	v_permlane32_swap_b32_e32 v42, v43
	s_and_saveexec_b64 s[90:91], s[2:3]
	s_cbranch_execz .LBB0_196
	s_cmp_eq_u32 s14, 2
	s_cselect_b32 s74, s19, s23
	s_cselect_b32 s75, s97, s22
	v_mov_b32_e32 v44, s75
	v_mov_b32_e32 v45, s74
	v_lshl_add_u64 v[44:45], v[156:157], 2, v[44:45]
	s_waitcnt lgkmcnt(0)
	v_add_f32_e32 v42, v42, v43
	global_atomic_add_f32 v[44:45], v42, off offset:576

; __device__ __forceinline__ unsigned cvt_pk(float lo, float hi) { unsigned r; asm("v_cvt_pk_bf16_f32 %0, %1, %2" : "=v"(r) : "v"(lo), "v"(hi)); return r; }
; __device__ __forceinline__ void fadd_atomic(float* p, float v) { __hip_atomic_fetch_add(p, v, __ATOMIC_RELAXED, __HIP_MEMORY_SCOPE_AGENT); }
;     __device__ __forceinline__ void operator()(const f32x4 (&acc)[2][2][4][2], const Unit& u, int wr, int wc, int fr, int fq) const {
;     ...
;             for (int m = 0; m < 4; ++m) { const int row = row0 + ai * HALF + m * 16; const float s = pre[ai * 4 + m];
; #pragma unroll
;                 for (int bj = 0; bj < 2; ++bj) { const int hc = u.pn * 2 + bj; const int col = u.pn * BM + bj * HALF + wc * 32 + 8 * fq;
;                     const f32x4 v0 = acc[ai][bj][m][0] * s, v1 = acc[ai][bj][m][1] * s;
;                     u32x4 w; w.x = cvt_pk(v0[0], v0[1]); w.y = cvt_pk(v0[2], v0[3]); w.z = cvt_pk(v1[0], v1[1]); w.w = cvt_pk(v1[2], v1[3]);
;                     *(u32x4*)(P + (size_t)row * INP + col) = w;
;                     if (hc < 5) { float q = (v0[0] * v0[0] + v0[1] * v0[1]) + (v0[2] * v0[2] + v0[3] * v0[3]) + (v1[0] * v1[0] + v1[1] * v1[1]) + (v1[2] * v1[2] + v1[3] * v1[3]);
;                         q += __shfl_xor(q, 16); q += __shfl_xor(q, 32);
;                         if (fq == 0) fadd_atomic((hc < 3 ? ss_cq : ss_ckv) + row, q); } } }
.LBB0_197:
	v_mov_b32_e32 v42, v153
	s_waitcnt lgkmcnt(0)
	v_mov_b32_e32 v43, v153
	v_mov_b32_e32 v44, v153
	v_mov_b32_e32 v45, v153
	v_pk_mul_f32 v[38:39], v[38:39], v[44:45]
	v_pk_mul_f32 v[36:37], v[36:37], v[42:43]
	v_pk_mul_f32 v[34:35], v[34:35], v[44:45]
	v_pk_mul_f32 v[32:33], v[32:33], v[42:43]
	s_and_b64 vcc, exec, s[8:9]
	v_cvt_pk_bf16_f32 v42, v36, v37
	v_cvt_pk_bf16_f32 v43, v38, v39
	v_cvt_pk_bf16_f32 v44, v32, v33
	v_cvt_pk_bf16_f32 v45, v34, v35
	global_store_dwordx4 v[40:41], v[42:45], off offset:256
	s_cbranch_vccnz .LBB0_201
	v_mul_f32_e32 v37, v37, v37
	v_fmac_f32_e32 v37, v36, v36
	v_mul_f32_e32 v36, v39, v39
	v_fmac_f32_e32 v36, v38, v38
	v_mul_f32_e32 v33, v33, v33
	v_add_f32_e32 v36, v37, v36
	v_fmac_f32_e32 v33, v32, v32
	v_add_f32_e32 v32, v33, v36
	v_mul_f32_e32 v33, v35, v35
	v_fmac_f32_e32 v33, v34, v34
	v_and_b32_e32 v34, 64, v168
	v_add_f32_e32 v32, v33, v32
	v_xor_b32_e32 v33, 16, v168
	v_add_u32_e32 v34, 64, v34
	v_cmp_lt_i32_e32 vcc, v33, v34
	s_nop 1
	v_cndmask_b32_e32 v33, v168, v33, vcc
	v_lshlrev_b32_e32 v33, 2, v33
	v_mov_b32_e32 v33, v32
	s_nop 1
	v_permlane16_swap_b32_e32 v32, v33
	s_waitcnt lgkmcnt(0)
	v_add_f32_e32 v32, v32, v33
	v_xor_b32_e32 v33, 32, v168
	v_cmp_lt_i32_e32 vcc, v33, v34
	s_nop 1
	v_cndmask_b32_e32 v33, v168, v33, vcc
	v_lshlrev_b32_e32 v33, 2, v33
	v_mov_b32_e32 v33, v32
	s_nop 1
	v_permlane32_swap_b32_e32 v32, v33
	s_and_saveexec_b64 s[90:91], s[2:3]
	s_cbranch_execz .LBB0_200
	s_cmp_lt_i32 s65, 3
	s_cselect_b32 s74, s23, s19
	s_cselect_b32 s75, s22, s97
	v_mov_b32_e32 v34, s75
	v_mov_b32_e32 v35, s74
	v_lshl_add_u64 v[34:35], v[156:157], 2, v[34:35]
	s_waitcnt lgkmcnt(0)
	v_add_f32_e32 v32, v32, v33
	global_atomic_add_f32 v[34:35], v32, off offset:576

; __device__ __forceinline__ unsigned cvt_pk(float lo, float hi) { unsigned r; asm("v_cvt_pk_bf16_f32 %0, %1, %2" : "=v"(r) : "v"(lo), "v"(hi)); return r; }
; __device__ __forceinline__ void fadd_atomic(float* p, float v) { __hip_atomic_fetch_add(p, v, __ATOMIC_RELAXED, __HIP_MEMORY_SCOPE_AGENT); }
;     __device__ __forceinline__ void operator()(const f32x4 (&acc)[2][2][4][2], const Unit& u, int wr, int wc, int fr, int fq) const {
;     ...
;             for (int m = 0; m < 4; ++m) { const int row = row0 + ai * HALF + m * 16; const float s = pre[ai * 4 + m];
; #pragma unroll
;                 for (int bj = 0; bj < 2; ++bj) { const int hc = u.pn * 2 + bj; const int col = u.pn * BM + bj * HALF + wc * 32 + 8 * fq;
;                     const f32x4 v0 = acc[ai][bj][m][0] * s, v1 = acc[ai][bj][m][1] * s;
;                     u32x4 w; w.x = cvt_pk(v0[0], v0[1]); w.y = cvt_pk(v0[2], v0[3]); w.z = cvt_pk(v1[0], v1[1]); w.w = cvt_pk(v1[2], v1[3]);
;                     *(u32x4*)(P + (size_t)row * INP + col) = w;
;                     if (hc < 5) { float q = (v0[0] * v0[0] + v0[1] * v0[1]) + (v0[2] * v0[2] + v0[3] * v0[3]) + (v1[0] * v1[0] + v1[1] * v1[1]) + (v1[2] * v1[2] + v1[3] * v1[3]);
;                         q += __shfl_xor(q, 16); q += __shfl_xor(q, 32);
;                         if (fq == 0) fadd_atomic((hc < 3 ? ss_cq : ss_ckv) + row, q); } } }
.LBB0_201:
	v_add_u32_e32 v38, 0xa0, v156
	s_waitcnt lgkmcnt(0)
	v_pk_mul_f32 v[32:33], v[28:29], v[154:155] op_sel_hi:[1,0]
	v_pk_mul_f32 v[28:29], v[24:25], v[154:155] op_sel_hi:[1,0]
	v_mov_b64_e32 v[24:25], s[30:31]
	v_mad_i64_i32 v[24:25], s[74:75], v38, s73, v[24:25]
	v_pk_mul_f32 v[30:31], v[30:31], v[154:155] op_sel_hi:[1,0]
	v_pk_mul_f32 v[26:27], v[26:27], v[154:155] op_sel_hi:[1,0]
	v_lshl_add_u64 v[24:25], v[158:159], 1, v[24:25]
	s_and_b64 vcc, exec, s[0:1]
	v_cvt_pk_bf16_f32 v34, v32, v33
	v_cvt_pk_bf16_f32 v35, v30, v31
	v_cvt_pk_bf16_f32 v36, v28, v29
	v_cvt_pk_bf16_f32 v37, v26, v27
	global_store_dwordx4 v[24:25], v[34:37], off
	s_cbranch_vccnz .LBB0_205
	v_mul_f32_e32 v33, v33, v33
	v_mul_f32_e32 v31, v31, v31
	v_fmac_f32_e32 v33, v32, v32
	v_fmac_f32_e32 v31, v30, v30
	v_mul_f32_e32 v29, v29, v29
	v_add_f32_e32 v30, v33, v31
	v_fmac_f32_e32 v29, v28, v28
	v_mul_f32_e32 v27, v27, v27
	v_add_f32_e32 v28, v29, v30
	v_fmac_f32_e32 v27, v26, v26
	v_add_f32_e32 v26, v27, v28
	v_and_b32_e32 v28, 64, v168
	v_xor_b32_e32 v27, 16, v168
	v_add_u32_e32 v28, 64, v28
	v_cmp_lt_i32_e32 vcc, v27, v28
	s_nop 1
	v_cndmask_b32_e32 v27, v168, v27, vcc
	v_lshlrev_b32_e32 v27, 2, v27
	v_mov_b32_e32 v27, v26
	s_nop 1
	v_permlane16_swap_b32_e32 v26, v27
	s_waitcnt lgkmcnt(0)
	v_add_f32_e32 v26, v26, v27
	v_xor_b32_e32 v27, 32, v168
	v_cmp_lt_i32_e32 vcc, v27, v28
	s_nop 1
	v_cndmask_b32_e32 v27, v168, v27, vcc
	v_lshlrev_b32_e32 v27, 2, v27
	v_mov_b32_e32 v27, v26
	s_nop 1
	v_permlane32_swap_b32_e32 v26, v27
	s_and_saveexec_b64 s[90:91], s[2:3]
	s_cbranch_execz .LBB0_204
	s_cmp_eq_u32 s14, 2
	s_cselect_b32 s74, s19, s23
	s_cselect_b32 s75, s97, s22
	v_mov_b32_e32 v28, s75
	v_mov_b32_e32 v29, s74
	v_lshl_add_u64 v[28:29], v[156:157], 2, v[28:29]
	s_waitcnt lgkmcnt(0)
	v_add_f32_e32 v26, v26, v27
	global_atomic_add_f32 v[28:29], v26, off offset:640

; __device__ __forceinline__ unsigned cvt_pk(float lo, float hi) { unsigned r; asm("v_cvt_pk_bf16_f32 %0, %1, %2" : "=v"(r) : "v"(lo), "v"(hi)); return r; }
; __device__ __forceinline__ void fadd_atomic(float* p, float v) { __hip_atomic_fetch_add(p, v, __ATOMIC_RELAXED, __HIP_MEMORY_SCOPE_AGENT); }
;     __device__ __forceinline__ void operator()(const f32x4 (&acc)[2][2][4][2], const Unit& u, int wr, int wc, int fr, int fq) const {
;     ...
;             for (int m = 0; m < 4; ++m) { const int row = row0 + ai * HALF + m * 16; const float s = pre[ai * 4 + m];
; #pragma unroll
;                 for (int bj = 0; bj < 2; ++bj) { const int hc = u.pn * 2 + bj; const int col = u.pn * BM + bj * HALF + wc * 32 + 8 * fq;
;                     const f32x4 v0 = acc[ai][bj][m][0] * s, v1 = acc[ai][bj][m][1] * s;
;                     u32x4 w; w.x = cvt_pk(v0[0], v0[1]); w.y = cvt_pk(v0[2], v0[3]); w.z = cvt_pk(v1[0], v1[1]); w.w = cvt_pk(v1[2], v1[3]);
;                     *(u32x4*)(P + (size_t)row * INP + col) = w;
;                     if (hc < 5) { float q = (v0[0] * v0[0] + v0[1] * v0[1]) + (v0[2] * v0[2] + v0[3] * v0[3]) + (v1[0] * v1[0] + v1[1] * v1[1]) + (v1[2] * v1[2] + v1[3] * v1[3]);
;                         q += __shfl_xor(q, 16); q += __shfl_xor(q, 32);
;                         if (fq == 0) fadd_atomic((hc < 3 ? ss_cq : ss_ckv) + row, q); } } }
.LBB0_205:
	v_mov_b32_e32 v26, v154
	s_waitcnt lgkmcnt(0)
	v_mov_b32_e32 v27, v154
	v_mov_b32_e32 v28, v154
	v_mov_b32_e32 v29, v154
	v_pk_mul_f32 v[22:23], v[22:23], v[28:29]
	v_pk_mul_f32 v[20:21], v[20:21], v[26:27]
	v_pk_mul_f32 v[18:19], v[18:19], v[28:29]
	v_pk_mul_f32 v[16:17], v[16:17], v[26:27]
	s_and_b64 vcc, exec, s[8:9]
	v_cvt_pk_bf16_f32 v26, v20, v21
	v_cvt_pk_bf16_f32 v27, v22, v23
	v_cvt_pk_bf16_f32 v28, v16, v17
	v_cvt_pk_bf16_f32 v29, v18, v19
	global_store_dwordx4 v[24:25], v[26:29], off offset:256
	s_cbranch_vccnz .LBB0_209
	v_mul_f32_e32 v21, v21, v21
	v_fmac_f32_e32 v21, v20, v20
	v_mul_f32_e32 v20, v23, v23
	v_fmac_f32_e32 v20, v22, v22
	v_mul_f32_e32 v17, v17, v17
	v_add_f32_e32 v20, v21, v20
	v_fmac_f32_e32 v17, v16, v16
	v_add_f32_e32 v16, v17, v20
	v_mul_f32_e32 v17, v19, v19
	v_fmac_f32_e32 v17, v18, v18
	v_and_b32_e32 v18, 64, v168
	v_add_f32_e32 v16, v17, v16
	v_xor_b32_e32 v17, 16, v168
	v_add_u32_e32 v18, 64, v18
	v_cmp_lt_i32_e32 vcc, v17, v18
	s_nop 1
	v_cndmask_b32_e32 v17, v168, v17, vcc
	v_lshlrev_b32_e32 v17, 2, v17
	v_mov_b32_e32 v17, v16
	s_nop 1
	v_permlane16_swap_b32_e32 v16, v17
	s_waitcnt lgkmcnt(0)
	v_add_f32_e32 v16, v16, v17
	v_xor_b32_e32 v17, 32, v168
	v_cmp_lt_i32_e32 vcc, v17, v18
	s_nop 1
	v_cndmask_b32_e32 v17, v168, v17, vcc
	v_lshlrev_b32_e32 v17, 2, v17
	v_mov_b32_e32 v17, v16
	s_nop 1
	v_permlane32_swap_b32_e32 v16, v17
	s_and_saveexec_b64 s[90:91], s[2:3]
	s_cbranch_execz .LBB0_208
	s_cmp_lt_i32 s65, 3
	s_cselect_b32 s74, s23, s19
	s_cselect_b32 s75, s22, s97
	v_mov_b32_e32 v18, s75
	v_mov_b32_e32 v19, s74
	v_lshl_add_u64 v[18:19], v[156:157], 2, v[18:19]
	s_waitcnt lgkmcnt(0)
	v_add_f32_e32 v16, v16, v17
	global_atomic_add_f32 v[18:19], v16, off offset:640

; __device__ __forceinline__ unsigned cvt_pk(float lo, float hi) { unsigned r; asm("v_cvt_pk_bf16_f32 %0, %1, %2" : "=v"(r) : "v"(lo), "v"(hi)); return r; }
; __device__ __forceinline__ void fadd_atomic(float* p, float v) { __hip_atomic_fetch_add(p, v, __ATOMIC_RELAXED, __HIP_MEMORY_SCOPE_AGENT); }
;     __device__ __forceinline__ void operator()(const f32x4 (&acc)[2][2][4][2], const Unit& u, int wr, int wc, int fr, int fq) const {
;     ...
;             for (int m = 0; m < 4; ++m) { const int row = row0 + ai * HALF + m * 16; const float s = pre[ai * 4 + m];
; #pragma unroll
;                 for (int bj = 0; bj < 2; ++bj) { const int hc = u.pn * 2 + bj; const int col = u.pn * BM + bj * HALF + wc * 32 + 8 * fq;
;                     const f32x4 v0 = acc[ai][bj][m][0] * s, v1 = acc[ai][bj][m][1] * s;
;                     u32x4 w; w.x = cvt_pk(v0[0], v0[1]); w.y = cvt_pk(v0[2], v0[3]); w.z = cvt_pk(v1[0], v1[1]); w.w = cvt_pk(v1[2], v1[3]);
;                     *(u32x4*)(P + (size_t)row * INP + col) = w;
;                     if (hc < 5) { float q = (v0[0] * v0[0] + v0[1] * v0[1]) + (v0[2] * v0[2] + v0[3] * v0[3]) + (v1[0] * v1[0] + v1[1] * v1[1]) + (v1[2] * v1[2] + v1[3] * v1[3]);
;                         q += __shfl_xor(q, 16); q += __shfl_xor(q, 32);
;                         if (fq == 0) fadd_atomic((hc < 3 ? ss_cq : ss_ckv) + row, q); } } }
.LBB0_209:
	v_mov_b32_e32 v18, v155
	v_add_u32_e32 v22, 0xb0, v156
	s_waitcnt lgkmcnt(0)
	v_pk_mul_f32 v[16:17], v[12:13], v[18:19] op_sel_hi:[1,0]
	v_pk_mul_f32 v[12:13], v[8:9], v[18:19] op_sel_hi:[1,0]
	v_mov_b64_e32 v[8:9], s[30:31]
	v_mad_i64_i32 v[8:9], s[74:75], v22, s73, v[8:9]
	v_pk_mul_f32 v[14:15], v[14:15], v[18:19] op_sel_hi:[1,0]
	v_pk_mul_f32 v[10:11], v[10:11], v[18:19] op_sel_hi:[1,0]
	v_lshl_add_u64 v[8:9], v[158:159], 1, v[8:9]
	s_and_b64 vcc, exec, s[0:1]
	v_cvt_pk_bf16_f32 v18, v16, v17
	v_cvt_pk_bf16_f32 v19, v14, v15
	v_cvt_pk_bf16_f32 v20, v12, v13
	v_cvt_pk_bf16_f32 v21, v10, v11
	global_store_dwordx4 v[8:9], v[18:21], off
	s_cbranch_vccnz .LBB0_213
	v_mul_f32_e32 v17, v17, v17
	v_mul_f32_e32 v15, v15, v15
	v_fmac_f32_e32 v17, v16, v16
	v_fmac_f32_e32 v15, v14, v14
	v_mul_f32_e32 v13, v13, v13
	v_add_f32_e32 v14, v17, v15
	v_fmac_f32_e32 v13, v12, v12
	v_mul_f32_e32 v11, v11, v11
	v_add_f32_e32 v12, v13, v14
	v_fmac_f32_e32 v11, v10, v10
	v_add_f32_e32 v10, v11, v12
	v_and_b32_e32 v12, 64, v168
	v_xor_b32_e32 v11, 16, v168
	v_add_u32_e32 v12, 64, v12
	v_cmp_lt_i32_e32 vcc, v11, v12
	s_nop 1
	v_cndmask_b32_e32 v11, v168, v11, vcc
	v_lshlrev_b32_e32 v11, 2, v11
	v_mov_b32_e32 v11, v10
	s_nop 1
	v_permlane16_swap_b32_e32 v10, v11
	s_waitcnt lgkmcnt(0)
	v_add_f32_e32 v10, v10, v11
	v_xor_b32_e32 v11, 32, v168
	v_cmp_lt_i32_e32 vcc, v11, v12
	s_nop 1
	v_cndmask_b32_e32 v11, v168, v11, vcc
	v_lshlrev_b32_e32 v11, 2, v11
	v_mov_b32_e32 v11, v10
	s_nop 1
	v_permlane32_swap_b32_e32 v10, v11
	s_and_saveexec_b64 s[0:1], s[2:3]
	s_cbranch_execz .LBB0_212
	s_cmp_eq_u32 s14, 2
	s_cselect_b32 s14, s19, s23
	s_cselect_b32 s74, s97, s22
	v_mov_b32_e32 v12, s74
	v_mov_b32_e32 v13, s14
	v_lshl_add_u64 v[12:13], v[156:157], 2, v[12:13]
	s_waitcnt lgkmcnt(0)
	v_add_f32_e32 v10, v10, v11
	global_atomic_add_f32 v[12:13], v10, off offset:704

; __device__ __forceinline__ unsigned cvt_pk(float lo, float hi) { unsigned r; asm("v_cvt_pk_bf16_f32 %0, %1, %2" : "=v"(r) : "v"(lo), "v"(hi)); return r; }
; __device__ __forceinline__ void fadd_atomic(float* p, float v) { __hip_atomic_fetch_add(p, v, __ATOMIC_RELAXED, __HIP_MEMORY_SCOPE_AGENT); }
;     __device__ __forceinline__ void operator()(const f32x4 (&acc)[2][2][4][2], const Unit& u, int wr, int wc, int fr, int fq) const {
;     ...
;             for (int m = 0; m < 4; ++m) { const int row = row0 + ai * HALF + m * 16; const float s = pre[ai * 4 + m];
; #pragma unroll
;                 for (int bj = 0; bj < 2; ++bj) { const int hc = u.pn * 2 + bj; const int col = u.pn * BM + bj * HALF + wc * 32 + 8 * fq;
;                     const f32x4 v0 = acc[ai][bj][m][0] * s, v1 = acc[ai][bj][m][1] * s;
;                     u32x4 w; w.x = cvt_pk(v0[0], v0[1]); w.y = cvt_pk(v0[2], v0[3]); w.z = cvt_pk(v1[0], v1[1]); w.w = cvt_pk(v1[2], v1[3]);
;                     *(u32x4*)(P + (size_t)row * INP + col) = w;
;                     if (hc < 5) { float q = (v0[0] * v0[0] + v0[1] * v0[1]) + (v0[2] * v0[2] + v0[3] * v0[3]) + (v1[0] * v1[0] + v1[1] * v1[1]) + (v1[2] * v1[2] + v1[3] * v1[3]);
;                         q += __shfl_xor(q, 16); q += __shfl_xor(q, 32);
;                         if (fq == 0) fadd_atomic((hc < 3 ? ss_cq : ss_ckv) + row, q); } } }
.LBB0_213:
	v_mov_b32_e32 v10, v155
	s_waitcnt lgkmcnt(0)
	v_mov_b32_e32 v11, v155
	v_mov_b32_e32 v12, v155
	v_mov_b32_e32 v13, v155
	v_pk_mul_f32 v[6:7], v[6:7], v[12:13]
	v_pk_mul_f32 v[4:5], v[4:5], v[10:11]
	v_pk_mul_f32 v[2:3], v[2:3], v[12:13]
	v_pk_mul_f32 v[0:1], v[0:1], v[10:11]
	s_and_b64 vcc, exec, s[8:9]
	v_cvt_pk_bf16_f32 v10, v4, v5
	v_cvt_pk_bf16_f32 v11, v6, v7
	v_cvt_pk_bf16_f32 v12, v0, v1
	v_cvt_pk_bf16_f32 v13, v2, v3
	global_store_dwordx4 v[8:9], v[10:13], off offset:256
	s_cbranch_vccnz .LBB0_217
	v_mul_f32_e32 v5, v5, v5
	v_fmac_f32_e32 v5, v4, v4
	v_mul_f32_e32 v4, v7, v7
	v_fmac_f32_e32 v4, v6, v6
	v_mul_f32_e32 v1, v1, v1
	v_add_f32_e32 v4, v5, v4
	v_fmac_f32_e32 v1, v0, v0
	v_add_f32_e32 v0, v1, v4
	v_mul_f32_e32 v1, v3, v3
	v_fmac_f32_e32 v1, v2, v2
	v_and_b32_e32 v2, 64, v168
	v_add_f32_e32 v0, v1, v0
	v_xor_b32_e32 v1, 16, v168
	v_add_u32_e32 v2, 64, v2
	v_cmp_lt_i32_e32 vcc, v1, v2
	s_nop 1
	v_cndmask_b32_e32 v1, v168, v1, vcc
	v_lshlrev_b32_e32 v1, 2, v1
	v_mov_b32_e32 v1, v0
	s_nop 1
	v_permlane16_swap_b32_e32 v0, v1
	s_waitcnt lgkmcnt(0)
	v_add_f32_e32 v0, v0, v1
	v_xor_b32_e32 v1, 32, v168
	v_cmp_lt_i32_e32 vcc, v1, v2
	s_nop 1
	v_cndmask_b32_e32 v1, v168, v1, vcc
	v_lshlrev_b32_e32 v1, 2, v1
	v_mov_b32_e32 v1, v0
	s_nop 1
	v_permlane32_swap_b32_e32 v0, v1
	s_and_saveexec_b64 s[0:1], s[2:3]
	s_cbranch_execz .LBB0_216
	s_cmp_lt_i32 s65, 3
	s_cselect_b32 s8, s23, s19
	s_cselect_b32 s9, s22, s97
	v_mov_b32_e32 v2, s9
	v_mov_b32_e32 v3, s8
	v_lshl_add_u64 v[2:3], v[156:157], 2, v[2:3]
	s_waitcnt lgkmcnt(0)
	v_add_f32_e32 v0, v0, v1
	global_atomic_add_f32 v[2:3], v0, off offset:704

; #define LAS __attribute__((address_space(3)))
; __device__ __forceinline__ float frsq(float x) { return __builtin_amdgcn_rsqf(x); }
; #define MFMA16(a, b, c) __builtin_amdgcn_mfma_f32_16x16x32_bf16((a), (b), (c), 0, 0, 0)
; __device__ __forceinline__ void qkv_head_unit(const Params& p, LAS unsigned char* lds, int h, int blk_begin, int blk_end) {
;     ...
;         for (int pb = blk_begin + 2 * w; pb < blk_end; pb += 16) {
;             const bool two = (pb + 1) < blk_end;
;             const int blk1 = two ? pb + 1 : pb;
;             const int rowm[2] = {16 * pb + fr, 16 * blk1 + fr};
;             bf16x8 af[2][12]; float ssv[2];
; #pragma unroll
;             for (int m = 0; m < 2; ++m) { ssv[m] = ss_cq[rowm[m]];
; #pragma unroll
;                 for (int ks = 0; ks < 12; ++ks) af[m][ks] = *(const bf16x8*)(P + (size_t)rowm[m] * INP + 32 * ks + 8 * fq); }
;             f32x4 acc[2][6];
; #pragma unroll
;             for (int m = 0; m < 2; ++m)
; #pragma unroll
;                 for (int n = 0; n < 6; ++n) acc[m][n] = (f32x4){0.f, 0.f, 0.f, 0.f};
; #pragma unroll
;             for (int ks = 0; ks < 12; ++ks)
; #pragma unroll
;                 for (int n = 0; n < 6; ++n) { const bf16x8 bw = *(const LAS bf16x8*)(wl + (16 * n + fr) * WQS + 32 * ks + 8 * fq);
;                     acc[0][n] = MFMA16(bw, af[0][ks], acc[0][n]); acc[1][n] = MFMA16(bw, af[1][ks], acc[1][n]); }
; #pragma unroll
;             for (int mi = 0; mi < 2; ++mi) {
;                 const bool valid = (mi == 0) || two;
;                 const int t = rowm[mi] % TT;
;                 const float sc = frsq(ssv[mi] * (1.0f / 384.0f) + EPS);
.LBB0_506:
	v_add_u32_e32 v0, 1, v176
	v_cmp_gt_i32_e64 s[2:3], s12, v0
	v_add_u32_e32 v126, s14, v175
	v_ashrrev_i32_e32 v127, 31, v126
	v_cndmask_b32_e64 v0, v176, v0, s[2:3]
	v_lshlrev_b32_e32 v177, 4, v0
	v_or_b32_e32 v124, v177, v158
	v_lshl_add_u64 v[26:27], v[126:127], 2, s[22:23]
	v_ashrrev_i32_e32 v125, 31, v124
	global_load_dword v0, v[26:27], off
	v_lshl_add_u64 v[30:31], v[124:125], 2, s[22:23]
	v_and_b32_e32 v227, 3, v163
	v_bfe_u32 v226, v163, 2, 4
	global_load_dword v125, v[30:31], off
	v_lshlrev_b32_e32 v227, 4, v227
	v_sub_u32_e32 v228, v116, v137
	v_and_b32_e32 v230, -16, v126
	v_add_u32_e32 v228, v228, v227
	v_mov_b32_e32 v229, v117
	v_add_u32_e32 v230, v230, v226
	v_add_u32_e32 v231, v177, v226
	v_mad_i64_i32 v[26:27], s[0:1], v230, s89, v[228:229]
	v_mad_i64_i32 v[30:31], s[0:1], v231, s89, v[228:229]
	global_load_dwordx4 v[178:181], v[26:27], off
	global_load_dwordx4 v[182:185], v[30:31], off
	global_load_dwordx4 v[106:109], v[26:27], off offset:64
	global_load_dwordx4 v[110:113], v[30:31], off offset:64
	global_load_dwordx4 v[98:101], v[26:27], off offset:128
	global_load_dwordx4 v[102:105], v[30:31], off offset:128
	global_load_dwordx4 v[90:93], v[26:27], off offset:192
	global_load_dwordx4 v[94:97], v[30:31], off offset:192
	global_load_dwordx4 v[82:85], v[26:27], off offset:256
	global_load_dwordx4 v[86:89], v[30:31], off offset:256
	global_load_dwordx4 v[74:77], v[26:27], off offset:320
	global_load_dwordx4 v[78:81], v[30:31], off offset:320
	global_load_dwordx4 v[66:69], v[26:27], off offset:384
	global_load_dwordx4 v[70:73], v[30:31], off offset:384
	global_load_dwordx4 v[58:61], v[26:27], off offset:448
	global_load_dwordx4 v[62:65], v[30:31], off offset:448
	global_load_dwordx4 v[50:53], v[26:27], off offset:512
	global_load_dwordx4 v[54:57], v[30:31], off offset:512
	global_load_dwordx4 v[42:45], v[26:27], off offset:576
	global_load_dwordx4 v[46:49], v[30:31], off offset:576
	global_load_dwordx4 v[34:37], v[26:27], off offset:640
	global_load_dwordx4 v[38:41], v[30:31], off offset:640
	s_nop 0
	global_load_dwordx4 v[26:29], v[26:27], off offset:704
	global_load_dwordx4 v[30:33], v[30:31], off offset:704
	s_waitcnt vmcnt(23)
	ds_write_b128 v242, v[178:181]
	ds_read_b128 v[178:181], v243
	s_waitcnt vmcnt(22)
	ds_write_b128 v242, v[182:185] offset:1024
	ds_read_b128 v[182:185], v243 offset:1024
	s_waitcnt vmcnt(21)
	ds_write_b128 v242, v[106:109] offset:2048
	ds_read_b128 v[106:109], v243 offset:2048
	s_waitcnt vmcnt(20)
	ds_write_b128 v242, v[110:113]
	ds_read_b128 v[110:113], v243
	ds_read_b128 v[226:229], v165 offset:0
	ds_read_b128 v[230:233], v165 offset:12544
	ds_read_b128 v[234:237], v165 offset:25088
	ds_read_b128 v[238:241], v165 offset:37632
	s_waitcnt lgkmcnt(3)
	v_mfma_f32_16x16x32_bf16 v[186:189], v[226:229], v[178:181], 0
	v_fmamk_f32 v0, v0, 0x3b2aaaab, v140
	v_rsq_f32_e32 v0, v0
	v_mfma_f32_16x16x32_bf16 v[190:193], v[226:229], v[182:185], 0
	ds_read_b128 v[226:229], v165 offset:50176
	s_waitcnt lgkmcnt(3)
	v_mfma_f32_16x16x32_bf16 v[194:197], v[230:233], v[178:181], 0
	v_mfma_f32_16x16x32_bf16 v[198:201], v[230:233], v[182:185], 0
	ds_read_b128 v[230:233], v165 offset:62720
	s_waitcnt vmcnt(19)
	ds_write_b128 v242, v[98:101] offset:1024
	ds_read_b128 v[98:101], v243 offset:1024
	s_waitcnt vmcnt(18)
	ds_write_b128 v242, v[102:105] offset:2048
	ds_read_b128 v[102:105], v243 offset:2048
	s_waitcnt lgkmcnt(7)
	v_mfma_f32_16x16x32_bf16 v[202:205], v[234:237], v[178:181], 0
	v_mfma_f32_16x16x32_bf16 v[206:209], v[234:237], v[182:185], 0
	ds_read_b128 v[234:237], v165 offset:64
	s_waitcnt lgkmcnt(7)
	v_mfma_f32_16x16x32_bf16 v[210:213], v[238:241], v[178:181], 0
	v_mfma_f32_16x16x32_bf16 v[214:217], v[238:241], v[182:185], 0
	ds_read_b128 v[238:241], v165 offset:12608
	s_waitcnt lgkmcnt(7)
	v_mfma_f32_16x16x32_bf16 v[218:221], v[226:229], v[178:181], 0
	v_mfma_f32_16x16x32_bf16 v[222:225], v[226:229], v[182:185], 0
	ds_read_b128 v[226:229], v165 offset:25152
	s_waitcnt lgkmcnt(7)
	v_mfma_f32_16x16x32_bf16 v[178:181], v[230:233], v[178:181], 0
	v_mfma_f32_16x16x32_bf16 v[182:185], v[230:233], v[182:185], 0
	ds_read_b128 v[230:233], v165 offset:37696
	s_waitcnt lgkmcnt(3)
	v_mfma_f32_16x16x32_bf16 v[186:189], v[234:237], v[106:109], v[186:189]
	v_mfma_f32_16x16x32_bf16 v[190:193], v[234:237], v[110:113], v[190:193]
	ds_read_b128 v[234:237], v165 offset:50240
	s_waitcnt lgkmcnt(3)
	v_mfma_f32_16x16x32_bf16 v[194:197], v[238:241], v[106:109], v[194:197]
	v_mfma_f32_16x16x32_bf16 v[198:201], v[238:241], v[110:113], v[198:201]
	ds_read_b128 v[238:241], v165 offset:62784
	s_waitcnt vmcnt(17)
	ds_write_b128 v242, v[90:93]
	ds_read_b128 v[90:93], v243
	s_waitcnt vmcnt(16)
	ds_write_b128 v242, v[94:97] offset:1024
	ds_read_b128 v[94:97], v243 offset:1024
	s_waitcnt lgkmcnt(7)
	v_mfma_f32_16x16x32_bf16 v[202:205], v[226:229], v[106:109], v[202:205]
	v_mfma_f32_16x16x32_bf16 v[206:209], v[226:229], v[110:113], v[206:209]
	ds_read_b128 v[226:229], v165 offset:128
	s_waitcnt lgkmcnt(7)
	v_mfma_f32_16x16x32_bf16 v[210:213], v[230:233], v[106:109], v[210:213]
	v_mfma_f32_16x16x32_bf16 v[214:217], v[230:233], v[110:113], v[214:217]
	ds_read_b128 v[230:233], v165 offset:12672
	s_waitcnt lgkmcnt(7)
	v_mfma_f32_16x16x32_bf16 v[218:221], v[234:237], v[106:109], v[218:221]
	v_mfma_f32_16x16x32_bf16 v[222:225], v[234:237], v[110:113], v[222:225]
	ds_read_b128 v[234:237], v165 offset:25216
	s_waitcnt lgkmcnt(7)
	v_mfma_f32_16x16x32_bf16 v[178:181], v[238:241], v[106:109], v[178:181]
	v_mfma_f32_16x16x32_bf16 v[182:185], v[238:241], v[110:113], v[182:185]
	ds_read_b128 v[238:241], v165 offset:37760
	s_waitcnt lgkmcnt(3)
; #define LAS __attribute__((address_space(3)))
; #define MFMA16(a, b, c) __builtin_amdgcn_mfma_f32_16x16x32_bf16((a), (b), (c), 0, 0, 0)
; __device__ __forceinline__ void qkv_head_unit(const Params& p, LAS unsigned char* lds, int h, int blk_begin, int blk_end) {
;     ...
; #pragma unroll
;             for (int ks = 0; ks < 12; ++ks)
; #pragma unroll
;                 for (int n = 0; n < 6; ++n) { const bf16x8 bw = *(const LAS bf16x8*)(wl + (16 * n + fr) * WQS + 32 * ks + 8 * fq);
;                     acc[0][n] = MFMA16(bw, af[0][ks], acc[0][n]); acc[1][n] = MFMA16(bw, af[1][ks], acc[1][n]); }
	v_mfma_f32_16x16x32_bf16 v[186:189], v[226:229], v[98:101], v[186:189]
	v_mfma_f32_16x16x32_bf16 v[190:193], v[226:229], v[102:105], v[190:193]
	ds_read_b128 v[226:229], v165 offset:50304
	s_waitcnt lgkmcnt(3)
	v_mfma_f32_16x16x32_bf16 v[194:197], v[230:233], v[98:101], v[194:197]
	v_mfma_f32_16x16x32_bf16 v[198:201], v[230:233], v[102:105], v[198:201]
	ds_read_b128 v[230:233], v165 offset:62848
	s_waitcnt vmcnt(15)
	ds_write_b128 v242, v[82:85] offset:2048
	ds_read_b128 v[82:85], v243 offset:2048
	s_waitcnt vmcnt(14)
	ds_write_b128 v242, v[86:89]
	ds_read_b128 v[86:89], v243
	s_waitcnt lgkmcnt(7)
	v_mfma_f32_16x16x32_bf16 v[202:205], v[234:237], v[98:101], v[202:205]
	v_mfma_f32_16x16x32_bf16 v[206:209], v[234:237], v[102:105], v[206:209]
	ds_read_b128 v[234:237], v165 offset:192
	s_waitcnt lgkmcnt(7)
	v_mfma_f32_16x16x32_bf16 v[210:213], v[238:241], v[98:101], v[210:213]
	v_mfma_f32_16x16x32_bf16 v[214:217], v[238:241], v[102:105], v[214:217]
	ds_read_b128 v[238:241], v165 offset:12736
	s_waitcnt lgkmcnt(7)
	v_mfma_f32_16x16x32_bf16 v[218:221], v[226:229], v[98:101], v[218:221]
	v_mfma_f32_16x16x32_bf16 v[222:225], v[226:229], v[102:105], v[222:225]
	ds_read_b128 v[226:229], v165 offset:25280
	s_waitcnt lgkmcnt(7)
	v_mfma_f32_16x16x32_bf16 v[178:181], v[230:233], v[98:101], v[178:181]
	v_mfma_f32_16x16x32_bf16 v[182:185], v[230:233], v[102:105], v[182:185]
	ds_read_b128 v[230:233], v165 offset:37824
	s_waitcnt lgkmcnt(3)
	v_mfma_f32_16x16x32_bf16 v[186:189], v[234:237], v[90:93], v[186:189]
	v_mfma_f32_16x16x32_bf16 v[190:193], v[234:237], v[94:97], v[190:193]
	ds_read_b128 v[234:237], v165 offset:50368
	s_waitcnt lgkmcnt(3)
	v_mfma_f32_16x16x32_bf16 v[194:197], v[238:241], v[90:93], v[194:197]
	v_mfma_f32_16x16x32_bf16 v[198:201], v[238:241], v[94:97], v[198:201]
	ds_read_b128 v[238:241], v165 offset:62912
	s_waitcnt vmcnt(13)
	ds_write_b128 v242, v[74:77] offset:1024
	ds_read_b128 v[74:77], v243 offset:1024
	s_waitcnt vmcnt(12)
	ds_write_b128 v242, v[78:81] offset:2048
	ds_read_b128 v[78:81], v243 offset:2048
	s_waitcnt lgkmcnt(7)
	v_mfma_f32_16x16x32_bf16 v[202:205], v[226:229], v[90:93], v[202:205]
	v_mfma_f32_16x16x32_bf16 v[206:209], v[226:229], v[94:97], v[206:209]
	ds_read_b128 v[226:229], v165 offset:256
	s_waitcnt lgkmcnt(7)
	v_mfma_f32_16x16x32_bf16 v[210:213], v[230:233], v[90:93], v[210:213]
	v_mfma_f32_16x16x32_bf16 v[214:217], v[230:233], v[94:97], v[214:217]
	ds_read_b128 v[230:233], v165 offset:12800
	s_waitcnt lgkmcnt(7)
	v_mfma_f32_16x16x32_bf16 v[218:221], v[234:237], v[90:93], v[218:221]
	v_mfma_f32_16x16x32_bf16 v[222:225], v[234:237], v[94:97], v[222:225]
	ds_read_b128 v[234:237], v165 offset:25344
	s_waitcnt lgkmcnt(7)
	v_mfma_f32_16x16x32_bf16 v[178:181], v[238:241], v[90:93], v[178:181]
	v_mfma_f32_16x16x32_bf16 v[182:185], v[238:241], v[94:97], v[182:185]
	ds_read_b128 v[238:241], v165 offset:37888
	s_waitcnt lgkmcnt(3)
	v_mfma_f32_16x16x32_bf16 v[186:189], v[226:229], v[82:85], v[186:189]
	v_mfma_f32_16x16x32_bf16 v[190:193], v[226:229], v[86:89], v[190:193]
	ds_read_b128 v[226:229], v165 offset:50432
	s_waitcnt lgkmcnt(3)
	v_mfma_f32_16x16x32_bf16 v[194:197], v[230:233], v[82:85], v[194:197]
	v_mfma_f32_16x16x32_bf16 v[198:201], v[230:233], v[86:89], v[198:201]
	ds_read_b128 v[230:233], v165 offset:62976
	s_waitcnt vmcnt(11)
	ds_write_b128 v242, v[66:69]
	ds_read_b128 v[66:69], v243
	s_waitcnt vmcnt(10)
	ds_write_b128 v242, v[70:73] offset:1024
	ds_read_b128 v[70:73], v243 offset:1024
	s_waitcnt lgkmcnt(7)
	v_mfma_f32_16x16x32_bf16 v[202:205], v[234:237], v[82:85], v[202:205]
	v_mfma_f32_16x16x32_bf16 v[206:209], v[234:237], v[86:89], v[206:209]
	ds_read_b128 v[234:237], v165 offset:320
	s_waitcnt lgkmcnt(7)
	v_mfma_f32_16x16x32_bf16 v[210:213], v[238:241], v[82:85], v[210:213]
	v_mfma_f32_16x16x32_bf16 v[214:217], v[238:241], v[86:89], v[214:217]
	ds_read_b128 v[238:241], v165 offset:12864
	s_waitcnt lgkmcnt(7)
	v_mfma_f32_16x16x32_bf16 v[218:221], v[226:229], v[82:85], v[218:221]
	v_mfma_f32_16x16x32_bf16 v[222:225], v[226:229], v[86:89], v[222:225]
	ds_read_b128 v[226:229], v165 offset:25408
	s_waitcnt lgkmcnt(7)
	v_mfma_f32_16x16x32_bf16 v[178:181], v[230:233], v[82:85], v[178:181]
	v_mfma_f32_16x16x32_bf16 v[182:185], v[230:233], v[86:89], v[182:185]
	ds_read_b128 v[230:233], v165 offset:37952
	s_waitcnt lgkmcnt(3)
	v_mfma_f32_16x16x32_bf16 v[186:189], v[234:237], v[74:77], v[186:189]
	v_mfma_f32_16x16x32_bf16 v[190:193], v[234:237], v[78:81], v[190:193]
	ds_read_b128 v[234:237], v165 offset:50496
	s_waitcnt lgkmcnt(3)
	v_mfma_f32_16x16x32_bf16 v[194:197], v[238:241], v[74:77], v[194:197]
	v_mfma_f32_16x16x32_bf16 v[198:201], v[238:241], v[78:81], v[198:201]
	ds_read_b128 v[238:241], v165 offset:63040
	s_waitcnt vmcnt(9)
	ds_write_b128 v242, v[58:61] offset:2048
	ds_read_b128 v[58:61], v243 offset:2048
	s_waitcnt vmcnt(8)
	ds_write_b128 v242, v[62:65]
	ds_read_b128 v[62:65], v243
	s_waitcnt lgkmcnt(7)
	v_mfma_f32_16x16x32_bf16 v[202:205], v[226:229], v[74:77], v[202:205]
	v_mfma_f32_16x16x32_bf16 v[206:209], v[226:229], v[78:81], v[206:209]
	ds_read_b128 v[226:229], v165 offset:384
	s_waitcnt lgkmcnt(7)
	v_mfma_f32_16x16x32_bf16 v[210:213], v[230:233], v[74:77], v[210:213]
	v_mfma_f32_16x16x32_bf16 v[214:217], v[230:233], v[78:81], v[214:217]
	ds_read_b128 v[230:233], v165 offset:12928
	s_waitcnt lgkmcnt(7)
	v_mfma_f32_16x16x32_bf16 v[218:221], v[234:237], v[74:77], v[218:221]
	v_mfma_f32_16x16x32_bf16 v[222:225], v[234:237], v[78:81], v[222:225]
	ds_read_b128 v[234:237], v165 offset:25472
	s_waitcnt lgkmcnt(7)
; #define LAS __attribute__((address_space(3)))
; #define MFMA16(a, b, c) __builtin_amdgcn_mfma_f32_16x16x32_bf16((a), (b), (c), 0, 0, 0)
; __device__ __forceinline__ void qkv_head_unit(const Params& p, LAS unsigned char* lds, int h, int blk_begin, int blk_end) {
;     ...
; #pragma unroll
;             for (int ks = 0; ks < 12; ++ks)
; #pragma unroll
;                 for (int n = 0; n < 6; ++n) { const bf16x8 bw = *(const LAS bf16x8*)(wl + (16 * n + fr) * WQS + 32 * ks + 8 * fq);
;                     acc[0][n] = MFMA16(bw, af[0][ks], acc[0][n]); acc[1][n] = MFMA16(bw, af[1][ks], acc[1][n]); }
	v_mfma_f32_16x16x32_bf16 v[178:181], v[238:241], v[74:77], v[178:181]
	v_mfma_f32_16x16x32_bf16 v[182:185], v[238:241], v[78:81], v[182:185]
	ds_read_b128 v[238:241], v165 offset:38016
	s_waitcnt lgkmcnt(3)
	v_mfma_f32_16x16x32_bf16 v[186:189], v[226:229], v[66:69], v[186:189]
	v_mfma_f32_16x16x32_bf16 v[190:193], v[226:229], v[70:73], v[190:193]
	ds_read_b128 v[226:229], v165 offset:50560
	s_waitcnt lgkmcnt(3)
	v_mfma_f32_16x16x32_bf16 v[194:197], v[230:233], v[66:69], v[194:197]
	v_mfma_f32_16x16x32_bf16 v[198:201], v[230:233], v[70:73], v[198:201]
	ds_read_b128 v[230:233], v165 offset:63104
	s_waitcnt vmcnt(7)
	ds_write_b128 v242, v[50:53] offset:1024
	ds_read_b128 v[50:53], v243 offset:1024
	s_waitcnt vmcnt(6)
	ds_write_b128 v242, v[54:57] offset:2048
	ds_read_b128 v[54:57], v243 offset:2048
	s_waitcnt lgkmcnt(7)
	v_mfma_f32_16x16x32_bf16 v[202:205], v[234:237], v[66:69], v[202:205]
	v_mfma_f32_16x16x32_bf16 v[206:209], v[234:237], v[70:73], v[206:209]
	ds_read_b128 v[234:237], v165 offset:448
	s_waitcnt lgkmcnt(7)
	v_mfma_f32_16x16x32_bf16 v[210:213], v[238:241], v[66:69], v[210:213]
	v_mfma_f32_16x16x32_bf16 v[214:217], v[238:241], v[70:73], v[214:217]
	ds_read_b128 v[238:241], v165 offset:12992
	s_waitcnt lgkmcnt(7)
	v_mfma_f32_16x16x32_bf16 v[218:221], v[226:229], v[66:69], v[218:221]
	v_mfma_f32_16x16x32_bf16 v[222:225], v[226:229], v[70:73], v[222:225]
	ds_read_b128 v[226:229], v165 offset:25536
	s_waitcnt lgkmcnt(7)
	v_mfma_f32_16x16x32_bf16 v[178:181], v[230:233], v[66:69], v[178:181]
	v_mfma_f32_16x16x32_bf16 v[182:185], v[230:233], v[70:73], v[182:185]
	ds_read_b128 v[230:233], v165 offset:38080
	s_waitcnt lgkmcnt(3)
	v_mfma_f32_16x16x32_bf16 v[186:189], v[234:237], v[58:61], v[186:189]
	v_mfma_f32_16x16x32_bf16 v[190:193], v[234:237], v[62:65], v[190:193]
	ds_read_b128 v[234:237], v165 offset:50624
	s_waitcnt lgkmcnt(3)
	v_mfma_f32_16x16x32_bf16 v[194:197], v[238:241], v[58:61], v[194:197]
	v_mfma_f32_16x16x32_bf16 v[198:201], v[238:241], v[62:65], v[198:201]
	ds_read_b128 v[238:241], v165 offset:63168
	s_waitcnt vmcnt(5)
	ds_write_b128 v242, v[42:45]
	ds_read_b128 v[42:45], v243
	s_waitcnt vmcnt(4)
	ds_write_b128 v242, v[46:49] offset:1024
	ds_read_b128 v[46:49], v243 offset:1024
	s_waitcnt lgkmcnt(7)
	v_mfma_f32_16x16x32_bf16 v[202:205], v[226:229], v[58:61], v[202:205]
	v_mfma_f32_16x16x32_bf16 v[206:209], v[226:229], v[62:65], v[206:209]
	ds_read_b128 v[226:229], v165 offset:512
	s_waitcnt lgkmcnt(7)
	v_mfma_f32_16x16x32_bf16 v[210:213], v[230:233], v[58:61], v[210:213]
	v_mfma_f32_16x16x32_bf16 v[214:217], v[230:233], v[62:65], v[214:217]
	ds_read_b128 v[230:233], v165 offset:13056
	s_waitcnt lgkmcnt(7)
	v_mfma_f32_16x16x32_bf16 v[218:221], v[234:237], v[58:61], v[218:221]
	v_mfma_f32_16x16x32_bf16 v[222:225], v[234:237], v[62:65], v[222:225]
	ds_read_b128 v[234:237], v165 offset:25600
	s_waitcnt lgkmcnt(7)
	v_mfma_f32_16x16x32_bf16 v[178:181], v[238:241], v[58:61], v[178:181]
	v_mfma_f32_16x16x32_bf16 v[182:185], v[238:241], v[62:65], v[182:185]
	ds_read_b128 v[238:241], v165 offset:38144
	s_waitcnt lgkmcnt(3)
	v_mfma_f32_16x16x32_bf16 v[186:189], v[226:229], v[50:53], v[186:189]
	v_mfma_f32_16x16x32_bf16 v[190:193], v[226:229], v[54:57], v[190:193]
	ds_read_b128 v[226:229], v165 offset:50688
	s_waitcnt lgkmcnt(3)
	v_mfma_f32_16x16x32_bf16 v[194:197], v[230:233], v[50:53], v[194:197]
	v_mfma_f32_16x16x32_bf16 v[198:201], v[230:233], v[54:57], v[198:201]
	ds_read_b128 v[230:233], v165 offset:63232
	s_waitcnt vmcnt(3)
	ds_write_b128 v242, v[34:37] offset:2048
	ds_read_b128 v[34:37], v243 offset:2048
	s_waitcnt vmcnt(2)
	ds_write_b128 v242, v[38:41]
	ds_read_b128 v[38:41], v243
	s_waitcnt lgkmcnt(7)
	v_mfma_f32_16x16x32_bf16 v[202:205], v[234:237], v[50:53], v[202:205]
	v_mfma_f32_16x16x32_bf16 v[206:209], v[234:237], v[54:57], v[206:209]
	ds_read_b128 v[234:237], v165 offset:576
	s_waitcnt lgkmcnt(7)
	v_mfma_f32_16x16x32_bf16 v[210:213], v[238:241], v[50:53], v[210:213]
	v_mfma_f32_16x16x32_bf16 v[214:217], v[238:241], v[54:57], v[214:217]
	ds_read_b128 v[238:241], v165 offset:13120
	s_waitcnt lgkmcnt(7)
	v_mfma_f32_16x16x32_bf16 v[218:221], v[226:229], v[50:53], v[218:221]
	v_mfma_f32_16x16x32_bf16 v[222:225], v[226:229], v[54:57], v[222:225]
	ds_read_b128 v[226:229], v165 offset:25664
	s_waitcnt lgkmcnt(7)
	v_mfma_f32_16x16x32_bf16 v[178:181], v[230:233], v[50:53], v[178:181]
	v_mfma_f32_16x16x32_bf16 v[182:185], v[230:233], v[54:57], v[182:185]
	ds_read_b128 v[230:233], v165 offset:38208
	s_waitcnt lgkmcnt(3)
	v_mfma_f32_16x16x32_bf16 v[186:189], v[234:237], v[42:45], v[186:189]
	v_mfma_f32_16x16x32_bf16 v[190:193], v[234:237], v[46:49], v[190:193]
	ds_read_b128 v[234:237], v165 offset:50752
	s_waitcnt lgkmcnt(3)
	v_mfma_f32_16x16x32_bf16 v[194:197], v[238:241], v[42:45], v[194:197]
	v_mfma_f32_16x16x32_bf16 v[198:201], v[238:241], v[46:49], v[198:201]
	ds_read_b128 v[238:241], v165 offset:63296
	s_waitcnt vmcnt(1)
	ds_write_b128 v242, v[26:29] offset:1024
	ds_read_b128 v[26:29], v243 offset:1024
	s_waitcnt vmcnt(0)
	ds_write_b128 v242, v[30:33] offset:2048
	ds_read_b128 v[30:33], v243 offset:2048
	s_waitcnt lgkmcnt(7)
	v_mfma_f32_16x16x32_bf16 v[202:205], v[226:229], v[42:45], v[202:205]
	v_mfma_f32_16x16x32_bf16 v[206:209], v[226:229], v[46:49], v[206:209]
	ds_read_b128 v[226:229], v165 offset:640
	s_waitcnt lgkmcnt(7)
	v_mfma_f32_16x16x32_bf16 v[210:213], v[230:233], v[42:45], v[210:213]
	v_mfma_f32_16x16x32_bf16 v[214:217], v[230:233], v[46:49], v[214:217]
	ds_read_b128 v[230:233], v165 offset:13184
	s_waitcnt lgkmcnt(7)
; #define LAS __attribute__((address_space(3)))
; __device__ __forceinline__ float frsq(float x) { return __builtin_amdgcn_rsqf(x); }
; #define MFMA16(a, b, c) __builtin_amdgcn_mfma_f32_16x16x32_bf16((a), (b), (c), 0, 0, 0)
; __device__ __forceinline__ void qkv_head_unit(const Params& p, LAS unsigned char* lds, int h, int blk_begin, int blk_end) {
;     ...
; #pragma unroll
;             for (int ks = 0; ks < 12; ++ks)
; #pragma unroll
;                 for (int n = 0; n < 6; ++n) { const bf16x8 bw = *(const LAS bf16x8*)(wl + (16 * n + fr) * WQS + 32 * ks + 8 * fq);
;                     acc[0][n] = MFMA16(bw, af[0][ks], acc[0][n]); acc[1][n] = MFMA16(bw, af[1][ks], acc[1][n]); }
; #pragma unroll
;             for (int mi = 0; mi < 2; ++mi) {
;                 const bool valid = (mi == 0) || two;
;                 const int t = rowm[mi] % TT;
;                 const float sc = frsq(ssv[mi] * (1.0f / 384.0f) + EPS);
;                 float ssq = 0.f;
; #pragma unroll
;                 for (int n = 0; n < 6; ++n) { acc[mi][n] *= sc; ssq += (acc[mi][n][0] * acc[mi][n][0] + acc[mi][n][1] * acc[mi][n][1]) + (acc[mi][n][2] * acc[mi][n][2] + acc[mi][n][3] * acc[mi][n][3]); }
;                 ssq += __shfl_xor(ssq, 16); ssq += __shfl_xor(ssq, 32);
	v_mfma_f32_16x16x32_bf16 v[218:221], v[234:237], v[42:45], v[218:221]
	v_mfma_f32_16x16x32_bf16 v[222:225], v[234:237], v[46:49], v[222:225]
	ds_read_b128 v[234:237], v165 offset:25728
	s_waitcnt lgkmcnt(7)
	v_mfma_f32_16x16x32_bf16 v[178:181], v[238:241], v[42:45], v[178:181]
	v_mfma_f32_16x16x32_bf16 v[182:185], v[238:241], v[46:49], v[182:185]
	ds_read_b128 v[238:241], v165 offset:38272
	s_waitcnt lgkmcnt(3)
	v_mfma_f32_16x16x32_bf16 v[186:189], v[226:229], v[34:37], v[186:189]
	v_mfma_f32_16x16x32_bf16 v[190:193], v[226:229], v[38:41], v[190:193]
	ds_read_b128 v[226:229], v165 offset:50816
	s_waitcnt lgkmcnt(3)
	v_mfma_f32_16x16x32_bf16 v[194:197], v[230:233], v[34:37], v[194:197]
	v_mfma_f32_16x16x32_bf16 v[198:201], v[230:233], v[38:41], v[198:201]
	ds_read_b128 v[230:233], v165 offset:63360
	s_waitcnt lgkmcnt(3)
	v_mfma_f32_16x16x32_bf16 v[202:205], v[234:237], v[34:37], v[202:205]
	v_mfma_f32_16x16x32_bf16 v[206:209], v[234:237], v[38:41], v[206:209]
	ds_read_b128 v[234:237], v165 offset:704
	s_waitcnt lgkmcnt(3)
	v_mfma_f32_16x16x32_bf16 v[210:213], v[238:241], v[34:37], v[210:213]
	v_mfma_f32_16x16x32_bf16 v[214:217], v[238:241], v[38:41], v[214:217]
	ds_read_b128 v[238:241], v165 offset:13248
	s_waitcnt lgkmcnt(3)
	v_mfma_f32_16x16x32_bf16 v[218:221], v[226:229], v[34:37], v[218:221]
	v_mfma_f32_16x16x32_bf16 v[222:225], v[226:229], v[38:41], v[222:225]
	ds_read_b128 v[226:229], v165 offset:25792
	s_waitcnt lgkmcnt(3)
	v_mfma_f32_16x16x32_bf16 v[178:181], v[230:233], v[34:37], v[178:181]
	v_mfma_f32_16x16x32_bf16 v[182:185], v[230:233], v[38:41], v[182:185]
	ds_read_b128 v[230:233], v165 offset:38336
	s_waitcnt lgkmcnt(3)
	v_mfma_f32_16x16x32_bf16 v[54:57], v[234:237], v[26:29], v[186:189]
	v_mfma_f32_16x16x32_bf16 v[34:37], v[234:237], v[30:33], v[190:193]
	ds_read_b128 v[234:237], v165 offset:50880
	s_waitcnt lgkmcnt(3)
	v_mfma_f32_16x16x32_bf16 v[62:65], v[238:241], v[26:29], v[194:197]
	v_mfma_f32_16x16x32_bf16 v[46:49], v[238:241], v[30:33], v[198:201]
	ds_read_b128 v[238:241], v165 offset:63424
	s_waitcnt lgkmcnt(3)
	v_mfma_f32_16x16x32_bf16 v[58:61], v[226:229], v[26:29], v[202:205]
	v_mfma_f32_16x16x32_bf16 v[50:53], v[226:229], v[30:33], v[206:209]
	s_waitcnt lgkmcnt(2)
	v_mfma_f32_16x16x32_bf16 v[66:69], v[230:233], v[26:29], v[210:213]
	v_mfma_f32_16x16x32_bf16 v[42:45], v[230:233], v[30:33], v[214:217]
	s_waitcnt lgkmcnt(1)
	v_mfma_f32_16x16x32_bf16 v[70:73], v[234:237], v[26:29], v[218:221]
	v_mfma_f32_16x16x32_bf16 v[38:41], v[234:237], v[30:33], v[222:225]
	s_waitcnt lgkmcnt(0)
	v_mfma_f32_16x16x32_bf16 v[78:81], v[238:241], v[26:29], v[178:181]
	v_mfma_f32_16x16x32_bf16 v[26:29], v[238:241], v[30:33], v[182:185]
	s_nop 7
	v_pk_mul_f32 v[68:69], v[0:1], v[68:69] op_sel_hi:[0,1]
	v_pk_mul_f32 v[66:67], v[0:1], v[66:67] op_sel_hi:[0,1]
	v_mul_f32_e64 v72, v0, v72
	v_mul_f32_e64 v73, v0, v73
	v_pk_mul_f32 v[70:71], v[0:1], v[70:71] op_sel_hi:[0,1]
	v_mul_f32_e64 v32, v0, v54
	v_mul_f32_e64 v33, v0, v55
	v_pk_mul_f32 v[76:77], v[0:1], v[58:59] op_sel_hi:[0,1]
	v_mul_f32_e32 v58, v33, v33
	v_pk_mul_f32 v[30:31], v[0:1], v[56:57] op_sel_hi:[0,1]
	v_pk_mul_f32 v[74:75], v[0:1], v[60:61] op_sel_hi:[0,1]
	v_mul_f32_e32 v60, v76, v76
	v_pk_fma_f32 v[58:59], v[32:33], v[32:33], v[58:59] op_sel_hi:[1,1,0]
	v_pk_mul_f32 v[56:57], v[0:1], v[62:63] op_sel_hi:[0,1]
	v_mov_b32_e32 v59, v60
	v_mul_f32_e32 v60, v31, v31
	v_mul_f32_e32 v62, v77, v77
	v_pk_fma_f32 v[60:61], v[30:31], v[30:31], v[60:61] op_sel_hi:[1,1,0]
	v_pk_mul_f32 v[54:55], v[0:1], v[64:65] op_sel_hi:[0,1]
	v_mov_b32_e32 v61, v62
	v_pk_add_f32 v[58:59], v[58:59], v[60:61]
	v_mul_f32_e32 v60, v57, v57
	v_mul_f32_e32 v63, v74, v74
	v_pk_fma_f32 v[60:61], v[56:57], v[56:57], v[60:61] op_sel_hi:[1,1,0]
	v_mul_f32_e32 v62, v55, v55
	v_mul_f32_e32 v64, v75, v75
	v_mov_b32_e32 v61, v63
	v_pk_fma_f32 v[62:63], v[54:55], v[54:55], v[62:63] op_sel_hi:[1,1,0]
	v_pk_mul_f32 v[78:79], v[0:1], v[78:79] op_sel_hi:[0,1]
	v_mov_b32_e32 v63, v64
	v_pk_add_f32 v[60:61], v[60:61], v[62:63]
	v_pk_mul_f32 v[62:63], v[68:69], v[68:69]
	v_pk_add_f32 v[58:59], v[58:59], v[60:61]
	v_pk_mul_f32 v[60:61], v[66:67], v[66:67]
	v_pk_mul_f32 v[80:81], v[0:1], v[80:81] op_sel_hi:[0,1]
	v_pk_mov_b32 v[64:65], v[60:61], v[62:63] op_sel:[1,0]
	v_mov_b32_e32 v61, v63
	v_pk_add_f32 v[60:61], v[64:65], v[60:61]
	v_mul_f32_e32 v0, v78, v78
	v_mul_f32_e32 v62, v79, v79
	v_pk_add_f32 v[58:59], v[58:59], v[58:59] op_sel:[0,1] op_sel_hi:[1,0]
	v_pk_add_f32 v[60:61], v[60:61], v[60:61] op_sel:[0,1] op_sel_hi:[1,0]
	v_mov_b32_e32 v59, v0
	v_mov_b32_e32 v61, v62
	v_mul_f32_e32 v0, v71, v71
	v_mul_f32_e32 v63, v80, v80
	v_pk_add_f32 v[58:59], v[58:59], v[60:61]
	v_pk_fma_f32 v[60:61], v[70:71], v[70:71], v[0:1] op_sel_hi:[1,1,0]
	v_mul_f32_e32 v0, v73, v73
	v_mul_f32_e32 v64, v81, v81
	v_mov_b32_e32 v61, v63
	v_pk_fma_f32 v[62:63], v[72:73], v[72:73], v[0:1] op_sel_hi:[1,1,0]
	s_nop 0
	v_mov_b32_e32 v63, v64
	v_pk_add_f32 v[60:61], v[60:61], v[62:63]
	s_nop 0
	v_pk_add_f32 v[58:59], v[58:59], v[60:61]
	s_nop 0
	v_add_f32_e32 v0, v58, v59
	v_mov_b32_e32 v58, v0
	s_nop 1
	v_permlane16_swap_b32_e32 v0, v58
	s_waitcnt lgkmcnt(0)
	v_add_f32_e32 v0, v0, v58
	v_mov_b32_e32 v58, v0
	s_nop 1
	v_permlane32_swap_b32_e32 v0, v58
	s_waitcnt lgkmcnt(0)
; #define LAS __attribute__((address_space(3)))
; __device__ __forceinline__ unsigned cvt_pk(float lo, float hi) { unsigned r; asm("v_cvt_pk_bf16_f32 %0, %1, %2" : "=v"(r) : "v"(lo), "v"(hi)); return r; }
; __device__ __forceinline__ float frsq(float x) { return __builtin_amdgcn_rsqf(x); }
; __device__ __forceinline__ void qkv_head_unit(const Params& p, LAS unsigned char* lds, int h, int blk_begin, int blk_end) {
;     ...
;                 const float rq = frsq(ssq * (1.0f / 96.0f) + EPS);
; #pragma unroll
;                 for (int n = 0; n < 6; ++n) acc[mi][n] = acc[mi][n] * rq * gvv[n];
; #pragma unroll
;                 for (int i = 0; i < 4; ++i) { float sn, cs; sincos_rr((float)t * frq[i], sn, cs);
;                     const float x1 = acc[mi][4][i], x2 = acc[mi][5][i]; acc[mi][4][i] = x1 * cs - x2 * sn; acc[mi][5][i] = x1 * sn + x2 * cs; }
; #pragma unroll
;                 for (int n = 0; n < 6; ++n) { u32x2 wv; wv.x = cvt_pk(acc[mi][n][0] * QSCALE, acc[mi][n][1] * QSCALE); wv.y = cvt_pk(acc[mi][n][2] * QSCALE, acc[mi][n][3] * QSCALE); *(LAS u32x2*)(stg + fr * 104 + 16 * n + 4 * fq) = wv; }
;                 asm volatile("s_waitcnt lgkmcnt(0)" ::: "memory");
; #pragma unroll
;                 for (int j = 0; j < 3; ++j) { const int c = lane + 64 * j, rw = c / 12, cc = c % 12; const int row2 = 16 * (mi ? blk1 : pb) + rw, b2 = row2 / TT, t2 = row2 % TT;
;                     const u32x4 v = *(const LAS u32x4*)(stg + rw * 104 + 8 * cc);
;                     if (valid && t2 >= NMETA) *(u32x4*)(Q + (((size_t)(b2 * NH + h)) * SEQ + (t2 - NMETA)) * QKH + 8 * cc) = v; }
;                 asm volatile("s_waitcnt lgkmcnt(0)" ::: "memory"); __builtin_amdgcn_sched_barrier(0);
	v_add_f32_e32 v0, v0, v58
	v_fmamk_f32 v0, v0, 0x3c2aaaab, v140
	v_rsq_f32_e32 v0, v0
	s_nop 0
	v_pk_mul_f32 v[32:33], v[32:33], v[0:1] op_sel_hi:[1,0]
	v_pk_mul_f32 v[30:31], v[30:31], v[0:1] op_sel_hi:[1,0]
	v_pk_mul_f32 v[64:65], v[2:3], v[32:33]
	v_pk_mul_f32 v[32:33], v[54:55], v[0:1] op_sel_hi:[1,0]
	v_pk_mul_f32 v[62:63], v[4:5], v[30:31]
	v_pk_mul_f32 v[30:31], v[56:57], v[0:1] op_sel_hi:[1,0]
	v_pk_mul_f32 v[58:59], v[8:9], v[32:33]
	v_pk_mul_f32 v[32:33], v[74:75], v[0:1] op_sel_hi:[1,0]
	v_pk_mul_f32 v[60:61], v[6:7], v[30:31]
	v_pk_mul_f32 v[30:31], v[76:77], v[0:1] op_sel_hi:[1,0]
	v_pk_mul_f32 v[54:55], v[12:13], v[32:33]
	v_pk_mul_f32 v[32:33], v[66:67], v[0:1] op_sel_hi:[1,0]
	v_pk_mul_f32 v[66:67], v[70:71], v[0:1] op_sel_hi:[1,0]
	v_pk_mul_f32 v[56:57], v[10:11], v[30:31]
	v_pk_mul_f32 v[30:31], v[68:69], v[0:1] op_sel_hi:[1,0]
	v_pk_mul_f32 v[68:69], v[72:73], v[0:1] op_sel_hi:[1,0]
	v_pk_mul_f32 v[72:73], v[18:19], v[66:67]
	v_pk_mul_f32 v[70:71], v[78:79], v[0:1] op_sel_hi:[1,0]
	v_pk_mul_f32 v[66:67], v[80:81], v[0:1] op_sel_hi:[1,0]
	v_mul_hi_i32 v0, v126, s90
	v_lshrrev_b32_e32 v74, 31, v0
	v_ashrrev_i32_e32 v0, 7, v0
	v_add_u32_e32 v0, v0, v74
	v_mul_lo_u32 v0, v0, s86
	v_sub_u32_e32 v0, v126, v0
	v_cvt_f32_i32_e32 v0, v0
	v_pk_mul_f32 v[70:71], v[22:23], v[70:71]
	v_mov_b32_e32 v76, v72
	v_mov_b32_e32 v77, v70
	v_mul_f32_e32 v74, v154, v0
	v_mul_f32_e32 v75, 0.15915494, v74
	v_rndne_f32_e32 v75, v75
	v_fmac_f32_e32 v74, 0xc0c90fdb, v75
	v_fmac_f32_e32 v74, 0x343bbd2e, v75
	v_mul_f32_e32 v74, 0.15915494, v74
	v_sin_f32_e32 v75, v74
	v_cos_f32_e32 v74, v74
	v_mul_f32_e32 v70, v155, v0
	v_mul_f32_e32 v72, 0.15915494, v70
	v_rndne_f32_e32 v72, v72
	v_pk_mul_f32 v[78:79], v[74:75], v[76:77]
	v_fmac_f32_e32 v70, 0xc0c90fdb, v72
	v_sub_f32_e32 v80, v78, v79
	v_mov_b32_e32 v78, v75
	v_mov_b32_e32 v79, v74
	v_fmac_f32_e32 v70, 0x343bbd2e, v72
	v_pk_mul_f32 v[74:75], v[78:79], v[76:77]
	v_mul_f32_e32 v70, 0.15915494, v70
	v_add_f32_e32 v76, v74, v75
	v_sin_f32_e32 v75, v70
	v_cos_f32_e32 v74, v70
	v_mov_b32_e32 v70, v73
	v_pk_mul_f32 v[66:67], v[24:25], v[66:67]
	v_pk_mul_f32 v[68:69], v[20:21], v[68:69]
	v_pk_mul_f32 v[72:73], v[74:75], v[70:71]
	v_pk_mul_f32 v[30:31], v[16:17], v[30:31]
	v_sub_f32_e32 v77, v72, v73
	v_mov_b32_e32 v72, v75
	v_mov_b32_e32 v73, v74
	v_pk_mul_f32 v[70:71], v[72:73], v[70:71]
	v_mov_b32_e32 v73, v66
	v_add_f32_e32 v78, v70, v71
	v_mul_f32_e32 v70, v156, v0
	v_mul_f32_e32 v71, 0.15915494, v70
	v_rndne_f32_e32 v71, v71
	v_fmac_f32_e32 v70, 0xc0c90fdb, v71
	v_fmac_f32_e32 v70, 0x343bbd2e, v71
	v_mul_f32_e32 v70, 0.15915494, v70
	v_sin_f32_e32 v71, v70
	v_cos_f32_e32 v70, v70
	v_mul_f32_e32 v0, v157, v0
	v_mul_f32_e32 v66, 0.15915494, v0
	v_mov_b32_e32 v72, v68
	v_rndne_f32_e32 v66, v66
	v_pk_mul_f32 v[74:75], v[70:71], v[72:73]
	v_fmac_f32_e32 v0, 0xc0c90fdb, v66
	v_sub_f32_e32 v79, v74, v75
	v_mov_b32_e32 v74, v71
	v_mov_b32_e32 v75, v70
	v_fmac_f32_e32 v0, 0x343bbd2e, v66
	v_pk_mul_f32 v[70:71], v[74:75], v[72:73]
	v_mul_f32_e32 v0, 0.15915494, v0
	v_add_f32_e32 v72, v70, v71
	v_sin_f32_e32 v71, v0
	v_cos_f32_e32 v70, v0
	v_pk_mul_f32 v[32:33], v[14:15], v[32:33]
	v_mov_b32_e32 v66, v69
	v_mul_f32_e32 v32, 0x3e16c740, v32
	v_pk_mul_f32 v[68:69], v[70:71], v[66:67]
	v_mul_f32_e32 v33, 0x3e16c740, v33
	v_mul_f32_e32 v30, 0x3e16c740, v30
	v_mul_f32_e32 v31, 0x3e16c740, v31
	v_sub_f32_e32 v0, v68, v69
	v_mov_b32_e32 v68, v71
	v_mov_b32_e32 v69, v70
	v_mul_f32_e32 v64, 0x3e16c740, v64
	v_mul_f32_e32 v65, 0x3e16c740, v65
	v_mul_f32_e32 v62, 0x3e16c740, v62
	v_cvt_pk_bf16_f32 v32, v32, v33
	v_cvt_pk_bf16_f32 v33, v30, v31
	v_mul_f32_e32 v30, 0x3e16c740, v80
	v_mul_f32_e32 v31, 0x3e16c740, v77
	v_pk_mul_f32 v[66:67], v[68:69], v[66:67]
	v_cvt_pk_bf16_f32 v64, v64, v65
	v_mul_f32_e32 v63, 0x3e16c740, v63
	v_cvt_pk_bf16_f32 v65, v62, v63
	v_add_u32_e32 v62, v160, v114
	v_mul_f32_e32 v56, 0x3e16c740, v56
	v_mul_f32_e32 v57, 0x3e16c740, v57
	v_cvt_pk_bf16_f32 v30, v30, v31
	v_mul_f32_e32 v31, 0x3e16c740, v79
	v_mul_f32_e32 v0, 0x3e16c740, v0
	v_add_f32_e32 v66, v66, v67
	v_cvt_pk_bf16_f32 v56, v56, v57
	v_mul_f32_e32 v54, 0x3e16c740, v54
	v_mul_f32_e32 v55, 0x3e16c740, v55
	v_cvt_pk_bf16_f32 v57, v54, v55
	ds_write2_b64 v62, v[56:57], v[32:33] offset0:8 offset1:12
	v_cvt_pk_bf16_f32 v31, v31, v0
	v_mul_f32_e32 v0, 0x3e16c740, v76
	v_mul_f32_e32 v32, 0x3e16c740, v78
	v_cvt_pk_bf16_f32 v32, v0, v32
	v_mul_f32_e32 v0, 0x3e16c740, v72
	v_mul_f32_e32 v33, 0x3e16c740, v66
	v_cvt_pk_bf16_f32 v33, v0, v33
	v_add_u32_e32 v0, s14, v174
	ds_write2_b64 v62, v[30:31], v[32:33] offset0:16 offset1:20
	v_mul_hi_i32 v30, v0, s90
	v_mul_f32_e32 v60, 0x3e16c740, v60
	v_mul_f32_e32 v61, 0x3e16c740, v61
	v_lshrrev_b32_e32 v31, 31, v30
	v_ashrrev_i32_e32 v30, 7, v30
	v_cvt_pk_bf16_f32 v60, v60, v61
	v_mul_f32_e32 v58, 0x3e16c740, v58
	v_mul_f32_e32 v59, 0x3e16c740, v59
	v_cvt_pk_bf16_f32 v61, v58, v59
	ds_write2_b64 v62, v[64:65], v[60:61] offset1:4
	v_add_u32_e32 v30, v30, v31
	s_waitcnt lgkmcnt(0)
	v_mul_i32_i24_e32 v31, 0x810, v30
	v_sub_u32_e32 v0, v0, v31
	v_cmp_lt_i32_e64 s[0:1], 15, v0
	s_and_saveexec_b64 s[10:11], s[0:1]
	s_cbranch_execz .LBB0_508
	v_lshl_or_b32 v30, v30, 3, s16
	ds_read_b128 v[54:57], v167
	v_ashrrev_i32_e32 v31, 31, v30
	v_lshlrev_b64 v[30:31], 11, v[30:31]
	v_add_u32_e32 v0, -16, v0
	v_lshl_add_u64 v[30:31], v[30:31], 0, v[0:1]
	v_mad_u64_u32 v[32:33], s[0:1], v30, s91, v[118:119]
	v_mad_i32_i24 v33, v31, s91, v33
	s_waitcnt lgkmcnt(0)
	global_store_dwordx4 v[32:33], v[54:57], off

; __device__ __forceinline__ float frsq(float x) { return __builtin_amdgcn_rsqf(x); }
; __device__ __forceinline__ void qkv_head_unit(const Params& p, LAS unsigned char* lds, int h, int blk_begin, int blk_end) {
;     ...
;                 const float sc = frsq(ssv[mi] * (1.0f / 384.0f) + EPS);
;                 float ssq = 0.f;
; #pragma unroll
;                 for (int n = 0; n < 6; ++n) { acc[mi][n] *= sc; ssq += (acc[mi][n][0] * acc[mi][n][0] + acc[mi][n][1] * acc[mi][n][1]) + (acc[mi][n][2] * acc[mi][n][2] + acc[mi][n][3] * acc[mi][n][3]); }
;                 ssq += __shfl_xor(ssq, 16); ssq += __shfl_xor(ssq, 32);
.LBB0_512:
	s_or_b64 exec, exec, s[10:11]
	s_waitcnt lgkmcnt(0)
	v_fmamk_f32 v0, v125, 0x3b2aaaab, v140
	v_rsq_f32_e32 v0, v0
	s_nop 0
	v_pk_mul_f32 v[32:33], v[0:1], v[34:35] op_sel_hi:[0,1]
	v_pk_mul_f32 v[34:35], v[0:1], v[48:49] op_sel_hi:[0,1]
	v_pk_mul_f32 v[48:49], v[0:1], v[50:51] op_sel_hi:[0,1]
	v_mul_f32_e32 v50, v33, v33
	v_pk_mul_f32 v[30:31], v[0:1], v[36:37] op_sel_hi:[0,1]
	v_pk_mul_f32 v[36:37], v[0:1], v[46:47] op_sel_hi:[0,1]
	v_pk_mul_f32 v[46:47], v[0:1], v[52:53] op_sel_hi:[0,1]
	v_mul_f32_e32 v52, v48, v48
	v_pk_fma_f32 v[50:51], v[32:33], v[32:33], v[50:51] op_sel_hi:[1,1,0]
	v_mul_f32_e32 v54, v49, v49
	v_mov_b32_e32 v51, v52
	v_mul_f32_e32 v52, v31, v31
	v_pk_fma_f32 v[52:53], v[30:31], v[30:31], v[52:53] op_sel_hi:[1,1,0]
	v_mul_f32_e32 v55, v46, v46
	v_mov_b32_e32 v53, v54
	v_pk_add_f32 v[50:51], v[50:51], v[52:53]
	v_mul_f32_e32 v52, v37, v37
	v_pk_fma_f32 v[52:53], v[36:37], v[36:37], v[52:53] op_sel_hi:[1,1,0]
	v_mul_f32_e32 v54, v35, v35
	v_mul_f32_e32 v56, v47, v47
	v_mov_b32_e32 v53, v55
	v_pk_fma_f32 v[54:55], v[34:35], v[34:35], v[54:55] op_sel_hi:[1,1,0]
	v_pk_mul_f32 v[42:43], v[0:1], v[42:43] op_sel_hi:[0,1]
	v_mov_b32_e32 v55, v56
	v_pk_add_f32 v[52:53], v[52:53], v[54:55]
	v_pk_mul_f32 v[44:45], v[0:1], v[44:45] op_sel_hi:[0,1]
	v_pk_add_f32 v[50:51], v[50:51], v[52:53]
	v_pk_mul_f32 v[52:53], v[44:45], v[44:45]
	v_pk_mul_f32 v[54:55], v[42:43], v[42:43]
	v_pk_mul_f32 v[26:27], v[0:1], v[26:27] op_sel_hi:[0,1]
	v_pk_mov_b32 v[56:57], v[54:55], v[52:53] op_sel:[1,0]
	v_mov_b32_e32 v55, v53
	v_pk_add_f32 v[52:53], v[56:57], v[54:55]
	v_pk_mul_f32 v[40:41], v[0:1], v[40:41] op_sel_hi:[0,1]
	v_pk_mul_f32 v[38:39], v[0:1], v[38:39] op_sel_hi:[0,1]
	v_pk_mul_f32 v[28:29], v[0:1], v[28:29] op_sel_hi:[0,1]
	v_mul_f32_e32 v0, v26, v26
	v_mul_f32_e32 v54, v27, v27
	v_pk_add_f32 v[50:51], v[50:51], v[50:51] op_sel:[0,1] op_sel_hi:[1,0]
	v_pk_add_f32 v[52:53], v[52:53], v[52:53] op_sel:[0,1] op_sel_hi:[1,0]
	v_mov_b32_e32 v51, v0
	v_mov_b32_e32 v53, v54
	v_mul_f32_e32 v0, v39, v39
	v_mul_f32_e32 v55, v28, v28
	v_pk_add_f32 v[50:51], v[50:51], v[52:53]
	v_pk_fma_f32 v[52:53], v[38:39], v[38:39], v[0:1] op_sel_hi:[1,1,0]
	v_mul_f32_e32 v0, v41, v41
	v_mul_f32_e32 v56, v29, v29
	v_mov_b32_e32 v53, v55
	v_pk_fma_f32 v[54:55], v[40:41], v[40:41], v[0:1] op_sel_hi:[1,1,0]
	s_nop 0
	v_mov_b32_e32 v55, v56
	v_pk_add_f32 v[52:53], v[52:53], v[54:55]
	s_nop 0
	v_pk_add_f32 v[50:51], v[50:51], v[52:53]
	s_nop 0
	v_add_f32_e32 v0, v50, v51
	v_mov_b32_e32 v50, v0
	s_nop 1
	v_permlane16_swap_b32_e32 v0, v50
	s_waitcnt lgkmcnt(0)
	v_add_f32_e32 v0, v0, v50
	v_mov_b32_e32 v50, v0
	s_nop 1
	v_permlane32_swap_b32_e32 v0, v50
	s_waitcnt lgkmcnt(0)
; #define LAS __attribute__((address_space(3)))
; __device__ __forceinline__ unsigned cvt_pk(float lo, float hi) { unsigned r; asm("v_cvt_pk_bf16_f32 %0, %1, %2" : "=v"(r) : "v"(lo), "v"(hi)); return r; }
; __device__ __forceinline__ float frsq(float x) { return __builtin_amdgcn_rsqf(x); }
; __device__ __forceinline__ void qkv_head_unit(const Params& p, LAS unsigned char* lds, int h, int blk_begin, int blk_end) {
;     ...
;                 const float rq = frsq(ssq * (1.0f / 96.0f) + EPS);
; #pragma unroll
;                 for (int n = 0; n < 6; ++n) acc[mi][n] = acc[mi][n] * rq * gvv[n];
; #pragma unroll
;                 for (int i = 0; i < 4; ++i) { float sn, cs; sincos_rr((float)t * frq[i], sn, cs);
;                     const float x1 = acc[mi][4][i], x2 = acc[mi][5][i]; acc[mi][4][i] = x1 * cs - x2 * sn; acc[mi][5][i] = x1 * sn + x2 * cs; }
; #pragma unroll
;                 for (int n = 0; n < 6; ++n) { u32x2 wv; wv.x = cvt_pk(acc[mi][n][0] * QSCALE, acc[mi][n][1] * QSCALE); wv.y = cvt_pk(acc[mi][n][2] * QSCALE, acc[mi][n][3] * QSCALE); *(LAS u32x2*)(stg + fr * 104 + 16 * n + 4 * fq) = wv; }
;                 asm volatile("s_waitcnt lgkmcnt(0)" ::: "memory");
; #pragma unroll
;                 for (int j = 0; j < 3; ++j) { const int c = lane + 64 * j, rw = c / 12, cc = c % 12; const int row2 = 16 * (mi ? blk1 : pb) + rw, b2 = row2 / TT, t2 = row2 % TT;
;                     const u32x4 v = *(const LAS u32x4*)(stg + rw * 104 + 8 * cc);
;                     if (valid && t2 >= NMETA) *(u32x4*)(Q + (((size_t)(b2 * NH + h)) * SEQ + (t2 - NMETA)) * QKH + 8 * cc) = v; }
;                 asm volatile("s_waitcnt lgkmcnt(0)" ::: "memory"); __builtin_amdgcn_sched_barrier(0);
	v_add_f32_e32 v0, v0, v50
	v_mul_hi_i32 v50, v124, s90
	v_lshrrev_b32_e32 v51, 31, v50
	v_ashrrev_i32_e32 v50, 7, v50
	v_add_u32_e32 v50, v50, v51
	v_mul_lo_u32 v50, v50, s86
	v_fmamk_f32 v0, v0, 0x3c2aaaab, v140
	v_sub_u32_e32 v50, v124, v50
	v_rsq_f32_e32 v0, v0
	v_cvt_f32_i32_e32 v56, v50
	v_pk_mul_f32 v[32:33], v[32:33], v[0:1] op_sel_hi:[1,0]
	v_pk_mul_f32 v[30:31], v[30:31], v[0:1] op_sel_hi:[1,0]
	v_pk_mul_f32 v[36:37], v[36:37], v[0:1] op_sel_hi:[1,0]
	v_pk_mul_f32 v[34:35], v[34:35], v[0:1] op_sel_hi:[1,0]
	v_pk_mul_f32 v[48:49], v[48:49], v[0:1] op_sel_hi:[1,0]
	v_pk_mul_f32 v[46:47], v[46:47], v[0:1] op_sel_hi:[1,0]
	v_pk_mul_f32 v[42:43], v[42:43], v[0:1] op_sel_hi:[1,0]
	v_pk_mul_f32 v[44:45], v[44:45], v[0:1] op_sel_hi:[1,0]
	v_pk_mul_f32 v[38:39], v[38:39], v[0:1] op_sel_hi:[1,0]
	v_pk_mul_f32 v[40:41], v[40:41], v[0:1] op_sel_hi:[1,0]
	v_pk_mul_f32 v[26:27], v[26:27], v[0:1] op_sel_hi:[1,0]
	v_pk_mul_f32 v[28:29], v[28:29], v[0:1] op_sel_hi:[1,0]
	v_mul_f32_e32 v0, v154, v56
	v_mul_f32_e32 v50, 0.15915494, v0
	v_rndne_f32_e32 v50, v50
	v_fmac_f32_e32 v0, 0xc0c90fdb, v50
	v_fmac_f32_e32 v0, 0x343bbd2e, v50
	v_pk_mul_f32 v[26:27], v[22:23], v[26:27]
	v_pk_mul_f32 v[38:39], v[18:19], v[38:39]
	v_mul_f32_e32 v0, 0.15915494, v0
	v_mov_b32_e32 v53, v26
	v_mul_f32_e32 v26, v155, v56
	v_sin_f32_e32 v51, v0
	v_cos_f32_e32 v50, v0
	v_mov_b32_e32 v52, v38
	v_mul_f32_e32 v38, 0.15915494, v26
	v_rndne_f32_e32 v38, v38
	v_fmac_f32_e32 v26, 0xc0c90fdb, v38
	v_fmac_f32_e32 v26, 0x343bbd2e, v38
	v_pk_mul_f32 v[54:55], v[50:51], v[52:53]
	v_mul_f32_e32 v26, 0.15915494, v26
	v_sub_f32_e32 v0, v54, v55
	v_mov_b32_e32 v54, v51
	v_mov_b32_e32 v55, v50
	v_sin_f32_e32 v51, v26
	v_cos_f32_e32 v50, v26
	v_mov_b32_e32 v26, v39
	v_pk_mul_f32 v[52:53], v[54:55], v[52:53]
	v_pk_mul_f32 v[40:41], v[20:21], v[40:41]
	v_pk_mul_f32 v[38:39], v[50:51], v[26:27]
	v_add_f32_e32 v52, v52, v53
	v_sub_f32_e32 v53, v38, v39
	v_mov_b32_e32 v38, v51
	v_mov_b32_e32 v39, v50
	v_pk_mul_f32 v[26:27], v[38:39], v[26:27]
	v_mul_f32_e32 v38, v156, v56
	v_mul_f32_e32 v39, 0.15915494, v38
	v_rndne_f32_e32 v39, v39
	v_fmac_f32_e32 v38, 0xc0c90fdb, v39
	v_fmac_f32_e32 v38, 0x343bbd2e, v39
	v_mul_f32_e32 v38, 0.15915494, v38
	v_sin_f32_e32 v39, v38
	v_cos_f32_e32 v38, v38
	v_pk_mul_f32 v[28:29], v[24:25], v[28:29]
	v_add_f32_e32 v54, v26, v27
	v_mov_b32_e32 v26, v40
	v_mov_b32_e32 v27, v28
	v_pk_mul_f32 v[50:51], v[38:39], v[26:27]
	v_mul_f32_e32 v28, v157, v56
	v_sub_f32_e32 v40, v50, v51
	v_mov_b32_e32 v51, v38
	v_mul_f32_e32 v38, 0.15915494, v28
	v_rndne_f32_e32 v38, v38
	v_fmac_f32_e32 v28, 0xc0c90fdb, v38
	v_fmac_f32_e32 v28, 0x343bbd2e, v38
	v_mul_f32_e32 v28, 0.15915494, v28
	v_mov_b32_e32 v50, v39
	v_sin_f32_e32 v39, v28
	v_cos_f32_e32 v38, v28
	v_pk_mul_f32 v[26:27], v[50:51], v[26:27]
	v_mov_b32_e32 v28, v41
	v_add_f32_e32 v50, v26, v27
	v_pk_mul_f32 v[26:27], v[38:39], v[28:29]
	v_pk_mul_f32 v[32:33], v[2:3], v[32:33]
	v_sub_f32_e32 v41, v26, v27
	v_mov_b32_e32 v26, v39
	v_mov_b32_e32 v27, v38
	v_pk_mul_f32 v[26:27], v[26:27], v[28:29]
	v_pk_mul_f32 v[30:31], v[4:5], v[30:31]
	v_add_f32_e32 v38, v26, v27
	v_mul_f32_e32 v26, 0x3e16c740, v32
	v_mul_f32_e32 v27, 0x3e16c740, v33
	v_pk_mul_f32 v[36:37], v[6:7], v[36:37]
	v_cvt_pk_bf16_f32 v26, v26, v27
	v_mul_f32_e32 v27, 0x3e16c740, v30
	v_mul_f32_e32 v28, 0x3e16c740, v31
	v_pk_mul_f32 v[34:35], v[8:9], v[34:35]
	v_cvt_pk_bf16_f32 v27, v27, v28
	v_mul_f32_e32 v28, 0x3e16c740, v36
	v_mul_f32_e32 v29, 0x3e16c740, v37
	v_pk_mul_f32 v[48:49], v[10:11], v[48:49]
	v_cvt_pk_bf16_f32 v28, v28, v29
	v_mul_f32_e32 v29, 0x3e16c740, v34
	v_pk_mul_f32 v[46:47], v[12:13], v[46:47]
	v_mul_f32_e32 v30, 0x3e16c740, v35
	v_cvt_pk_bf16_f32 v29, v29, v30
	ds_write2_b64 v62, v[26:27], v[28:29] offset1:4
	v_mul_f32_e32 v26, 0x3e16c740, v48
	v_mul_f32_e32 v27, 0x3e16c740, v49
	v_pk_mul_f32 v[42:43], v[14:15], v[42:43]
	v_cvt_pk_bf16_f32 v26, v26, v27
	v_mul_f32_e32 v27, 0x3e16c740, v46
	v_mul_f32_e32 v28, 0x3e16c740, v47
	v_pk_mul_f32 v[44:45], v[16:17], v[44:45]
	v_cvt_pk_bf16_f32 v27, v27, v28
	v_mul_f32_e32 v28, 0x3e16c740, v42
	v_mul_f32_e32 v29, 0x3e16c740, v43
	v_cvt_pk_bf16_f32 v28, v28, v29
	v_mul_f32_e32 v29, 0x3e16c740, v44
	v_mul_f32_e32 v30, 0x3e16c740, v45
	v_cvt_pk_bf16_f32 v29, v29, v30
	ds_write2_b64 v62, v[26:27], v[28:29] offset0:8 offset1:12
	v_mul_f32_e32 v0, 0x3e16c740, v0
	v_mul_f32_e32 v26, 0x3e16c740, v53
	v_cvt_pk_bf16_f32 v26, v0, v26
	v_mul_f32_e32 v0, 0x3e16c740, v40
	v_mul_f32_e32 v27, 0x3e16c740, v41
	v_cvt_pk_bf16_f32 v27, v0, v27
	v_mul_f32_e32 v0, 0x3e16c740, v52
	v_mul_f32_e32 v28, 0x3e16c740, v54
	v_cvt_pk_bf16_f32 v28, v0, v28
	v_mul_f32_e32 v0, 0x3e16c740, v50
	v_mul_f32_e32 v29, 0x3e16c740, v38
	v_cvt_pk_bf16_f32 v29, v0, v29
	v_or_b32_e32 v0, v177, v166
	ds_write2_b64 v62, v[26:27], v[28:29] offset0:16 offset1:20
	v_mul_hi_i32 v26, v0, s90
	v_lshrrev_b32_e32 v27, 31, v26
	v_ashrrev_i32_e32 v26, 7, v26
	v_add_u32_e32 v26, v26, v27
	v_mul_i32_i24_e32 v27, 0x810, v26
	s_waitcnt lgkmcnt(0)
	v_sub_u32_e32 v0, v0, v27
	v_cmp_lt_i32_e64 s[0:1], 15, v0
	s_and_b64 s[10:11], s[2:3], s[0:1]
	s_and_saveexec_b64 s[0:1], s[10:11]
	s_cbranch_execz .LBB0_514
	v_lshl_or_b32 v26, v26, 3, s16
	ds_read_b128 v[28:31], v167
	v_ashrrev_i32_e32 v27, 31, v26
	v_lshlrev_b64 v[26:27], 11, v[26:27]
	v_add_u32_e32 v0, -16, v0
	v_lshl_add_u64 v[26:27], v[26:27], 0, v[0:1]
	v_mad_u64_u32 v[32:33], s[10:11], v26, s91, v[118:119]
	v_mad_i32_i24 v33, v27, s91, v33
	s_waitcnt lgkmcnt(0)
	global_store_dwordx4 v[32:33], v[28:31], off

; #define LAS __attribute__((address_space(3)))
; #define MFMA16(a, b, c) __builtin_amdgcn_mfma_f32_16x16x32_bf16((a), (b), (c), 0, 0, 0)
; __device__ __forceinline__ void qkv_head_unit(const Params& p, LAS unsigned char* lds, int h, int blk_begin, int blk_end) {
;     ...
;         for (int pb = blk_begin + 2 * w; pb < blk_end; pb += 16) {
;             const bool two = (pb + 1) < blk_end;
;             const int blk1 = two ? pb + 1 : pb;
;             const int rowm[2] = {16 * pb + fr, 16 * blk1 + fr};
;             bf16x8 af[2][8]; float ssv[2]; u32x2 k1v[2], k2v[2];
; #pragma unroll
;             for (int m = 0; m < 2; ++m) { ssv[m] = ss_ckv[rowm[m]]; k1v[m] = *(const u32x2*)(P + (size_t)rowm[m] * INP + C_KR + 4 * fq); k2v[m] = *(const u32x2*)(P + (size_t)rowm[m] * INP + C_KR + 16 + 4 * fq);
; #pragma unroll
;                 for (int ks = 0; ks < 8; ++ks) af[m][ks] = *(const bf16x8*)(P + (size_t)rowm[m] * INP + C_CKV + 32 * ks + 8 * fq); }
;             {
;                 f32x4 acc[2][4];
; #pragma unroll
;                 for (int m = 0; m < 2; ++m)
; #pragma unroll
;                     for (int n = 0; n < 4; ++n) acc[m][n] = (f32x4){0.f, 0.f, 0.f, 0.f};
; #pragma unroll
;                 for (int ks = 0; ks < 8; ++ks)
; #pragma unroll
;                     for (int n = 0; n < 4; ++n) { const bf16x8 bw = *(const LAS bf16x8*)(wl + (16 * n + fr) * WKS + 32 * ks + 8 * fq);
;                         acc[0][n] = MFMA16(bw, af[0][ks], acc[0][n]); acc[1][n] = MFMA16(bw, af[1][ks], acc[1][n]); }
.LBB0_524:
	v_add_u32_e32 v177, 1, v159
	v_cmp_gt_i32_e32 vcc, s12, v177
	v_add_u32_e32 v126, v158, v161
	v_ashrrev_i32_e32 v127, 31, v126
	v_cndmask_b32_e32 v0, v159, v177, vcc
	v_lshlrev_b32_e32 v178, 4, v0
	v_or_b32_e32 v120, v178, v158
	v_lshl_add_u64 v[22:23], v[126:127], 2, s[42:43]
	v_mov_b64_e32 v[26:27], s[40:41]
	global_load_dword v127, v[22:23], off
	v_mad_i64_i32 v[22:23], s[4:5], v126, s89, v[26:27]
	v_lshlrev_b32_e32 v0, 1, v115
	v_ashrrev_i32_e32 v121, 31, v120
	v_lshl_add_u64 v[24:25], v[22:23], 0, v[0:1]
	v_lshl_add_u64 v[34:35], v[120:121], 2, s[42:43]
	v_mad_i64_i32 v[22:23], s[4:5], v120, s89, v[26:27]
	global_load_dwordx2 v[130:131], v[24:25], off offset:1280
	global_load_dwordx2 v[128:129], v[24:25], off offset:1312
	global_load_dword v121, v[34:35], off
	v_lshl_add_u64 v[34:35], v[22:23], 0, v[0:1]
	v_and_b32_e32 v0, 3, v163
	v_bfe_u32 v226, v163, 2, 4
	global_load_dwordx2 v[124:125], v[34:35], off offset:1280
	global_load_dwordx2 v[122:123], v[34:35], off offset:1312
	v_lshlrev_b32_e32 v0, 4, v0
	v_and_b32_e32 v227, -16, v126
	v_lshl_add_u64 v[28:29], v[26:27], 0, v[0:1]
	v_add_u32_e32 v227, v227, v226
	v_add_u32_e32 v226, v178, v226
	v_mad_i64_i32 v[22:23], s[4:5], v227, s89, v[28:29]
	v_mad_i64_i32 v[26:27], s[4:5], v226, s89, v[28:29]
	global_load_dwordx4 v[78:81], v[22:23], off offset:768
	global_load_dwordx4 v[82:85], v[26:27], off offset:768
	global_load_dwordx4 v[66:69], v[22:23], off offset:832
	global_load_dwordx4 v[74:77], v[26:27], off offset:832
	global_load_dwordx4 v[62:65], v[22:23], off offset:896
	global_load_dwordx4 v[70:73], v[26:27], off offset:896
	global_load_dwordx4 v[50:53], v[22:23], off offset:960
	global_load_dwordx4 v[58:61], v[26:27], off offset:960
	global_load_dwordx4 v[46:49], v[22:23], off offset:1024
	global_load_dwordx4 v[54:57], v[26:27], off offset:1024
	global_load_dwordx4 v[38:41], v[22:23], off offset:1088
	global_load_dwordx4 v[42:45], v[26:27], off offset:1088
	global_load_dwordx4 v[30:33], v[22:23], off offset:1152
	global_load_dwordx4 v[34:37], v[26:27], off offset:1152
	s_nop 0
	global_load_dwordx4 v[22:25], v[22:23], off offset:1216
	global_load_dwordx4 v[26:29], v[26:27], off offset:1216
	s_waitcnt vmcnt(15)
	ds_write_b128 v242, v[78:81]
	ds_read_b128 v[78:81], v243
	s_waitcnt vmcnt(14)
	ds_write_b128 v242, v[82:85] offset:1024
	ds_read_b128 v[82:85], v243 offset:1024
	s_waitcnt vmcnt(13)
	ds_write_b128 v242, v[66:69] offset:2048
	ds_read_b128 v[66:69], v243 offset:2048
	s_waitcnt vmcnt(12)
	ds_write_b128 v242, v[74:77]
	ds_read_b128 v[74:77], v243
	ds_read_b128 v[230:233], v164 offset:0
	ds_read_b128 v[234:237], v164 offset:8448
	ds_read_b128 v[238:241], v164 offset:16896
	ds_read_b128 v[180:183], v164 offset:25344
	s_waitcnt lgkmcnt(3)
	v_mfma_f32_16x16x32_bf16 v[188:191], v[230:233], v[78:81], 0
	v_fmamk_f32 v0, v127, 0x3b800000, v140
	v_rsq_f32_e32 v0, v0
	v_mfma_f32_16x16x32_bf16 v[98:101], v[230:233], v[82:85], 0
	ds_read_b128 v[230:233], v164 offset:64
	s_waitcnt lgkmcnt(3)
	v_mfma_f32_16x16x32_bf16 v[192:195], v[234:237], v[78:81], 0
	v_mfma_f32_16x16x32_bf16 v[86:89], v[234:237], v[82:85], 0
	ds_read_b128 v[234:237], v164 offset:8512
	s_waitcnt vmcnt(11)
	ds_write_b128 v242, v[62:65] offset:1024
	ds_read_b128 v[62:65], v243 offset:1024
	s_waitcnt vmcnt(10)
	ds_write_b128 v242, v[70:73] offset:2048
	ds_read_b128 v[70:73], v243 offset:2048
	s_waitcnt lgkmcnt(7)
	v_mfma_f32_16x16x32_bf16 v[196:199], v[238:241], v[78:81], 0
	v_mfma_f32_16x16x32_bf16 v[94:97], v[238:241], v[82:85], 0
	ds_read_b128 v[238:241], v164 offset:16960
	s_waitcnt lgkmcnt(7)
	v_mfma_f32_16x16x32_bf16 v[184:187], v[180:183], v[78:81], 0
	v_mfma_f32_16x16x32_bf16 v[90:93], v[180:183], v[82:85], 0
	ds_read_b128 v[180:183], v164 offset:25408
	s_waitcnt lgkmcnt(7)
	v_mfma_f32_16x16x32_bf16 v[188:191], v[230:233], v[66:69], v[188:191]
	v_mfma_f32_16x16x32_bf16 v[98:101], v[230:233], v[74:77], v[98:101]
	ds_read_b128 v[230:233], v164 offset:128
	s_waitcnt lgkmcnt(7)
	v_mfma_f32_16x16x32_bf16 v[192:195], v[234:237], v[66:69], v[192:195]
	v_mfma_f32_16x16x32_bf16 v[86:89], v[234:237], v[74:77], v[86:89]
	ds_read_b128 v[234:237], v164 offset:8576
	s_waitcnt vmcnt(9)
	ds_write_b128 v242, v[50:53]
	ds_read_b128 v[50:53], v243
	s_waitcnt vmcnt(8)
	ds_write_b128 v242, v[58:61] offset:1024
	ds_read_b128 v[58:61], v243 offset:1024
	s_waitcnt lgkmcnt(7)
	v_mfma_f32_16x16x32_bf16 v[196:199], v[238:241], v[66:69], v[196:199]
	v_mfma_f32_16x16x32_bf16 v[94:97], v[238:241], v[74:77], v[94:97]
	ds_read_b128 v[238:241], v164 offset:17024
	s_waitcnt lgkmcnt(7)
	v_mfma_f32_16x16x32_bf16 v[184:187], v[180:183], v[66:69], v[184:187]
	v_mfma_f32_16x16x32_bf16 v[90:93], v[180:183], v[74:77], v[90:93]
	ds_read_b128 v[180:183], v164 offset:25472
	s_waitcnt lgkmcnt(7)
	v_mfma_f32_16x16x32_bf16 v[188:191], v[230:233], v[62:65], v[188:191]
	v_mfma_f32_16x16x32_bf16 v[98:101], v[230:233], v[70:73], v[98:101]
	ds_read_b128 v[230:233], v164 offset:192
	s_waitcnt lgkmcnt(7)
	v_mfma_f32_16x16x32_bf16 v[192:195], v[234:237], v[62:65], v[192:195]
	v_mfma_f32_16x16x32_bf16 v[86:89], v[234:237], v[70:73], v[86:89]
	ds_read_b128 v[234:237], v164 offset:8640
	s_waitcnt vmcnt(7)
	ds_write_b128 v242, v[46:49] offset:2048
	ds_read_b128 v[46:49], v243 offset:2048
	s_waitcnt vmcnt(6)
	ds_write_b128 v242, v[54:57]
	ds_read_b128 v[54:57], v243
	s_waitcnt lgkmcnt(7)
	v_mfma_f32_16x16x32_bf16 v[196:199], v[238:241], v[62:65], v[196:199]
	v_mfma_f32_16x16x32_bf16 v[94:97], v[238:241], v[70:73], v[94:97]
	ds_read_b128 v[238:241], v164 offset:17088
	s_waitcnt lgkmcnt(7)
; #define LAS __attribute__((address_space(3)))
; #define MFMA16(a, b, c) __builtin_amdgcn_mfma_f32_16x16x32_bf16((a), (b), (c), 0, 0, 0)
; __device__ __forceinline__ void qkv_head_unit(const Params& p, LAS unsigned char* lds, int h, int blk_begin, int blk_end) {
;     ...
; #pragma unroll
;                 for (int ks = 0; ks < 8; ++ks)
; #pragma unroll
;                     for (int n = 0; n < 4; ++n) { const bf16x8 bw = *(const LAS bf16x8*)(wl + (16 * n + fr) * WKS + 32 * ks + 8 * fq);
;                         acc[0][n] = MFMA16(bw, af[0][ks], acc[0][n]); acc[1][n] = MFMA16(bw, af[1][ks], acc[1][n]); }
	v_mfma_f32_16x16x32_bf16 v[184:187], v[180:183], v[62:65], v[184:187]
	v_mfma_f32_16x16x32_bf16 v[90:93], v[180:183], v[70:73], v[90:93]
	ds_read_b128 v[180:183], v164 offset:25536
	s_waitcnt lgkmcnt(7)
	v_mfma_f32_16x16x32_bf16 v[188:191], v[230:233], v[50:53], v[188:191]
	v_mfma_f32_16x16x32_bf16 v[98:101], v[230:233], v[58:61], v[98:101]
	ds_read_b128 v[230:233], v164 offset:256
	s_waitcnt lgkmcnt(7)
	v_mfma_f32_16x16x32_bf16 v[192:195], v[234:237], v[50:53], v[192:195]
	v_mfma_f32_16x16x32_bf16 v[86:89], v[234:237], v[58:61], v[86:89]
	ds_read_b128 v[234:237], v164 offset:8704
	s_waitcnt vmcnt(5)
	ds_write_b128 v242, v[38:41] offset:1024
	ds_read_b128 v[38:41], v243 offset:1024
	s_waitcnt vmcnt(4)
	ds_write_b128 v242, v[42:45] offset:2048
	ds_read_b128 v[42:45], v243 offset:2048
	s_waitcnt lgkmcnt(7)
	v_mfma_f32_16x16x32_bf16 v[196:199], v[238:241], v[50:53], v[196:199]
	v_mfma_f32_16x16x32_bf16 v[94:97], v[238:241], v[58:61], v[94:97]
	ds_read_b128 v[238:241], v164 offset:17152
	s_waitcnt lgkmcnt(7)
	v_mfma_f32_16x16x32_bf16 v[184:187], v[180:183], v[50:53], v[184:187]
	v_mfma_f32_16x16x32_bf16 v[90:93], v[180:183], v[58:61], v[90:93]
	ds_read_b128 v[180:183], v164 offset:25600
	s_waitcnt lgkmcnt(7)
	v_mfma_f32_16x16x32_bf16 v[188:191], v[230:233], v[46:49], v[188:191]
	v_mfma_f32_16x16x32_bf16 v[98:101], v[230:233], v[54:57], v[98:101]
	ds_read_b128 v[230:233], v164 offset:320
	s_waitcnt lgkmcnt(7)
	v_mfma_f32_16x16x32_bf16 v[192:195], v[234:237], v[46:49], v[192:195]
	v_mfma_f32_16x16x32_bf16 v[86:89], v[234:237], v[54:57], v[86:89]
	ds_read_b128 v[234:237], v164 offset:8768
	s_waitcnt vmcnt(3)
	ds_write_b128 v242, v[30:33]
	ds_read_b128 v[30:33], v243
	s_waitcnt vmcnt(2)
	ds_write_b128 v242, v[34:37] offset:1024
	ds_read_b128 v[34:37], v243 offset:1024
	s_waitcnt lgkmcnt(7)
	v_mfma_f32_16x16x32_bf16 v[196:199], v[238:241], v[46:49], v[196:199]
	v_mfma_f32_16x16x32_bf16 v[94:97], v[238:241], v[54:57], v[94:97]
	ds_read_b128 v[238:241], v164 offset:17216
	s_waitcnt lgkmcnt(7)
	v_mfma_f32_16x16x32_bf16 v[184:187], v[180:183], v[46:49], v[184:187]
	v_mfma_f32_16x16x32_bf16 v[90:93], v[180:183], v[54:57], v[90:93]
	ds_read_b128 v[180:183], v164 offset:25664
	s_waitcnt lgkmcnt(7)
	v_mfma_f32_16x16x32_bf16 v[188:191], v[230:233], v[38:41], v[188:191]
	v_mfma_f32_16x16x32_bf16 v[98:101], v[230:233], v[42:45], v[98:101]
	ds_read_b128 v[230:233], v164 offset:384
	s_waitcnt lgkmcnt(7)
	v_mfma_f32_16x16x32_bf16 v[192:195], v[234:237], v[38:41], v[192:195]
	v_mfma_f32_16x16x32_bf16 v[86:89], v[234:237], v[42:45], v[86:89]
	ds_read_b128 v[234:237], v164 offset:8832
	s_waitcnt vmcnt(1)
	ds_write_b128 v242, v[22:25] offset:2048
	ds_read_b128 v[22:25], v243 offset:2048
	s_waitcnt vmcnt(0)
	ds_write_b128 v242, v[26:29]
	ds_read_b128 v[26:29], v243
	s_waitcnt lgkmcnt(7)
	v_mfma_f32_16x16x32_bf16 v[196:199], v[238:241], v[38:41], v[196:199]
	v_mfma_f32_16x16x32_bf16 v[94:97], v[238:241], v[42:45], v[94:97]
	ds_read_b128 v[238:241], v164 offset:17280
	s_waitcnt lgkmcnt(7)
	v_mfma_f32_16x16x32_bf16 v[184:187], v[180:183], v[38:41], v[184:187]
	v_mfma_f32_16x16x32_bf16 v[90:93], v[180:183], v[42:45], v[90:93]
	ds_read_b128 v[180:183], v164 offset:25728
	s_waitcnt lgkmcnt(7)
	v_mfma_f32_16x16x32_bf16 v[188:191], v[230:233], v[30:33], v[188:191]
	v_mfma_f32_16x16x32_bf16 v[98:101], v[230:233], v[34:37], v[98:101]
	ds_read_b128 v[230:233], v164 offset:448
	s_waitcnt lgkmcnt(7)
	v_mfma_f32_16x16x32_bf16 v[192:195], v[234:237], v[30:33], v[192:195]
	v_mfma_f32_16x16x32_bf16 v[86:89], v[234:237], v[34:37], v[86:89]
	ds_read_b128 v[234:237], v164 offset:8896
	s_waitcnt lgkmcnt(3)
	v_mfma_f32_16x16x32_bf16 v[196:199], v[238:241], v[30:33], v[196:199]
	v_mfma_f32_16x16x32_bf16 v[94:97], v[238:241], v[34:37], v[94:97]
	ds_read_b128 v[238:241], v164 offset:17344
	s_waitcnt lgkmcnt(3)
	v_mfma_f32_16x16x32_bf16 v[184:187], v[180:183], v[30:33], v[184:187]
	v_mfma_f32_16x16x32_bf16 v[90:93], v[180:183], v[34:37], v[90:93]
	ds_read_b128 v[180:183], v164 offset:25792
	s_waitcnt lgkmcnt(3)
	v_mfma_f32_16x16x32_bf16 v[188:191], v[230:233], v[22:25], v[188:191]
	v_mfma_f32_16x16x32_bf16 v[98:101], v[230:233], v[26:29], v[98:101]
	s_waitcnt lgkmcnt(2)
	v_mfma_f32_16x16x32_bf16 v[192:195], v[234:237], v[22:25], v[192:195]
	v_mfma_f32_16x16x32_bf16 v[86:89], v[234:237], v[26:29], v[86:89]
	s_waitcnt lgkmcnt(1)
	v_mfma_f32_16x16x32_bf16 v[196:199], v[238:241], v[22:25], v[196:199]
	v_mfma_f32_16x16x32_bf16 v[94:97], v[238:241], v[26:29], v[94:97]
	s_waitcnt lgkmcnt(0)
; #define LAS __attribute__((address_space(3)))
; __device__ __forceinline__ unsigned cvt_pk(float lo, float hi) { unsigned r; asm("v_cvt_pk_bf16_f32 %0, %1, %2" : "=v"(r) : "v"(lo), "v"(hi)); return r; }
; __device__ __forceinline__ float bflo(unsigned w) { return __uint_as_float(w << 16); }
; __device__ __forceinline__ float bfhi(unsigned w) { return __uint_as_float(w & 0xffff0000u); }
; __device__ __forceinline__ float frsq(float x) { return __builtin_amdgcn_rsqf(x); }
; __device__ __forceinline__ void qkv_head_unit(const Params& p, LAS unsigned char* lds, int h, int blk_begin, int blk_end) {
;     ...
;                 for (int mi = 0; mi < 2; ++mi) {
;                     const bool valid = (mi == 0) || two;
;                     const int t = rowm[mi] % TT;
;                     const float sc = frsq(ssv[mi] * (1.0f / 256.0f) + EPS);
;                     const u32x2 k1 = k1v[mi], k2 = k2v[mi];
;                     f32x4 kr1 = (f32x4){bflo(k1.x), bfhi(k1.x), bflo(k1.y), bfhi(k1.y)}, kr2 = (f32x4){bflo(k2.x), bfhi(k2.x), bflo(k2.y), bfhi(k2.y)};
;                     float ssq = (kr1[0] * kr1[0] + kr1[1] * kr1[1]) + (kr1[2] * kr1[2] + kr1[3] * kr1[3]) + (kr2[0] * kr2[0] + kr2[1] * kr2[1]) + (kr2[2] * kr2[2] + kr2[3] * kr2[3]);
; #pragma unroll
;                     for (int n = 0; n < 4; ++n) { acc[mi][n] *= sc; ssq += (acc[mi][n][0] * acc[mi][n][0] + acc[mi][n][1] * acc[mi][n][1]) + (acc[mi][n][2] * acc[mi][n][2] + acc[mi][n][3] * acc[mi][n][3]); }
;                     ssq += __shfl_xor(ssq, 16); ssq += __shfl_xor(ssq, 32);
;                     const float rk = frsq(ssq * (1.0f / 96.0f) + EPS);
;                     LAS bf16_t* dstk = stg + fr * 104 + 4 * fq;
; #pragma unroll
;                     for (int n = 0; n < 4; ++n) { const f32x4 v = acc[mi][n] * rk * gvv[n]; u32x2 wv; wv.x = cvt_pk(v[0], v[1]); wv.y = cvt_pk(v[2], v[3]); *(LAS u32x2*)(dstk + 16 * n) = wv; }
;                     { kr1 = kr1 * rk * gvv[4]; kr2 = kr2 * rk * gvv[5];
	v_mfma_f32_16x16x32_bf16 v[184:187], v[180:183], v[22:25], v[184:187]
	v_mfma_f32_16x16x32_bf16 v[90:93], v[180:183], v[26:29], v[90:93]
	v_lshlrev_b32_e32 v137, 16, v131
	v_lshlrev_b32_e32 v136, 16, v130
	v_and_b32_e32 v131, 0xffff0000, v131
	v_and_b32_e32 v130, 0xffff0000, v130
	v_pk_mul_f32 v[138:139], v[130:131], v[130:131]
	v_lshlrev_b32_e32 v132, 16, v129
	v_and_b32_e32 v134, 0xffff0000, v129
	s_nop 7
	v_pk_mul_f32 v[196:197], v[0:1], v[196:197] op_sel_hi:[0,1]
	v_mul_f32_e64 v184, v0, v184
	v_mul_f32_e64 v185, v0, v185
	v_pk_mul_f32 v[186:187], v[0:1], v[186:187] op_sel_hi:[0,1]
	v_pk_fma_f32 v[180:181], v[136:137], v[136:137], v[138:139]
	v_and_b32_e32 v139, 0xffff0000, v128
	v_lshlrev_b32_e32 v138, 16, v128
	v_pk_mul_f32 v[128:129], v[0:1], v[190:191] op_sel_hi:[0,1]
	v_pk_mul_f32 v[182:183], v[0:1], v[188:189] op_sel_hi:[0,1]
	v_mul_f32_e32 v190, v139, v139
	v_mul_f32_e32 v127, v128, v128
	v_mul_f32_e32 v179, v129, v129
	v_mov_b32_e32 v135, v183
	v_pk_add_f32 v[180:181], v[180:181], v[180:181] op_sel:[0,1] op_sel_hi:[1,0]
	v_pk_fma_f32 v[190:191], v[138:139], v[138:139], v[190:191] op_sel_hi:[1,1,0]
	v_mov_b32_e32 v133, v182
	v_pk_mul_f32 v[188:189], v[134:135], v[134:135]
	v_mov_b32_e32 v181, v127
	v_mov_b32_e32 v191, v179
	v_pk_fma_f32 v[188:189], v[132:133], v[132:133], v[188:189]
	v_pk_add_f32 v[180:181], v[180:181], v[190:191]
	v_pk_mul_f32 v[190:191], v[0:1], v[192:193] op_sel_hi:[0,1]
	v_pk_add_f32 v[180:181], v[188:189], v[180:181]
	v_pk_mul_f32 v[188:189], v[0:1], v[194:195] op_sel_hi:[0,1]
	v_pk_mul_f32 v[192:193], v[188:189], v[188:189]
	v_pk_mul_f32 v[194:195], v[190:191], v[190:191]
	v_mul_f32_e32 v127, v184, v184
	v_pk_mov_b32 v[200:201], v[194:195], v[192:193] op_sel:[1,0]
	v_mov_b32_e32 v195, v193
	v_pk_add_f32 v[192:193], v[200:201], v[194:195]
	v_mul_f32_e32 v133, v185, v185
	v_pk_add_f32 v[180:181], v[180:181], v[180:181] op_sel:[0,1] op_sel_hi:[1,0]
	v_pk_add_f32 v[192:193], v[192:193], v[192:193] op_sel:[0,1] op_sel_hi:[1,0]
	v_pk_mul_f32 v[194:195], v[0:1], v[198:199] op_sel_hi:[0,1]
	v_mov_b32_e32 v181, v127
	v_mov_b32_e32 v193, v133
	v_pk_add_f32 v[180:181], v[180:181], v[192:193]
	v_mul_f32_e32 v192, v197, v197
	v_mul_f32_e32 v198, v195, v195
	v_mul_f32_e32 v135, v186, v186
	v_mul_f32_e32 v179, v187, v187
	v_pk_fma_f32 v[192:193], v[196:197], v[196:197], v[192:193] op_sel_hi:[1,1,0]
	v_pk_fma_f32 v[198:199], v[194:195], v[194:195], v[198:199] op_sel_hi:[1,1,0]
	v_mov_b32_e32 v193, v135
	v_mov_b32_e32 v199, v179
	v_pk_add_f32 v[192:193], v[192:193], v[198:199]
	s_nop 0
	v_pk_add_f32 v[180:181], v[180:181], v[192:193]
	s_nop 0
	v_add_f32_e32 v127, v180, v181
	v_mov_b32_e32 v133, v127
	s_nop 1
	v_permlane16_swap_b32_e32 v127, v133
	s_waitcnt lgkmcnt(0)
	v_add_f32_e32 v127, v127, v133
	v_mov_b32_e32 v133, v127
	s_nop 1
	v_permlane32_swap_b32_e32 v127, v133
	s_waitcnt lgkmcnt(0)
	v_add_f32_e32 v127, v127, v133
	v_fmamk_f32 v127, v127, 0x3c2aaaab, v140
	v_rsq_f32_e32 v180, v127
	v_add_u32_e32 v127, v160, v114
	v_mov_b32_e32 v133, v134
	v_pk_mul_f32 v[182:183], v[182:183], v[180:181] op_sel_hi:[1,0]
	v_pk_mul_f32 v[128:129], v[128:129], v[180:181] op_sel_hi:[1,0]
	v_pk_mul_f32 v[182:183], v[6:7], v[182:183]
	v_pk_mul_f32 v[128:129], v[8:9], v[128:129]
	v_cvt_pk_bf16_f32 v182, v182, v183
	v_pk_mul_f32 v[188:189], v[188:189], v[180:181] op_sel_hi:[1,0]
	v_cvt_pk_bf16_f32 v183, v128, v129
	v_pk_mul_f32 v[128:129], v[190:191], v[180:181] op_sel_hi:[1,0]
	v_pk_mul_f32 v[188:189], v[12:13], v[188:189]
	v_pk_mul_f32 v[128:129], v[10:11], v[128:129]
	v_pk_mul_f32 v[134:135], v[138:139], v[180:181] op_sel_hi:[1,0]
	v_cvt_pk_bf16_f32 v128, v128, v129
	v_cvt_pk_bf16_f32 v129, v188, v189
	ds_write2_b64 v127, v[182:183], v[128:129] offset1:4
	v_pk_mul_f32 v[128:129], v[196:197], v[180:181] op_sel_hi:[1,0]
	v_pk_mul_f32 v[182:183], v[194:195], v[180:181] op_sel_hi:[1,0]
	v_pk_mul_f32 v[128:129], v[14:15], v[128:129]
	v_pk_mul_f32 v[182:183], v[16:17], v[182:183]
	v_cvt_pk_bf16_f32 v128, v128, v129
	v_mov_b32_e32 v139, v134
	v_cvt_pk_bf16_f32 v129, v182, v183
	v_pk_mul_f32 v[182:183], v[184:185], v[180:181] op_sel_hi:[1,0]
	v_pk_mul_f32 v[184:185], v[186:187], v[180:181] op_sel_hi:[1,0]
	v_pk_mul_f32 v[182:183], v[18:19], v[182:183]
	v_pk_mul_f32 v[184:185], v[20:21], v[184:185]
	v_cvt_pk_bf16_f32 v182, v182, v183
	v_pk_mul_f32 v[132:133], v[132:133], v[180:181] op_sel_hi:[1,0]
	v_cvt_pk_bf16_f32 v183, v184, v185
	ds_write2_b64 v127, v[128:129], v[182:183] offset0:8 offset1:12
	v_mul_hi_i32 v128, v126, s90
	v_lshrrev_b32_e32 v129, 31, v128
	v_ashrrev_i32_e32 v128, 7, v128
	v_add_u32_e32 v128, v128, v129
	v_mul_lo_u32 v128, v128, s86
	v_sub_u32_e32 v126, v126, v128
	v_cvt_f32_i32_e32 v126, v126
	v_mov_b32_e32 v128, v137
	v_mov_b32_e32 v137, v130
	v_mov_b32_e32 v129, v131
	v_pk_mul_f32 v[130:131], v[180:181], v[136:137] op_sel_hi:[0,1]
	v_mul_f32_e32 v136, v154, v126
	v_mul_f32_e32 v137, 0.15915494, v136
	v_rndne_f32_e32 v137, v137
	v_fmac_f32_e32 v136, 0xc0c90fdb, v137
	v_fmac_f32_e32 v136, 0x343bbd2e, v137
	v_mul_f32_e32 v136, 0.15915494, v136
	v_sin_f32_e32 v137, v136
	v_cos_f32_e32 v136, v136
	v_mov_b32_e32 v138, v130
	v_mul_f32_e32 v130, v155, v126
	v_mul_f32_e32 v134, 0.15915494, v130
	v_pk_mul_f32 v[138:139], v[118:119], v[138:139]
	v_rndne_f32_e32 v134, v134
	v_pk_mul_f32 v[128:129], v[180:181], v[128:129] op_sel_hi:[0,1]
	v_pk_mul_f32 v[180:181], v[136:137], v[138:139]
	v_fmac_f32_e32 v130, 0xc0c90fdb, v134
	v_sub_f32_e32 v179, v180, v181
	v_mov_b32_e32 v180, v137
	v_mov_b32_e32 v181, v136
	v_fmac_f32_e32 v130, 0x343bbd2e, v134
	v_pk_mul_f32 v[136:137], v[180:181], v[138:139]
	v_mul_f32_e32 v130, 0.15915494, v130
; #define LAS __attribute__((address_space(3)))
; __device__ __forceinline__ unsigned cvt_pk(float lo, float hi) { unsigned r; asm("v_cvt_pk_bf16_f32 %0, %1, %2" : "=v"(r) : "v"(lo), "v"(hi)); return r; }
; __device__ __forceinline__ void qkv_head_unit(const Params& p, LAS unsigned char* lds, int h, int blk_begin, int blk_end) {
;     ...
;                 for (int mi = 0; mi < 2; ++mi) {
;                     const bool valid = (mi == 0) || two;
;                     const int t = rowm[mi] % TT;
;                     const float sc = frsq(ssv[mi] * (1.0f / 256.0f) + EPS);
;                     const u32x2 k1 = k1v[mi], k2 = k2v[mi];
;                     f32x4 kr1 = (f32x4){bflo(k1.x), bfhi(k1.x), bflo(k1.y), bfhi(k1.y)}, kr2 = (f32x4){bflo(k2.x), bfhi(k2.x), bflo(k2.y), bfhi(k2.y)};
;                     float ssq = (kr1[0] * kr1[0] + kr1[1] * kr1[1]) + (kr1[2] * kr1[2] + kr1[3] * kr1[3]) + (kr2[0] * kr2[0] + kr2[1] * kr2[1]) + (kr2[2] * kr2[2] + kr2[3] * kr2[3]);
; #pragma unroll
;                     for (int n = 0; n < 4; ++n) { acc[mi][n] *= sc; ssq += (acc[mi][n][0] * acc[mi][n][0] + acc[mi][n][1] * acc[mi][n][1]) + (acc[mi][n][2] * acc[mi][n][2] + acc[mi][n][3] * acc[mi][n][3]); }
;                     ssq += __shfl_xor(ssq, 16); ssq += __shfl_xor(ssq, 32);
;     ...
;                     { kr1 = kr1 * rk * gvv[4]; kr2 = kr2 * rk * gvv[5];
;                       f32x4 o1, o2;
; #pragma unroll
;                       for (int i = 0; i < 4; ++i) { float sn, cs; sincos_rr((float)t * frq[i], sn, cs);
;                           o1[i] = kr1[i] * cs - kr2[i] * sn; o2[i] = kr1[i] * sn + kr2[i] * cs; }
;                       u32x2 wv; wv.x = cvt_pk(o1[0], o1[1]); wv.y = cvt_pk(o1[2], o1[3]); *(LAS u32x2*)(dstk + 64) = wv; wv.x = cvt_pk(o2[0], o2[1]); wv.y = cvt_pk(o2[2], o2[3]); *(LAS u32x2*)(dstk + 80) = wv; }
;                     asm volatile("s_waitcnt lgkmcnt(0)" ::: "memory");
; #pragma unroll
;                     for (int j = 0; j < 3; ++j) { const int c = lane + 64 * j, rw = c / 12, cc = c % 12; const int row2 = 16 * (mi ? blk1 : pb) + rw, b2 = row2 / TT, t2 = row2 % TT;
;                         const u32x4 v = *(const LAS u32x4*)(stg + rw * 104 + 8 * cc);
;                         if (valid) __builtin_nontemporal_store(v, (u32x4*)(Kb + (((size_t)(b2 * NH + h)) * TKP + t2) * QKH + 8 * cc)); }
	v_add_f32_e32 v138, v136, v137
	v_sin_f32_e32 v137, v130
	v_cos_f32_e32 v136, v130
	v_mov_b32_e32 v134, v131
	v_pk_mul_f32 v[130:131], v[2:3], v[134:135]
	s_nop 0
	v_pk_mul_f32 v[134:135], v[136:137], v[130:131]
	s_nop 0
	v_sub_f32_e32 v139, v134, v135
	v_mov_b32_e32 v134, v137
	v_mov_b32_e32 v135, v136
	v_pk_mul_f32 v[130:131], v[134:135], v[130:131]
	v_mov_b32_e32 v134, v128
	v_add_f32_e32 v180, v130, v131
	v_mul_f32_e32 v130, v156, v126
	v_mul_f32_e32 v131, 0.15915494, v130
	v_rndne_f32_e32 v131, v131
	v_fmac_f32_e32 v130, 0xc0c90fdb, v131
	v_fmac_f32_e32 v130, 0x343bbd2e, v131
	v_mul_f32_e32 v130, 0.15915494, v130
	v_sin_f32_e32 v131, v130
	v_cos_f32_e32 v130, v130
	v_mul_f32_e32 v126, v157, v126
	v_mov_b32_e32 v135, v132
	v_mul_f32_e32 v128, 0.15915494, v126
	v_pk_mul_f32 v[134:135], v[116:117], v[134:135]
	v_rndne_f32_e32 v128, v128
	v_pk_mul_f32 v[136:137], v[130:131], v[134:135]
	v_fmac_f32_e32 v126, 0xc0c90fdb, v128
	v_sub_f32_e32 v181, v136, v137
	v_mov_b32_e32 v136, v131
	v_mov_b32_e32 v137, v130
	v_fmac_f32_e32 v126, 0x343bbd2e, v128
	v_pk_mul_f32 v[130:131], v[136:137], v[134:135]
	v_mul_f32_e32 v126, 0.15915494, v126
	v_add_f32_e32 v134, v130, v131
	v_sin_f32_e32 v131, v126
	v_cos_f32_e32 v130, v126
	v_mov_b32_e32 v132, v129
	v_pk_mul_f32 v[128:129], v[4:5], v[132:133]
	s_nop 0
	v_pk_mul_f32 v[132:133], v[130:131], v[128:129]
	s_nop 0
	v_sub_f32_e32 v126, v132, v133
	v_mov_b32_e32 v132, v131
	v_mov_b32_e32 v133, v130
	v_pk_mul_f32 v[128:129], v[132:133], v[128:129]
	v_cvt_pk_bf16_f32 v130, v138, v180
	s_nop 0
	v_add_f32_e32 v131, v128, v129
	v_cvt_pk_bf16_f32 v129, v181, v126
	v_add_u32_e32 v126, v107, v161
	v_mul_hi_i32 v132, v126, s90
	v_lshrrev_b32_e32 v133, 31, v132
	v_ashrrev_i32_e32 v132, 7, v132
	v_add_u32_e32 v133, v132, v133
	v_mul_i32_i24_e32 v132, 0x810, v133
	v_sub_u32_e32 v132, v126, v132
	v_lshl_or_b32 v126, v133, 3, s16
	v_cvt_pk_bf16_f32 v131, v134, v131
	v_mul_hi_i32_i24_e32 v135, 0x840, v126
	v_mul_i32_i24_e32 v134, 0x840, v126
	v_ashrrev_i32_e32 v133, 31, v132
	v_lshl_add_u64 v[132:133], v[134:135], 0, v[132:133]
	v_mad_u64_u32 v[134:135], s[4:5], v132, s91, v[108:109]
	v_cvt_pk_bf16_f32 v128, v179, v139
	ds_write2_b64 v127, v[128:129], v[130:131] offset0:16 offset1:20
	v_mov_b32_e32 v126, v135
	s_waitcnt lgkmcnt(0)
	v_mad_u64_u32 v[132:133], s[4:5], v133, s91, v[126:127]
	v_add_u32_e32 v126, v170, v161
	ds_read_b128 v[128:131], v173
	v_mov_b32_e32 v135, v132
	v_mul_hi_i32 v132, v126, s90
	v_lshrrev_b32_e32 v133, 31, v132
	v_ashrrev_i32_e32 v132, 7, v132
	v_add_u32_e32 v133, v132, v133
	v_mul_i32_i24_e32 v132, 0x810, v133
	v_sub_u32_e32 v132, v126, v132
	v_lshl_or_b32 v126, v133, 3, s16
	s_waitcnt lgkmcnt(0)
	global_store_dwordx4 v[134:135], v[128:131], off nt
	v_mul_hi_i32_i24_e32 v135, 0x840, v126
	v_mul_i32_i24_e32 v134, 0x840, v126
	v_ashrrev_i32_e32 v133, 31, v132
	v_lshl_add_u64 v[132:133], v[134:135], 0, v[132:133]
	v_mad_u64_u32 v[134:135], s[4:5], v132, s91, v[110:111]
	v_mov_b32_e32 v126, v135
	v_mad_u64_u32 v[132:133], s[4:5], v133, s91, v[126:127]
	v_add_u32_e32 v126, v171, v161
	ds_read_b128 v[128:131], v174
	v_mov_b32_e32 v135, v132
	v_mul_hi_i32 v132, v126, s90
	v_lshrrev_b32_e32 v133, 31, v132
	v_ashrrev_i32_e32 v132, 7, v132
	v_add_u32_e32 v133, v132, v133
	v_mul_i32_i24_e32 v132, 0x810, v133
	v_sub_u32_e32 v132, v126, v132
	v_lshl_or_b32 v126, v133, 3, s16
	s_waitcnt lgkmcnt(0)
	global_store_dwordx4 v[134:135], v[128:131], off nt
	v_mul_hi_i32_i24_e32 v135, 0x840, v126
	v_mul_i32_i24_e32 v134, 0x840, v126
	v_ashrrev_i32_e32 v133, 31, v132
	ds_read_b128 v[128:131], v175
	v_lshl_add_u64 v[132:133], v[134:135], 0, v[132:133]
	v_mad_u64_u32 v[134:135], s[4:5], v132, s91, v[112:113]
	v_mov_b32_e32 v126, v135
	v_mad_u64_u32 v[132:133], s[4:5], v133, s91, v[126:127]
	v_mov_b32_e32 v135, v132
	s_waitcnt lgkmcnt(0)
	global_store_dwordx4 v[134:135], v[128:131], off nt
	s_waitcnt lgkmcnt(0)
	v_fmamk_f32 v121, v121, 0x3b800000, v140
	v_rsq_f32_e32 v126, v121
	v_lshlrev_b32_e32 v133, 16, v125
	v_lshlrev_b32_e32 v132, 16, v124
	v_and_b32_e32 v125, 0xffff0000, v125
	v_and_b32_e32 v124, 0xffff0000, v124
	v_pk_mul_f32 v[134:135], v[124:125], v[124:125]
	v_and_b32_e32 v137, 0xffff0000, v122
	v_pk_fma_f32 v[134:135], v[132:133], v[132:133], v[134:135]
	v_lshlrev_b32_e32 v136, 16, v122
	v_pk_mul_f32 v[98:99], v[126:127], v[98:99] op_sel_hi:[0,1]
	v_pk_mul_f32 v[100:101], v[126:127], v[100:101] op_sel_hi:[0,1]
	v_mul_f32_e32 v138, v137, v137
	v_and_b32_e32 v130, 0xffff0000, v123
	v_mul_f32_e32 v121, v100, v100
	v_mul_f32_e32 v179, v101, v101
	v_mov_b32_e32 v131, v99
	v_pk_add_f32 v[134:135], v[134:135], v[134:135] op_sel:[0,1] op_sel_hi:[1,0]
	v_pk_fma_f32 v[138:139], v[136:137], v[136:137], v[138:139] op_sel_hi:[1,1,0]
	v_lshlrev_b32_e32 v128, 16, v123
	v_mov_b32_e32 v129, v98
	v_pk_mul_f32 v[122:123], v[130:131], v[130:131]
	v_mov_b32_e32 v135, v121
	v_mov_b32_e32 v139, v179
	v_pk_fma_f32 v[122:123], v[128:129], v[128:129], v[122:123]
	v_pk_add_f32 v[134:135], v[134:135], v[138:139]
	v_pk_mul_f32 v[88:89], v[126:127], v[88:89] op_sel_hi:[0,1]
	v_pk_mul_f32 v[86:87], v[126:127], v[86:87] op_sel_hi:[0,1]
	v_pk_add_f32 v[122:123], v[122:123], v[134:135]
	v_pk_mul_f32 v[134:135], v[86:87], v[86:87]
	v_pk_mul_f32 v[138:139], v[88:89], v[88:89]
	v_pk_mul_f32 v[90:91], v[126:127], v[90:91] op_sel_hi:[0,1]
	v_pk_mov_b32 v[180:181], v[134:135], v[138:139] op_sel:[1,0]
	v_mov_b32_e32 v135, v139
	v_pk_add_f32 v[134:135], v[180:181], v[134:135]
	v_mul_f32_e32 v121, v90, v90
	v_mul_f32_e32 v129, v91, v91
	v_pk_add_f32 v[122:123], v[122:123], v[122:123] op_sel:[0,1] op_sel_hi:[1,0]
	v_pk_add_f32 v[134:135], v[134:135], v[134:135] op_sel:[0,1] op_sel_hi:[1,0]
	v_pk_mul_f32 v[96:97], v[126:127], v[96:97] op_sel_hi:[0,1]
	v_pk_mul_f32 v[94:95], v[126:127], v[94:95] op_sel_hi:[0,1]
	v_mov_b32_e32 v123, v121
	v_mov_b32_e32 v135, v129
	v_pk_mul_f32 v[92:93], v[126:127], v[92:93] op_sel_hi:[0,1]
	v_pk_add_f32 v[122:123], v[122:123], v[134:135]
	v_mul_f32_e32 v134, v95, v95
	v_mul_f32_e32 v138, v97, v97
	v_mul_f32_e32 v131, v92, v92
	v_mul_f32_e32 v179, v93, v93
	v_pk_fma_f32 v[134:135], v[94:95], v[94:95], v[134:135] op_sel_hi:[1,1,0]
	v_pk_fma_f32 v[138:139], v[96:97], v[96:97], v[138:139] op_sel_hi:[1,1,0]
	v_mov_b32_e32 v135, v131
	v_mov_b32_e32 v139, v179
	v_pk_add_f32 v[134:135], v[134:135], v[138:139]
	v_mov_b32_e32 v129, v130
	v_pk_add_f32 v[122:123], v[122:123], v[134:135]
	s_nop 0
	v_add_f32_e32 v121, v122, v123
	v_mov_b32_e32 v122, v121
	s_nop 1
	v_permlane16_swap_b32_e32 v121, v122
	s_waitcnt lgkmcnt(0)
; #define LAS __attribute__((address_space(3)))
; __device__ __forceinline__ unsigned cvt_pk(float lo, float hi) { unsigned r; asm("v_cvt_pk_bf16_f32 %0, %1, %2" : "=v"(r) : "v"(lo), "v"(hi)); return r; }
; __device__ __forceinline__ float frsq(float x) { return __builtin_amdgcn_rsqf(x); }
; __device__ __forceinline__ void qkv_head_unit(const Params& p, LAS unsigned char* lds, int h, int blk_begin, int blk_end) {
;     ...
;                     ssq += __shfl_xor(ssq, 16); ssq += __shfl_xor(ssq, 32);
;                     const float rk = frsq(ssq * (1.0f / 96.0f) + EPS);
;                     LAS bf16_t* dstk = stg + fr * 104 + 4 * fq;
; #pragma unroll
;                     for (int n = 0; n < 4; ++n) { const f32x4 v = acc[mi][n] * rk * gvv[n]; u32x2 wv; wv.x = cvt_pk(v[0], v[1]); wv.y = cvt_pk(v[2], v[3]); *(LAS u32x2*)(dstk + 16 * n) = wv; }
;                     { kr1 = kr1 * rk * gvv[4]; kr2 = kr2 * rk * gvv[5];
;                       f32x4 o1, o2;
; #pragma unroll
;                       for (int i = 0; i < 4; ++i) { float sn, cs; sincos_rr((float)t * frq[i], sn, cs);
;                           o1[i] = kr1[i] * cs - kr2[i] * sn; o2[i] = kr1[i] * sn + kr2[i] * cs; }
;                       u32x2 wv; wv.x = cvt_pk(o1[0], o1[1]); wv.y = cvt_pk(o1[2], o1[3]); *(LAS u32x2*)(dstk + 64) = wv; wv.x = cvt_pk(o2[0], o2[1]); wv.y = cvt_pk(o2[2], o2[3]); *(LAS u32x2*)(dstk + 80) = wv; }
;                     asm volatile("s_waitcnt lgkmcnt(0)" ::: "memory");
; #pragma unroll
;                     for (int j = 0; j < 3; ++j) { const int c = lane + 64 * j, rw = c / 12, cc = c % 12; const int row2 = 16 * (mi ? blk1 : pb) + rw, b2 = row2 / TT, t2 = row2 % TT;
;                         const u32x4 v = *(const LAS u32x4*)(stg + rw * 104 + 8 * cc);
;                         if (valid) __builtin_nontemporal_store(v, (u32x4*)(Kb + (((size_t)(b2 * NH + h)) * TKP + t2) * QKH + 8 * cc)); }
	v_add_f32_e32 v121, v121, v122
	v_mov_b32_e32 v122, v121
	s_nop 1
	v_permlane32_swap_b32_e32 v121, v122
	s_waitcnt lgkmcnt(0)
	v_add_f32_e32 v121, v121, v122
	v_fmamk_f32 v121, v121, 0x3c2aaaab, v140
	v_rsq_f32_e32 v122, v121
	s_nop 0
	v_pk_mul_f32 v[86:87], v[86:87], v[122:123] op_sel_hi:[1,0]
	v_pk_mul_f32 v[98:99], v[98:99], v[122:123] op_sel_hi:[1,0]
	v_pk_mul_f32 v[88:89], v[88:89], v[122:123] op_sel_hi:[1,0]
	v_pk_mul_f32 v[86:87], v[10:11], v[86:87]
	v_pk_mul_f32 v[100:101], v[100:101], v[122:123] op_sel_hi:[1,0]
	v_pk_mul_f32 v[98:99], v[6:7], v[98:99]
	v_pk_mul_f32 v[88:89], v[12:13], v[88:89]
	v_cvt_pk_bf16_f32 v86, v86, v87
	v_pk_mul_f32 v[100:101], v[8:9], v[100:101]
	v_cvt_pk_bf16_f32 v87, v88, v89
	v_cvt_pk_bf16_f32 v98, v98, v99
	v_pk_mul_f32 v[88:89], v[96:97], v[122:123] op_sel_hi:[1,0]
	v_cvt_pk_bf16_f32 v99, v100, v101
	ds_write2_b64 v127, v[98:99], v[86:87] offset1:4
	v_pk_mul_f32 v[86:87], v[94:95], v[122:123] op_sel_hi:[1,0]
	v_pk_mul_f32 v[88:89], v[16:17], v[88:89]
	v_pk_mul_f32 v[86:87], v[14:15], v[86:87]
	s_nop 0
	v_cvt_pk_bf16_f32 v86, v86, v87
	v_cvt_pk_bf16_f32 v87, v88, v89
	v_pk_mul_f32 v[88:89], v[90:91], v[122:123] op_sel_hi:[1,0]
	v_pk_mul_f32 v[90:91], v[92:93], v[122:123] op_sel_hi:[1,0]
	v_pk_mul_f32 v[88:89], v[18:19], v[88:89]
	v_pk_mul_f32 v[90:91], v[20:21], v[90:91]
	v_cvt_pk_bf16_f32 v88, v88, v89
	v_pk_mul_f32 v[92:93], v[136:137], v[122:123] op_sel_hi:[1,0]
	v_cvt_pk_bf16_f32 v89, v90, v91
	ds_write2_b64 v127, v[86:87], v[88:89] offset0:8 offset1:12
	v_mul_hi_i32 v86, v120, s90
	v_lshrrev_b32_e32 v87, 31, v86
	v_ashrrev_i32_e32 v86, 7, v86
	v_add_u32_e32 v86, v86, v87
	v_mul_lo_u32 v86, v86, s86
	v_sub_u32_e32 v90, v120, v86
	v_cvt_f32_i32_e32 v100, v90
	v_mov_b32_e32 v86, v133
	v_mov_b32_e32 v133, v124
	v_pk_mul_f32 v[88:89], v[122:123], v[132:133] op_sel_hi:[0,1]
	v_mul_f32_e32 v94, v154, v100
	v_mul_f32_e32 v95, 0.15915494, v94
	v_rndne_f32_e32 v95, v95
	v_fmac_f32_e32 v94, 0xc0c90fdb, v95
	v_fmac_f32_e32 v94, 0x343bbd2e, v95
	v_mul_f32_e32 v94, 0.15915494, v94
	v_sin_f32_e32 v95, v94
	v_cos_f32_e32 v94, v94
	v_mov_b32_e32 v96, v88
	v_mul_f32_e32 v88, v155, v100
	v_mov_b32_e32 v97, v92
	v_mul_f32_e32 v92, 0.15915494, v88
	v_rndne_f32_e32 v92, v92
	v_pk_mul_f32 v[96:97], v[118:119], v[96:97]
	v_fmac_f32_e32 v88, 0xc0c90fdb, v92
	v_pk_mul_f32 v[98:99], v[94:95], v[96:97]
	v_fmac_f32_e32 v88, 0x343bbd2e, v92
	v_sub_f32_e32 v101, v98, v99
	v_mov_b32_e32 v98, v95
	v_mov_b32_e32 v99, v94
	v_mul_f32_e32 v88, 0.15915494, v88
	v_pk_mul_f32 v[94:95], v[98:99], v[96:97]
	v_sin_f32_e32 v97, v88
	v_cos_f32_e32 v96, v88
	v_mov_b32_e32 v92, v89
	v_pk_mul_f32 v[88:89], v[2:3], v[92:93]
	v_mov_b32_e32 v87, v125
	v_pk_mul_f32 v[92:93], v[96:97], v[88:89]
	v_pk_mul_f32 v[86:87], v[122:123], v[86:87] op_sel_hi:[0,1]
	v_sub_f32_e32 v99, v92, v93
	v_mov_b32_e32 v92, v97
	v_mov_b32_e32 v93, v96
	v_pk_mul_f32 v[88:89], v[92:93], v[88:89]
	v_pk_mul_f32 v[90:91], v[128:129], v[122:123] op_sel_hi:[1,0]
	v_add_f32_e32 v96, v88, v89
	v_mul_f32_e32 v88, v156, v100
	v_mul_f32_e32 v89, 0.15915494, v88
	v_rndne_f32_e32 v89, v89
	v_fmac_f32_e32 v88, 0xc0c90fdb, v89
	v_fmac_f32_e32 v88, 0x343bbd2e, v89
	v_mul_f32_e32 v88, 0.15915494, v88
	v_sin_f32_e32 v89, v88
	v_cos_f32_e32 v88, v88
	v_mov_b32_e32 v92, v86
	v_mul_f32_e32 v86, v157, v100
	v_mov_b32_e32 v93, v90
	v_mul_f32_e32 v90, 0.15915494, v86
	v_rndne_f32_e32 v90, v90
	v_pk_mul_f32 v[92:93], v[116:117], v[92:93]
	v_fmac_f32_e32 v86, 0xc0c90fdb, v90
	v_add_f32_e32 v98, v94, v95
	v_pk_mul_f32 v[94:95], v[88:89], v[92:93]
	v_fmac_f32_e32 v86, 0x343bbd2e, v90
	v_sub_f32_e32 v97, v94, v95
	v_mov_b32_e32 v94, v89
	v_mov_b32_e32 v95, v88
	v_mul_f32_e32 v86, 0.15915494, v86
	v_pk_mul_f32 v[88:89], v[94:95], v[92:93]
	v_sin_f32_e32 v93, v86
	v_cos_f32_e32 v92, v86
	v_mov_b32_e32 v90, v87
	v_pk_mul_f32 v[86:87], v[4:5], v[90:91]
	v_add_f32_e32 v94, v88, v89
	v_pk_mul_f32 v[88:89], v[92:93], v[86:87]
	s_nop 0
	v_sub_f32_e32 v90, v88, v89
	v_mov_b32_e32 v88, v93
	v_mov_b32_e32 v89, v92
	v_pk_mul_f32 v[86:87], v[88:89], v[86:87]
	v_cvt_pk_bf16_f32 v88, v98, v96
	s_nop 0
	v_add_f32_e32 v89, v86, v87
	v_cvt_pk_bf16_f32 v86, v101, v99
	v_cvt_pk_bf16_f32 v87, v97, v90
	v_cvt_pk_bf16_f32 v89, v94, v89
	ds_write2_b64 v127, v[86:87], v[88:89] offset0:16 offset1:20
	s_waitcnt lgkmcnt(0)
	s_and_saveexec_b64 s[4:5], vcc
	s_cbranch_execz .LBB0_526
	v_or_b32_e32 v90, v178, v107
	v_mul_hi_i32 v91, v90, s90
	v_lshrrev_b32_e32 v92, 31, v91
	v_ashrrev_i32_e32 v91, 7, v91
	v_add_u32_e32 v91, v91, v92
	v_mul_i32_i24_e32 v92, 0x810, v91
	v_sub_u32_e32 v90, v90, v92
	v_lshl_or_b32 v91, v91, 3, s16
	v_mul_hi_i32_i24_e32 v93, 0x840, v91
	v_mul_i32_i24_e32 v92, 0x840, v91
	v_ashrrev_i32_e32 v91, 31, v90
	ds_read_b128 v[86:89], v173
	v_lshl_add_u64 v[90:91], v[92:93], 0, v[90:91]
	v_mad_u64_u32 v[94:95], s[8:9], v90, s91, v[108:109]
	v_mov_b32_e32 v90, v95
	v_mad_u64_u32 v[90:91], s[8:9], v91, s91, v[90:91]
	v_mov_b32_e32 v95, v90
	ds_read_b128 v[90:93], v174
	s_waitcnt lgkmcnt(1)
	global_store_dwordx4 v[94:95], v[86:89], off nt
	s_nop 1
	v_or_b32_e32 v86, v178, v170
	v_mul_hi_i32 v87, v86, s90
	v_lshrrev_b32_e32 v88, 31, v87
	v_ashrrev_i32_e32 v87, 7, v87
	v_add_u32_e32 v87, v87, v88
	v_mul_i32_i24_e32 v88, 0x810, v87
	v_sub_u32_e32 v86, v86, v88
	v_lshl_or_b32 v87, v87, 3, s16
	v_mul_hi_i32_i24_e32 v89, 0x840, v87
	v_mul_i32_i24_e32 v88, 0x840, v87
	v_ashrrev_i32_e32 v87, 31, v86
	v_lshl_add_u64 v[86:87], v[88:89], 0, v[86:87]
	v_mad_u64_u32 v[88:89], s[8:9], v86, s91, v[110:111]
	v_mov_b32_e32 v86, v89
	v_mad_u64_u32 v[86:87], s[8:9], v87, s91, v[86:87]
	v_mov_b32_e32 v89, v86
	s_waitcnt lgkmcnt(0)
	global_store_dwordx4 v[88:89], v[90:93], off nt
	ds_read_b128 v[86:89], v175
	s_nop 0
	v_or_b32_e32 v90, v178, v171
	v_mul_hi_i32 v91, v90, s90
	v_lshrrev_b32_e32 v92, 31, v91
	v_ashrrev_i32_e32 v91, 7, v91
	v_add_u32_e32 v91, v91, v92
	v_mul_i32_i24_e32 v92, 0x810, v91
	v_sub_u32_e32 v90, v90, v92
	v_lshl_or_b32 v91, v91, 3, s16
	v_mul_hi_i32_i24_e32 v93, 0x840, v91
	v_mul_i32_i24_e32 v92, 0x840, v91
	v_ashrrev_i32_e32 v91, 31, v90
	v_lshl_add_u64 v[90:91], v[92:93], 0, v[90:91]
	v_mad_u64_u32 v[92:93], s[8:9], v90, s91, v[112:113]
	v_mov_b32_e32 v90, v93
	v_mad_u64_u32 v[90:91], s[8:9], v91, s91, v[90:91]
	v_mov_b32_e32 v93, v90
	s_waitcnt lgkmcnt(0)
	global_store_dwordx4 v[92:93], v[86:89], off nt
